# MFMA order in GEMM K-loops: accumulate chains (k halves adjacent) visited in a snake so every consecutive MFMA pair either chains on the accumulator or shares one source operand; half the accumulators
# speedup vs baseline: 1.0153x; 1.0047x over previous
; #define PG8_STAGE(bufoff, gbase, voff) do { _Pragma("unroll") for (int _i = 0; _i < 2; ++_i) \
;         __builtin_amdgcn_global_load_lds((const unsigned*)((const char*)(gbase) + (voff)[_i]), (LAS unsigned*)(lds + (bufoff) + ldsw + _i * 8192), 16, 0, 0); } while (0)
; #define PG8_LDA(dst, b, h) do { _Pragma("unroll") for (int m = 0; m < 4; ++m) _Pragma("unroll") for (int k = 0; k < 2; ++k) dst[m][k] = *(const LAS bf16x8*)(lds + PG8_SA(b, h) + aoff + m * 2048 + k * 1024); } while (0)
; #define PG8_LDB(dst, b, h) do { _Pragma("unroll") for (int n = 0; n < 2; ++n) _Pragma("unroll") for (int k = 0; k < 2; ++k) dst[n][k] = *(const LAS bf16x8*)(lds + PG8_SB(b, h) + boff + n * 2048 + k * 1024); } while (0)
; #define PG8_SCHED __builtin_amdgcn_sched_barrier(0)
; template <class Epi, bool ALIGN_EPI>
; __device__ __forceinline__ void gemm_phase(LAS unsigned char* lds, const Gemm g, const StaticOrder& S, const Epi& E, const int tid) {
;     ...
;         const char* nA = has_next ? (const char*)g.A + (size_t)nxt.pm * tstepA + (size_t)nxt.pn * g.acs : cA; const char* nB = has_next ? (const char*)g.Bt + (size_t)nxt.pn * tstepB : cB;
;         for (int t = 0; t < nt; t += 2) {
;             const bool last = (t == nt - 2);
;             const char* a1 = cA + (size_t)(t + 1) * kstepA;
;             const char* a2 = last ? nA : cA + (size_t)(t + 2) * kstepA; const char* b2 = last ? nB : cB + (size_t)(t + 2) * kstepB;
;             const char* a3 = a2 + kstepA; const char* b3 = b2 + kstepB;
;             PG8_LDB(B0, 0, 0); PG8_LDB(B1, 0, 1); PG8_SCHED; PG8_LDA(At, 0, 0); PG8_STAGE(PG8_SA(1, 1), a1 + hstepA, voffA);
.LBB0_211:
	s_add_u32 s50, s48, 0x4000
	s_addc_u32 s51, s49, 0
	s_cmp_eq_u32 s89, 28
	s_cselect_b32 s54, s87, s50
	s_cselect_b32 s55, s43, s51
	s_cselect_b32 s52, vcc_lo, vcc_hi
	s_cselect_b32 s53, s35, s88
	s_add_u32 s50, s54, 0x8000
	s_addc_u32 s51, s55, 0
	s_add_i32 s90, 0, 0x10000
	v_add_u32_e32 v0, s90, v160
	s_add_i32 s92, 0, 0x14000
	ds_read_b128 v[132:135], v0
	ds_read_b128 v[136:139], v0 offset:1024
	ds_read_b128 v[152:155], v0 offset:2048
	ds_read_b128 v[156:159], v0 offset:3072
	v_add_u32_e32 v0, s92, v160
	ds_read_b128 v[162:165], v0
	ds_read_b128 v[166:169], v0 offset:1024
	ds_read_b128 v[170:173], v0 offset:2048
	ds_read_b128 v[174:177], v0 offset:3072
	s_add_i32 m0, s72, 0xc000
	ds_read_b128 v[178:181], v161
	ds_read_b128 v[182:185], v161 offset:1024
	ds_read_b128 v[186:189], v161 offset:2048
	ds_read_b128 v[190:193], v161 offset:3072
	ds_read_b128 v[194:197], v161 offset:4096
	ds_read_b128 v[198:201], v161 offset:5120
	ds_read_b128 v[214:217], v161 offset:6144

; #define PG8_STAGE(bufoff, gbase, voff) do { _Pragma("unroll") for (int _i = 0; _i < 2; ++_i) \
;         __builtin_amdgcn_global_load_lds((const unsigned*)((const char*)(gbase) + (voff)[_i]), (LAS unsigned*)(lds + (bufoff) + ldsw + _i * 8192), 16, 0, 0); } while (0)
; #define PG8_LDA(dst, b, h) do { _Pragma("unroll") for (int m = 0; m < 4; ++m) _Pragma("unroll") for (int k = 0; k < 2; ++k) dst[m][k] = *(const LAS bf16x8*)(lds + PG8_SA(b, h) + aoff + m * 2048 + k * 1024); } while (0)
; #define PG8_LDB(dst, b, h) do { _Pragma("unroll") for (int n = 0; n < 2; ++n) _Pragma("unroll") for (int k = 0; k < 2; ++k) dst[n][k] = *(const LAS bf16x8*)(lds + PG8_SB(b, h) + boff + n * 2048 + k * 1024); } while (0)
; #define PG8_MMA(ai, bj, At, Bt) do { __builtin_amdgcn_s_setprio(1); _Pragma("unroll") for (int m = 0; m < 4; ++m) _Pragma("unroll") for (int n = 0; n < 2; ++n) _Pragma("unroll") for (int k = 0; k < 2; ++k) \
;         acc[ai][bj][m][n] = __builtin_amdgcn_mfma_f32_16x16x32_bf16(Bt[n][k], At[m][k], acc[ai][bj][m][n], 0, 0, 0); __builtin_amdgcn_s_setprio(0); } while (0)
; #define PG8_WAIT_V(n) asm volatile("s_waitcnt vmcnt(" #n ")" ::: "memory")
; #define PG8_WAIT_L(n) asm volatile("s_waitcnt lgkmcnt(" #n ")" ::: "memory")
; #define PG8_BAR __builtin_amdgcn_s_barrier()
; #define PG8_SCHED __builtin_amdgcn_sched_barrier(0)
; template <class Epi, bool ALIGN_EPI>
; __device__ __forceinline__ void gemm_phase(LAS unsigned char* lds, const Gemm g, const StaticOrder& S, const Epi& E, const int tid) {
;     ...
;             PG8_LDB(B0, 0, 0); PG8_LDB(B1, 0, 1); PG8_SCHED; PG8_LDA(At, 0, 0); PG8_STAGE(PG8_SA(1, 1), a1 + hstepA, voffA);
;             PG8_WAIT_V(8); PG8_WAIT_L(0); PG8_BAR; PG8_MMA(0, 0, At, B0); PG8_MMA(0, 1, At, B1); PG8_BAR; PG8_SCHED;
	global_load_lds_dwordx4 v148, s[48:49]
	s_add_i32 m0, s72, 0xe000
	ds_read_b128 v[218:221], v161 offset:7168
	global_load_lds_dwordx4 v150, s[48:49]
	s_waitcnt vmcnt(8)
	s_waitcnt lgkmcnt(0)
	s_barrier


; #define PG8_MMA(ai, bj, At, Bt) do { __builtin_amdgcn_s_setprio(1); _Pragma("unroll") for (int m = 0; m < 4; ++m) _Pragma("unroll") for (int n = 0; n < 2; ++n) _Pragma("unroll") for (int k = 0; k < 2; ++k) \
;         acc[ai][bj][m][n] = __builtin_amdgcn_mfma_f32_16x16x32_bf16(Bt[n][k], At[m][k], acc[ai][bj][m][n], 0, 0, 0); __builtin_amdgcn_s_setprio(0); } while (0)
; #define PG8_WAIT_V(n) asm volatile("s_waitcnt vmcnt(" #n ")" ::: "memory")
; #define PG8_WAIT_L(n) asm volatile("s_waitcnt lgkmcnt(" #n ")" ::: "memory")
; #define PG8_BAR __builtin_amdgcn_s_barrier()
; #define PG8_SCHED __builtin_amdgcn_sched_barrier(0)
; template <class Epi, bool ALIGN_EPI>
; __device__ __forceinline__ void gemm_phase(LAS unsigned char* lds, const Gemm g, const StaticOrder& S, const Epi& E, const int tid) {
;     ...
;             PG8_WAIT_V(8); PG8_WAIT_L(0); PG8_BAR; PG8_MMA(0, 0, At, B0); PG8_MMA(0, 1, At, B1); PG8_BAR; PG8_SCHED;
	v_mfma_f32_16x16x32_bf16 v[88:91], v[132:135], v[178:181], v[88:91]
	v_mfma_f32_16x16x32_bf16 v[88:91], v[136:139], v[182:185], v[88:91]
	v_mfma_f32_16x16x32_bf16 v[124:127], v[156:159], v[182:185], v[124:127]
	v_mfma_f32_16x16x32_bf16 v[124:127], v[152:155], v[178:181], v[124:127]
	v_mfma_f32_16x16x32_bf16 v[120:123], v[152:155], v[186:189], v[120:123]
	v_mfma_f32_16x16x32_bf16 v[120:123], v[156:159], v[190:193], v[120:123]
	v_mfma_f32_16x16x32_bf16 v[52:55], v[136:139], v[190:193], v[52:55]
	v_mfma_f32_16x16x32_bf16 v[52:55], v[132:135], v[186:189], v[52:55]
	v_mfma_f32_16x16x32_bf16 v[40:43], v[132:135], v[194:197], v[40:43]
	v_mfma_f32_16x16x32_bf16 v[40:43], v[136:139], v[198:201], v[40:43]
	v_mfma_f32_16x16x32_bf16 v[116:119], v[156:159], v[198:201], v[116:119]
	v_mfma_f32_16x16x32_bf16 v[116:119], v[152:155], v[194:197], v[116:119]
	v_mfma_f32_16x16x32_bf16 v[112:115], v[152:155], v[214:217], v[112:115]
	v_mfma_f32_16x16x32_bf16 v[112:115], v[156:159], v[218:221], v[112:115]
	v_mfma_f32_16x16x32_bf16 v[36:39], v[136:139], v[218:221], v[36:39]
	v_mfma_f32_16x16x32_bf16 v[36:39], v[132:135], v[214:217], v[36:39]


; #define PG8_MMA(ai, bj, At, Bt) do { __builtin_amdgcn_s_setprio(1); _Pragma("unroll") for (int m = 0; m < 4; ++m) _Pragma("unroll") for (int n = 0; n < 2; ++n) _Pragma("unroll") for (int k = 0; k < 2; ++k) \
;         acc[ai][bj][m][n] = __builtin_amdgcn_mfma_f32_16x16x32_bf16(Bt[n][k], At[m][k], acc[ai][bj][m][n], 0, 0, 0); __builtin_amdgcn_s_setprio(0); } while (0)
; #define PG8_WAIT_V(n) asm volatile("s_waitcnt vmcnt(" #n ")" ::: "memory")
; #define PG8_WAIT_L(n) asm volatile("s_waitcnt lgkmcnt(" #n ")" ::: "memory")
; #define PG8_BAR __builtin_amdgcn_s_barrier()
; #define PG8_SCHED __builtin_amdgcn_sched_barrier(0)
; template <class Epi, bool ALIGN_EPI>
; __device__ __forceinline__ void gemm_phase(LAS unsigned char* lds, const Gemm g, const StaticOrder& S, const Epi& E, const int tid) {
;     ...
;             PG8_WAIT_V(8); PG8_WAIT_L(0); PG8_BAR; PG8_MMA(0, 0, At, B0); PG8_MMA(0, 1, At, B1); PG8_BAR; PG8_SCHED;
	v_mfma_f32_16x16x32_bf16 v[80:83], v[162:165], v[178:181], v[80:83]
	v_mfma_f32_16x16x32_bf16 v[80:83], v[166:169], v[182:185], v[80:83]
	v_mfma_f32_16x16x32_bf16 v[128:131], v[174:177], v[182:185], v[128:131]
	v_mfma_f32_16x16x32_bf16 v[128:131], v[170:173], v[178:181], v[128:131]
	v_mfma_f32_16x16x32_bf16 v[108:111], v[170:173], v[186:189], v[108:111]
	v_mfma_f32_16x16x32_bf16 v[108:111], v[174:177], v[190:193], v[108:111]
	v_mfma_f32_16x16x32_bf16 v[68:71], v[166:169], v[190:193], v[68:71]
	v_mfma_f32_16x16x32_bf16 v[68:71], v[162:165], v[186:189], v[68:71]
	v_mfma_f32_16x16x32_bf16 v[60:63], v[162:165], v[194:197], v[60:63]
	v_mfma_f32_16x16x32_bf16 v[60:63], v[166:169], v[198:201], v[60:63]
	v_mfma_f32_16x16x32_bf16 v[104:107], v[174:177], v[198:201], v[104:107]
	v_mfma_f32_16x16x32_bf16 v[104:107], v[170:173], v[194:197], v[104:107]
	v_mfma_f32_16x16x32_bf16 v[100:103], v[170:173], v[214:217], v[100:103]
	v_mfma_f32_16x16x32_bf16 v[100:103], v[174:177], v[218:221], v[100:103]
	v_mfma_f32_16x16x32_bf16 v[48:51], v[166:169], v[218:221], v[48:51]
	v_mfma_f32_16x16x32_bf16 v[48:51], v[162:165], v[214:217], v[48:51]

; #define PG8_STAGE(bufoff, gbase, voff) do { _Pragma("unroll") for (int _i = 0; _i < 2; ++_i) \
;         __builtin_amdgcn_global_load_lds((const unsigned*)((const char*)(gbase) + (voff)[_i]), (LAS unsigned*)(lds + (bufoff) + ldsw + _i * 8192), 16, 0, 0); } while (0)
; #define PG8_LDA(dst, b, h) do { _Pragma("unroll") for (int m = 0; m < 4; ++m) _Pragma("unroll") for (int k = 0; k < 2; ++k) dst[m][k] = *(const LAS bf16x8*)(lds + PG8_SA(b, h) + aoff + m * 2048 + k * 1024); } while (0)
; #define PG8_MMA(ai, bj, At, Bt) do { __builtin_amdgcn_s_setprio(1); _Pragma("unroll") for (int m = 0; m < 4; ++m) _Pragma("unroll") for (int n = 0; n < 2; ++n) _Pragma("unroll") for (int k = 0; k < 2; ++k) \
;         acc[ai][bj][m][n] = __builtin_amdgcn_mfma_f32_16x16x32_bf16(Bt[n][k], At[m][k], acc[ai][bj][m][n], 0, 0, 0); __builtin_amdgcn_s_setprio(0); } while (0)
; #define PG8_WAIT_V(n) asm volatile("s_waitcnt vmcnt(" #n ")" ::: "memory")
; #define PG8_WAIT_L(n) asm volatile("s_waitcnt lgkmcnt(" #n ")" ::: "memory")
; #define PG8_BAR __builtin_amdgcn_s_barrier()
; #define PG8_SCHED __builtin_amdgcn_sched_barrier(0)
; template <class Epi, bool ALIGN_EPI>
; __device__ __forceinline__ void gemm_phase(LAS unsigned char* lds, const Gemm g, const StaticOrder& S, const Epi& E, const int tid) {
;     ...
;             PG8_WAIT_V(8); PG8_WAIT_L(0); PG8_BAR; PG8_MMA(0, 0, At, B0); PG8_MMA(0, 1, At, B1); PG8_BAR; PG8_SCHED;
;             PG8_LDA(At, 0, 1); PG8_STAGE(PG8_SB(0, 0), b2, voffB); PG8_STAGE(PG8_SB(0, 1), b2 + hstepB, voffB); PG8_STAGE(PG8_SA(0, 0), a2, voffA);
	s_barrier
	s_add_i32 s90, s90, s71
	s_mov_b32 m0, s90
	ds_read_b128 v[178:181], v161 offset:16384
	ds_read_b128 v[182:185], v161 offset:17408
	ds_read_b128 v[186:189], v161 offset:18432
	ds_read_b128 v[190:193], v161 offset:19456


; #define PG8_STAGE(bufoff, gbase, voff) do { _Pragma("unroll") for (int _i = 0; _i < 2; ++_i) \
;         __builtin_amdgcn_global_load_lds((const unsigned*)((const char*)(gbase) + (voff)[_i]), (LAS unsigned*)(lds + (bufoff) + ldsw + _i * 8192), 16, 0, 0); } while (0)
; #define PG8_LDA(dst, b, h) do { _Pragma("unroll") for (int m = 0; m < 4; ++m) _Pragma("unroll") for (int k = 0; k < 2; ++k) dst[m][k] = *(const LAS bf16x8*)(lds + PG8_SA(b, h) + aoff + m * 2048 + k * 1024); } while (0)
; #define PG8_MMA(ai, bj, At, Bt) do { __builtin_amdgcn_s_setprio(1); _Pragma("unroll") for (int m = 0; m < 4; ++m) _Pragma("unroll") for (int n = 0; n < 2; ++n) _Pragma("unroll") for (int k = 0; k < 2; ++k) \
;         acc[ai][bj][m][n] = __builtin_amdgcn_mfma_f32_16x16x32_bf16(Bt[n][k], At[m][k], acc[ai][bj][m][n], 0, 0, 0); __builtin_amdgcn_s_setprio(0); } while (0)
; #define PG8_WAIT_V(n) asm volatile("s_waitcnt vmcnt(" #n ")" ::: "memory")
; #define PG8_WAIT_L(n) asm volatile("s_waitcnt lgkmcnt(" #n ")" ::: "memory")
; #define PG8_BAR __builtin_amdgcn_s_barrier()
; #define PG8_SCHED __builtin_amdgcn_sched_barrier(0)
; template <class Epi, bool ALIGN_EPI>
; __device__ __forceinline__ void gemm_phase(LAS unsigned char* lds, const Gemm g, const StaticOrder& S, const Epi& E, const int tid) {
;     ...
;             PG8_LDA(At, 0, 1); PG8_STAGE(PG8_SB(0, 0), b2, voffB); PG8_STAGE(PG8_SB(0, 1), b2 + hstepB, voffB); PG8_STAGE(PG8_SA(0, 0), a2, voffA);
;             PG8_WAIT_V(8); PG8_WAIT_L(0); PG8_BAR; PG8_MMA(1, 0, At, B0); PG8_MMA(1, 1, At, B1); PG8_BAR; PG8_SCHED;
	global_load_lds_dwordx4 v144, s[52:53]
	s_add_i32 m0, s90, 0x2000
	s_add_u32 s90, s52, 0x4000
	s_addc_u32 s91, s53, 0
	s_add_i32 s92, s92, s71
	global_load_lds_dwordx4 v140, s[52:53]
	s_mov_b32 m0, s92
	ds_read_b128 v[218:221], v161 offset:23552
	global_load_lds_dwordx4 v144, s[90:91]
	s_add_i32 m0, s92, 0x2000
	ds_read_b128 v[214:217], v161 offset:22528
	global_load_lds_dwordx4 v140, s[90:91]
	s_mov_b32 m0, s72
	ds_read_b128 v[198:201], v161 offset:21504
	global_load_lds_dwordx4 v146, s[54:55]
	s_mov_b32 m0, s73
	ds_read_b128 v[194:197], v161 offset:20480
	global_load_lds_dwordx4 v142, s[54:55]
	s_waitcnt vmcnt(8)
	s_waitcnt lgkmcnt(0)
	s_barrier


; #define PG8_MMA(ai, bj, At, Bt) do { __builtin_amdgcn_s_setprio(1); _Pragma("unroll") for (int m = 0; m < 4; ++m) _Pragma("unroll") for (int n = 0; n < 2; ++n) _Pragma("unroll") for (int k = 0; k < 2; ++k) \
;         acc[ai][bj][m][n] = __builtin_amdgcn_mfma_f32_16x16x32_bf16(Bt[n][k], At[m][k], acc[ai][bj][m][n], 0, 0, 0); __builtin_amdgcn_s_setprio(0); } while (0)
; #define PG8_WAIT_V(n) asm volatile("s_waitcnt vmcnt(" #n ")" ::: "memory")
; #define PG8_WAIT_L(n) asm volatile("s_waitcnt lgkmcnt(" #n ")" ::: "memory")
; #define PG8_BAR __builtin_amdgcn_s_barrier()
; #define PG8_SCHED __builtin_amdgcn_sched_barrier(0)
; template <class Epi, bool ALIGN_EPI>
; __device__ __forceinline__ void gemm_phase(LAS unsigned char* lds, const Gemm g, const StaticOrder& S, const Epi& E, const int tid) {
;     ...
;             PG8_WAIT_V(8); PG8_WAIT_L(0); PG8_BAR; PG8_MMA(1, 0, At, B0); PG8_MMA(1, 1, At, B1); PG8_BAR; PG8_SCHED;
	v_mfma_f32_16x16x32_bf16 v[24:27], v[132:135], v[178:181], v[24:27]
	v_mfma_f32_16x16x32_bf16 v[24:27], v[136:139], v[182:185], v[24:27]
	v_mfma_f32_16x16x32_bf16 v[92:95], v[156:159], v[182:185], v[92:95]
	v_mfma_f32_16x16x32_bf16 v[92:95], v[152:155], v[178:181], v[92:95]
	v_mfma_f32_16x16x32_bf16 v[84:87], v[152:155], v[186:189], v[84:87]
	v_mfma_f32_16x16x32_bf16 v[84:87], v[156:159], v[190:193], v[84:87]
	v_mfma_f32_16x16x32_bf16 v[16:19], v[136:139], v[190:193], v[16:19]
	v_mfma_f32_16x16x32_bf16 v[16:19], v[132:135], v[186:189], v[16:19]
	v_mfma_f32_16x16x32_bf16 v[8:11], v[132:135], v[194:197], v[8:11]
	v_mfma_f32_16x16x32_bf16 v[8:11], v[136:139], v[198:201], v[8:11]
	v_mfma_f32_16x16x32_bf16 v[76:79], v[152:155], v[194:197], v[76:79]
	v_mfma_f32_16x16x32_bf16 v[76:79], v[156:159], v[198:201], v[76:79]
	v_mfma_f32_16x16x32_bf16 v[2:5], v[132:135], v[214:217], v[4:7]
	v_mfma_f32_16x16x32_bf16 v[2:5], v[136:139], v[218:221], v[2:5]
	v_mfma_f32_16x16x32_bf16 v[64:67], v[152:155], v[214:217], v[64:67]
	v_mfma_f32_16x16x32_bf16 v[64:67], v[156:159], v[218:221], v[64:67]


; #define PG8_MMA(ai, bj, At, Bt) do { __builtin_amdgcn_s_setprio(1); _Pragma("unroll") for (int m = 0; m < 4; ++m) _Pragma("unroll") for (int n = 0; n < 2; ++n) _Pragma("unroll") for (int k = 0; k < 2; ++k) \
;         acc[ai][bj][m][n] = __builtin_amdgcn_mfma_f32_16x16x32_bf16(Bt[n][k], At[m][k], acc[ai][bj][m][n], 0, 0, 0); __builtin_amdgcn_s_setprio(0); } while (0)
; #define PG8_WAIT_V(n) asm volatile("s_waitcnt vmcnt(" #n ")" ::: "memory")
; #define PG8_WAIT_L(n) asm volatile("s_waitcnt lgkmcnt(" #n ")" ::: "memory")
; #define PG8_BAR __builtin_amdgcn_s_barrier()
; #define PG8_SCHED __builtin_amdgcn_sched_barrier(0)
; template <class Epi, bool ALIGN_EPI>
; __device__ __forceinline__ void gemm_phase(LAS unsigned char* lds, const Gemm g, const StaticOrder& S, const Epi& E, const int tid) {
;     ...
;             PG8_WAIT_V(8); PG8_WAIT_L(0); PG8_BAR; PG8_MMA(1, 0, At, B0); PG8_MMA(1, 1, At, B1); PG8_BAR; PG8_SCHED;
	v_mfma_f32_16x16x32_bf16 v[32:35], v[162:165], v[178:181], v[32:35]
	v_mfma_f32_16x16x32_bf16 v[32:35], v[166:169], v[182:185], v[32:35]
	v_mfma_f32_16x16x32_bf16 v[72:75], v[174:177], v[182:185], v[72:75]
	v_mfma_f32_16x16x32_bf16 v[72:75], v[170:173], v[178:181], v[72:75]
	v_mfma_f32_16x16x32_bf16 v[96:99], v[170:173], v[186:189], v[96:99]
	v_mfma_f32_16x16x32_bf16 v[96:99], v[174:177], v[190:193], v[96:99]
	v_mfma_f32_16x16x32_bf16 v[28:31], v[166:169], v[190:193], v[28:31]
	v_mfma_f32_16x16x32_bf16 v[28:31], v[162:165], v[186:189], v[28:31]
	v_mfma_f32_16x16x32_bf16 v[20:23], v[162:165], v[194:197], v[20:23]
	v_mfma_f32_16x16x32_bf16 v[20:23], v[166:169], v[198:201], v[20:23]
	v_mfma_f32_16x16x32_bf16 v[56:59], v[174:177], v[198:201], v[56:59]
	v_mfma_f32_16x16x32_bf16 v[56:59], v[170:173], v[194:197], v[56:59]
	v_mfma_f32_16x16x32_bf16 v[44:47], v[170:173], v[214:217], v[44:47]
	v_mfma_f32_16x16x32_bf16 v[44:47], v[174:177], v[218:221], v[44:47]
	v_mfma_f32_16x16x32_bf16 v[12:15], v[166:169], v[218:221], v[12:15]
	v_mfma_f32_16x16x32_bf16 v[12:15], v[162:165], v[214:217], v[12:15]

; #define PG8_STAGE(bufoff, gbase, voff) do { _Pragma("unroll") for (int _i = 0; _i < 2; ++_i) \
;         __builtin_amdgcn_global_load_lds((const unsigned*)((const char*)(gbase) + (voff)[_i]), (LAS unsigned*)(lds + (bufoff) + ldsw + _i * 8192), 16, 0, 0); } while (0)
; #define PG8_LDA(dst, b, h) do { _Pragma("unroll") for (int m = 0; m < 4; ++m) _Pragma("unroll") for (int k = 0; k < 2; ++k) dst[m][k] = *(const LAS bf16x8*)(lds + PG8_SA(b, h) + aoff + m * 2048 + k * 1024); } while (0)
; #define PG8_LDB(dst, b, h) do { _Pragma("unroll") for (int n = 0; n < 2; ++n) _Pragma("unroll") for (int k = 0; k < 2; ++k) dst[n][k] = *(const LAS bf16x8*)(lds + PG8_SB(b, h) + boff + n * 2048 + k * 1024); } while (0)
; #define PG8_MMA(ai, bj, At, Bt) do { __builtin_amdgcn_s_setprio(1); _Pragma("unroll") for (int m = 0; m < 4; ++m) _Pragma("unroll") for (int n = 0; n < 2; ++n) _Pragma("unroll") for (int k = 0; k < 2; ++k) \
;         acc[ai][bj][m][n] = __builtin_amdgcn_mfma_f32_16x16x32_bf16(Bt[n][k], At[m][k], acc[ai][bj][m][n], 0, 0, 0); __builtin_amdgcn_s_setprio(0); } while (0)
; #define PG8_WAIT_V(n) asm volatile("s_waitcnt vmcnt(" #n ")" ::: "memory")
; #define PG8_WAIT_L(n) asm volatile("s_waitcnt lgkmcnt(" #n ")" ::: "memory")
; #define PG8_BAR __builtin_amdgcn_s_barrier()
; #define PG8_SCHED __builtin_amdgcn_sched_barrier(0)
; template <class Epi, bool ALIGN_EPI>
; __device__ __forceinline__ void gemm_phase(LAS unsigned char* lds, const Gemm g, const StaticOrder& S, const Epi& E, const int tid) {
;     ...
;             PG8_LDB(B0, 1, 0); PG8_LDB(B1, 1, 1); PG8_SCHED; PG8_LDA(At, 1, 0); PG8_STAGE(PG8_SA(0, 1), a2 + hstepA, voffA);
;             PG8_WAIT_V(8); PG8_WAIT_L(0); PG8_BAR; PG8_MMA(0, 0, At, B0); PG8_MMA(0, 1, At, B1); PG8_BAR; PG8_SCHED;
	s_barrier
	s_add_i32 s90, 0, 0x18000
	v_add_u32_e32 v0, s90, v160
	s_add_i32 s91, 0, 0x1c000
	ds_read_b128 v[132:135], v0
	ds_read_b128 v[136:139], v0 offset:1024
	ds_read_b128 v[152:155], v0 offset:2048
	ds_read_b128 v[156:159], v0 offset:3072
	v_add_u32_e32 v0, s91, v160
	ds_read_b128 v[162:165], v0
	ds_read_b128 v[166:169], v0 offset:1024
	ds_read_b128 v[170:173], v0 offset:2048
	ds_read_b128 v[174:177], v0 offset:3072
	s_add_u32 s54, s54, 0x4000
	s_addc_u32 s55, s55, 0
	s_mov_b32 m0, s74
	ds_read_b128 v[178:181], v161 offset:32768
	ds_read_b128 v[182:185], v161 offset:33792
	ds_read_b128 v[186:189], v161 offset:34816
	ds_read_b128 v[190:193], v161 offset:35840
	ds_read_b128 v[194:197], v161 offset:36864
	ds_read_b128 v[198:201], v161 offset:37888
	ds_read_b128 v[214:217], v161 offset:38912

; #define PG8_STAGE(bufoff, gbase, voff) do { _Pragma("unroll") for (int _i = 0; _i < 2; ++_i) \
;         __builtin_amdgcn_global_load_lds((const unsigned*)((const char*)(gbase) + (voff)[_i]), (LAS unsigned*)(lds + (bufoff) + ldsw + _i * 8192), 16, 0, 0); } while (0)
; #define PG8_LDA(dst, b, h) do { _Pragma("unroll") for (int m = 0; m < 4; ++m) _Pragma("unroll") for (int k = 0; k < 2; ++k) dst[m][k] = *(const LAS bf16x8*)(lds + PG8_SA(b, h) + aoff + m * 2048 + k * 1024); } while (0)
; #define PG8_LDB(dst, b, h) do { _Pragma("unroll") for (int n = 0; n < 2; ++n) _Pragma("unroll") for (int k = 0; k < 2; ++k) dst[n][k] = *(const LAS bf16x8*)(lds + PG8_SB(b, h) + boff + n * 2048 + k * 1024); } while (0)
; #define PG8_MMA(ai, bj, At, Bt) do { __builtin_amdgcn_s_setprio(1); _Pragma("unroll") for (int m = 0; m < 4; ++m) _Pragma("unroll") for (int n = 0; n < 2; ++n) _Pragma("unroll") for (int k = 0; k < 2; ++k) \
;         acc[ai][bj][m][n] = __builtin_amdgcn_mfma_f32_16x16x32_bf16(Bt[n][k], At[m][k], acc[ai][bj][m][n], 0, 0, 0); __builtin_amdgcn_s_setprio(0); } while (0)
; #define PG8_WAIT_V(n) asm volatile("s_waitcnt vmcnt(" #n ")" ::: "memory")
; #define PG8_WAIT_L(n) asm volatile("s_waitcnt lgkmcnt(" #n ")" ::: "memory")
; #define PG8_BAR __builtin_amdgcn_s_barrier()
; #define PG8_SCHED __builtin_amdgcn_sched_barrier(0)
; template <class Epi, bool ALIGN_EPI>
; __device__ __forceinline__ void gemm_phase(LAS unsigned char* lds, const Gemm g, const StaticOrder& S, const Epi& E, const int tid) {
;     ...
;             PG8_LDB(B0, 1, 0); PG8_LDB(B1, 1, 1); PG8_SCHED; PG8_LDA(At, 1, 0); PG8_STAGE(PG8_SA(0, 1), a2 + hstepA, voffA);
;             PG8_WAIT_V(8); PG8_WAIT_L(0); PG8_BAR; PG8_MMA(0, 0, At, B0); PG8_MMA(0, 1, At, B1); PG8_BAR; PG8_SCHED;
	global_load_lds_dwordx4 v146, s[54:55]
	s_mov_b32 m0, s75
	ds_read_b128 v[218:221], v161 offset:39936
	global_load_lds_dwordx4 v142, s[54:55]
	s_waitcnt vmcnt(8)
	s_waitcnt lgkmcnt(0)
	s_barrier


; #define PG8_MMA(ai, bj, At, Bt) do { __builtin_amdgcn_s_setprio(1); _Pragma("unroll") for (int m = 0; m < 4; ++m) _Pragma("unroll") for (int n = 0; n < 2; ++n) _Pragma("unroll") for (int k = 0; k < 2; ++k) \
;         acc[ai][bj][m][n] = __builtin_amdgcn_mfma_f32_16x16x32_bf16(Bt[n][k], At[m][k], acc[ai][bj][m][n], 0, 0, 0); __builtin_amdgcn_s_setprio(0); } while (0)
; #define PG8_WAIT_V(n) asm volatile("s_waitcnt vmcnt(" #n ")" ::: "memory")
; #define PG8_WAIT_L(n) asm volatile("s_waitcnt lgkmcnt(" #n ")" ::: "memory")
; #define PG8_BAR __builtin_amdgcn_s_barrier()
; #define PG8_SCHED __builtin_amdgcn_sched_barrier(0)
; template <class Epi, bool ALIGN_EPI>
; __device__ __forceinline__ void gemm_phase(LAS unsigned char* lds, const Gemm g, const StaticOrder& S, const Epi& E, const int tid) {
;     ...
;             PG8_WAIT_V(8); PG8_WAIT_L(0); PG8_BAR; PG8_MMA(0, 0, At, B0); PG8_MMA(0, 1, At, B1); PG8_BAR; PG8_SCHED;
	v_mfma_f32_16x16x32_bf16 v[88:91], v[132:135], v[178:181], v[88:91]
	v_mfma_f32_16x16x32_bf16 v[88:91], v[136:139], v[182:185], v[88:91]
	v_mfma_f32_16x16x32_bf16 v[124:127], v[156:159], v[182:185], v[124:127]
	v_mfma_f32_16x16x32_bf16 v[124:127], v[152:155], v[178:181], v[124:127]
	v_mfma_f32_16x16x32_bf16 v[120:123], v[152:155], v[186:189], v[120:123]
	v_mfma_f32_16x16x32_bf16 v[120:123], v[156:159], v[190:193], v[120:123]
	v_mfma_f32_16x16x32_bf16 v[52:55], v[136:139], v[190:193], v[52:55]
	v_mfma_f32_16x16x32_bf16 v[52:55], v[132:135], v[186:189], v[52:55]
	v_mfma_f32_16x16x32_bf16 v[40:43], v[132:135], v[194:197], v[40:43]
	v_mfma_f32_16x16x32_bf16 v[40:43], v[136:139], v[198:201], v[40:43]
	v_mfma_f32_16x16x32_bf16 v[116:119], v[156:159], v[198:201], v[116:119]
	v_mfma_f32_16x16x32_bf16 v[116:119], v[152:155], v[194:197], v[116:119]
	v_mfma_f32_16x16x32_bf16 v[112:115], v[152:155], v[214:217], v[112:115]
	v_mfma_f32_16x16x32_bf16 v[112:115], v[156:159], v[218:221], v[112:115]
	v_mfma_f32_16x16x32_bf16 v[36:39], v[136:139], v[218:221], v[36:39]
	v_mfma_f32_16x16x32_bf16 v[36:39], v[132:135], v[214:217], v[36:39]


; #define PG8_MMA(ai, bj, At, Bt) do { __builtin_amdgcn_s_setprio(1); _Pragma("unroll") for (int m = 0; m < 4; ++m) _Pragma("unroll") for (int n = 0; n < 2; ++n) _Pragma("unroll") for (int k = 0; k < 2; ++k) \
;         acc[ai][bj][m][n] = __builtin_amdgcn_mfma_f32_16x16x32_bf16(Bt[n][k], At[m][k], acc[ai][bj][m][n], 0, 0, 0); __builtin_amdgcn_s_setprio(0); } while (0)
; #define PG8_WAIT_V(n) asm volatile("s_waitcnt vmcnt(" #n ")" ::: "memory")
; #define PG8_WAIT_L(n) asm volatile("s_waitcnt lgkmcnt(" #n ")" ::: "memory")
; #define PG8_BAR __builtin_amdgcn_s_barrier()
; #define PG8_SCHED __builtin_amdgcn_sched_barrier(0)
; template <class Epi, bool ALIGN_EPI>
; __device__ __forceinline__ void gemm_phase(LAS unsigned char* lds, const Gemm g, const StaticOrder& S, const Epi& E, const int tid) {
;     ...
;             PG8_WAIT_V(8); PG8_WAIT_L(0); PG8_BAR; PG8_MMA(0, 0, At, B0); PG8_MMA(0, 1, At, B1); PG8_BAR; PG8_SCHED;
	v_mfma_f32_16x16x32_bf16 v[80:83], v[162:165], v[178:181], v[80:83]
	v_mfma_f32_16x16x32_bf16 v[80:83], v[166:169], v[182:185], v[80:83]
	v_mfma_f32_16x16x32_bf16 v[128:131], v[174:177], v[182:185], v[128:131]
	v_mfma_f32_16x16x32_bf16 v[128:131], v[170:173], v[178:181], v[128:131]
	v_mfma_f32_16x16x32_bf16 v[108:111], v[170:173], v[186:189], v[108:111]
	v_mfma_f32_16x16x32_bf16 v[108:111], v[174:177], v[190:193], v[108:111]
	v_mfma_f32_16x16x32_bf16 v[68:71], v[166:169], v[190:193], v[68:71]
	v_mfma_f32_16x16x32_bf16 v[68:71], v[162:165], v[186:189], v[68:71]
	v_mfma_f32_16x16x32_bf16 v[60:63], v[162:165], v[194:197], v[60:63]
	v_mfma_f32_16x16x32_bf16 v[60:63], v[166:169], v[198:201], v[60:63]
	v_mfma_f32_16x16x32_bf16 v[104:107], v[174:177], v[198:201], v[104:107]
	v_mfma_f32_16x16x32_bf16 v[104:107], v[170:173], v[194:197], v[104:107]
	v_mfma_f32_16x16x32_bf16 v[100:103], v[170:173], v[214:217], v[100:103]
	v_mfma_f32_16x16x32_bf16 v[100:103], v[174:177], v[218:221], v[100:103]
	v_mfma_f32_16x16x32_bf16 v[48:51], v[166:169], v[218:221], v[48:51]
	v_mfma_f32_16x16x32_bf16 v[48:51], v[162:165], v[214:217], v[48:51]

; #define PG8_STAGE(bufoff, gbase, voff) do { _Pragma("unroll") for (int _i = 0; _i < 2; ++_i) \
;         __builtin_amdgcn_global_load_lds((const unsigned*)((const char*)(gbase) + (voff)[_i]), (LAS unsigned*)(lds + (bufoff) + ldsw + _i * 8192), 16, 0, 0); } while (0)
; #define PG8_LDA(dst, b, h) do { _Pragma("unroll") for (int m = 0; m < 4; ++m) _Pragma("unroll") for (int k = 0; k < 2; ++k) dst[m][k] = *(const LAS bf16x8*)(lds + PG8_SA(b, h) + aoff + m * 2048 + k * 1024); } while (0)
; template <class Epi, bool ALIGN_EPI>
; __device__ __forceinline__ void gemm_phase(LAS unsigned char* lds, const Gemm g, const StaticOrder& S, const Epi& E, const int tid) {
;     ...
;             PG8_LDA(At, 1, 1); PG8_STAGE(PG8_SB(1, 0), b3, voffB); PG8_STAGE(PG8_SB(1, 1), b3 + hstepB, voffB); PG8_STAGE(PG8_SA(1, 0), a3, voffA);
	s_barrier
	s_add_u32 s54, s52, 0x8000
	s_addc_u32 s55, s53, 0
	s_add_i32 s90, s90, s71
	s_mov_b32 m0, s90
	ds_read_b128 v[178:181], v161 offset:49152
	ds_read_b128 v[182:185], v161 offset:50176
	ds_read_b128 v[186:189], v161 offset:51200
	ds_read_b128 v[190:193], v161 offset:52224


; #define PG8_STAGE(bufoff, gbase, voff) do { _Pragma("unroll") for (int _i = 0; _i < 2; ++_i) \
;         __builtin_amdgcn_global_load_lds((const unsigned*)((const char*)(gbase) + (voff)[_i]), (LAS unsigned*)(lds + (bufoff) + ldsw + _i * 8192), 16, 0, 0); } while (0)
; #define PG8_LDA(dst, b, h) do { _Pragma("unroll") for (int m = 0; m < 4; ++m) _Pragma("unroll") for (int k = 0; k < 2; ++k) dst[m][k] = *(const LAS bf16x8*)(lds + PG8_SA(b, h) + aoff + m * 2048 + k * 1024); } while (0)
; #define PG8_MMA(ai, bj, At, Bt) do { __builtin_amdgcn_s_setprio(1); _Pragma("unroll") for (int m = 0; m < 4; ++m) _Pragma("unroll") for (int n = 0; n < 2; ++n) _Pragma("unroll") for (int k = 0; k < 2; ++k) \
;         acc[ai][bj][m][n] = __builtin_amdgcn_mfma_f32_16x16x32_bf16(Bt[n][k], At[m][k], acc[ai][bj][m][n], 0, 0, 0); __builtin_amdgcn_s_setprio(0); } while (0)
; #define PG8_WAIT_V(n) asm volatile("s_waitcnt vmcnt(" #n ")" ::: "memory")
; #define PG8_WAIT_L(n) asm volatile("s_waitcnt lgkmcnt(" #n ")" ::: "memory")
; #define PG8_BAR __builtin_amdgcn_s_barrier()
; #define PG8_SCHED __builtin_amdgcn_sched_barrier(0)
; template <class Epi, bool ALIGN_EPI>
; __device__ __forceinline__ void gemm_phase(LAS unsigned char* lds, const Gemm g, const StaticOrder& S, const Epi& E, const int tid) {
;     ...
;             PG8_LDA(At, 1, 1); PG8_STAGE(PG8_SB(1, 0), b3, voffB); PG8_STAGE(PG8_SB(1, 1), b3 + hstepB, voffB); PG8_STAGE(PG8_SA(1, 0), a3, voffA);
;             PG8_WAIT_V(8); PG8_WAIT_L(0); PG8_BAR; PG8_MMA(1, 0, At, B0); PG8_MMA(1, 1, At, B1); PG8_BAR; PG8_SCHED;
	global_load_lds_dwordx4 v144, s[54:55]
	s_add_i32 m0, s90, 0x2000
	s_add_u32 s52, s52, 0xc000
	s_addc_u32 s53, s53, 0
	global_load_lds_dwordx4 v140, s[54:55]
	s_add_i32 s54, s91, s71
	s_mov_b32 m0, s54
	ds_read_b128 v[218:221], v161 offset:56320
	global_load_lds_dwordx4 v144, s[52:53]
	s_add_i32 m0, s54, 0x2000
	ds_read_b128 v[214:217], v161 offset:55296
	global_load_lds_dwordx4 v140, s[52:53]
	s_mov_b32 m0, s79
	ds_read_b128 v[198:201], v161 offset:54272
	global_load_lds_dwordx4 v146, s[50:51]
	s_mov_b32 m0, s80
	ds_read_b128 v[194:197], v161 offset:53248
	global_load_lds_dwordx4 v142, s[50:51]
	s_waitcnt vmcnt(8)
	s_waitcnt lgkmcnt(0)
	s_barrier


; #define PG8_MMA(ai, bj, At, Bt) do { __builtin_amdgcn_s_setprio(1); _Pragma("unroll") for (int m = 0; m < 4; ++m) _Pragma("unroll") for (int n = 0; n < 2; ++n) _Pragma("unroll") for (int k = 0; k < 2; ++k) \
;         acc[ai][bj][m][n] = __builtin_amdgcn_mfma_f32_16x16x32_bf16(Bt[n][k], At[m][k], acc[ai][bj][m][n], 0, 0, 0); __builtin_amdgcn_s_setprio(0); } while (0)
; #define PG8_WAIT_V(n) asm volatile("s_waitcnt vmcnt(" #n ")" ::: "memory")
; #define PG8_WAIT_L(n) asm volatile("s_waitcnt lgkmcnt(" #n ")" ::: "memory")
; #define PG8_BAR __builtin_amdgcn_s_barrier()
; #define PG8_SCHED __builtin_amdgcn_sched_barrier(0)
; template <class Epi, bool ALIGN_EPI>
; __device__ __forceinline__ void gemm_phase(LAS unsigned char* lds, const Gemm g, const StaticOrder& S, const Epi& E, const int tid) {
;     ...
;             PG8_WAIT_V(8); PG8_WAIT_L(0); PG8_BAR; PG8_MMA(1, 0, At, B0); PG8_MMA(1, 1, At, B1); PG8_BAR; PG8_SCHED;
	v_mfma_f32_16x16x32_bf16 v[24:27], v[132:135], v[178:181], v[24:27]
	v_mfma_f32_16x16x32_bf16 v[24:27], v[136:139], v[182:185], v[24:27]
	v_mfma_f32_16x16x32_bf16 v[92:95], v[156:159], v[182:185], v[92:95]
	v_mfma_f32_16x16x32_bf16 v[92:95], v[152:155], v[178:181], v[92:95]
	v_mfma_f32_16x16x32_bf16 v[84:87], v[152:155], v[186:189], v[84:87]
	v_mfma_f32_16x16x32_bf16 v[84:87], v[156:159], v[190:193], v[84:87]
	v_mfma_f32_16x16x32_bf16 v[16:19], v[136:139], v[190:193], v[16:19]
	v_mfma_f32_16x16x32_bf16 v[16:19], v[132:135], v[186:189], v[16:19]
	v_mfma_f32_16x16x32_bf16 v[6:9], v[132:135], v[194:197], v[8:11]
	v_mfma_f32_16x16x32_bf16 v[8:11], v[136:139], v[198:201], v[6:9]
	v_mfma_f32_16x16x32_bf16 v[76:79], v[152:155], v[194:197], v[76:79]
	v_mfma_f32_16x16x32_bf16 v[76:79], v[156:159], v[198:201], v[76:79]
	v_mfma_f32_16x16x32_bf16 v[2:5], v[132:135], v[214:217], v[2:5]
	v_mfma_f32_16x16x32_bf16 v[4:7], v[136:139], v[218:221], v[2:5]
	v_mfma_f32_16x16x32_bf16 v[64:67], v[152:155], v[214:217], v[64:67]
	v_mfma_f32_16x16x32_bf16 v[64:67], v[156:159], v[218:221], v[64:67]


; #define PG8_MMA(ai, bj, At, Bt) do { __builtin_amdgcn_s_setprio(1); _Pragma("unroll") for (int m = 0; m < 4; ++m) _Pragma("unroll") for (int n = 0; n < 2; ++n) _Pragma("unroll") for (int k = 0; k < 2; ++k) \
;         acc[ai][bj][m][n] = __builtin_amdgcn_mfma_f32_16x16x32_bf16(Bt[n][k], At[m][k], acc[ai][bj][m][n], 0, 0, 0); __builtin_amdgcn_s_setprio(0); } while (0)
; #define PG8_WAIT_V(n) asm volatile("s_waitcnt vmcnt(" #n ")" ::: "memory")
; #define PG8_WAIT_L(n) asm volatile("s_waitcnt lgkmcnt(" #n ")" ::: "memory")
; #define PG8_BAR __builtin_amdgcn_s_barrier()
; #define PG8_SCHED __builtin_amdgcn_sched_barrier(0)
; template <class Epi, bool ALIGN_EPI>
; __device__ __forceinline__ void gemm_phase(LAS unsigned char* lds, const Gemm g, const StaticOrder& S, const Epi& E, const int tid) {
;     ...
;             PG8_WAIT_V(8); PG8_WAIT_L(0); PG8_BAR; PG8_MMA(1, 0, At, B0); PG8_MMA(1, 1, At, B1); PG8_BAR; PG8_SCHED;
	v_mfma_f32_16x16x32_bf16 v[32:35], v[162:165], v[178:181], v[32:35]
	v_mfma_f32_16x16x32_bf16 v[32:35], v[166:169], v[182:185], v[32:35]
	v_mfma_f32_16x16x32_bf16 v[72:75], v[174:177], v[182:185], v[72:75]
	v_mfma_f32_16x16x32_bf16 v[72:75], v[170:173], v[178:181], v[72:75]
	v_mfma_f32_16x16x32_bf16 v[96:99], v[170:173], v[186:189], v[96:99]
	v_mfma_f32_16x16x32_bf16 v[96:99], v[174:177], v[190:193], v[96:99]
	v_mfma_f32_16x16x32_bf16 v[28:31], v[166:169], v[190:193], v[28:31]
	v_mfma_f32_16x16x32_bf16 v[28:31], v[162:165], v[186:189], v[28:31]
	v_mfma_f32_16x16x32_bf16 v[20:23], v[162:165], v[194:197], v[20:23]
	v_mfma_f32_16x16x32_bf16 v[20:23], v[166:169], v[198:201], v[20:23]
	v_mfma_f32_16x16x32_bf16 v[56:59], v[174:177], v[198:201], v[56:59]
	v_mfma_f32_16x16x32_bf16 v[56:59], v[170:173], v[194:197], v[56:59]
	v_mfma_f32_16x16x32_bf16 v[44:47], v[170:173], v[214:217], v[44:47]
	v_mfma_f32_16x16x32_bf16 v[44:47], v[174:177], v[218:221], v[44:47]
	v_mfma_f32_16x16x32_bf16 v[12:15], v[166:169], v[218:221], v[12:15]
	v_mfma_f32_16x16x32_bf16 v[12:15], v[162:165], v[214:217], v[12:15]

; #define PG8_MMA(ai, bj, At, Bt) do { __builtin_amdgcn_s_setprio(1); _Pragma("unroll") for (int m = 0; m < 4; ++m) _Pragma("unroll") for (int n = 0; n < 2; ++n) _Pragma("unroll") for (int k = 0; k < 2; ++k) \
;         acc[ai][bj][m][n] = __builtin_amdgcn_mfma_f32_16x16x32_bf16(Bt[n][k], At[m][k], acc[ai][bj][m][n], 0, 0, 0); __builtin_amdgcn_s_setprio(0); } while (0)
; #define PG8_WAIT_V(n) asm volatile("s_waitcnt vmcnt(" #n ")" ::: "memory")
; #define PG8_WAIT_L(n) asm volatile("s_waitcnt lgkmcnt(" #n ")" ::: "memory")
; #define PG8_BAR __builtin_amdgcn_s_barrier()
; #define PG8_SCHED __builtin_amdgcn_sched_barrier(0)
; template <class Epi, bool ALIGN_EPI>
; __device__ __forceinline__ void gemm_phase(LAS unsigned char* lds, const Gemm g, const StaticOrder& S, const Epi& E, const int tid) {
;     ...
;             PG8_WAIT_V(8); PG8_WAIT_L(0); PG8_BAR; PG8_MMA(1, 0, At, B0); PG8_MMA(1, 1, At, B1); PG8_BAR; PG8_SCHED;
;         }
;         if constexpr (ALIGN_EPI) { if (wr == 0) PG8_BAR; }
	s_barrier
	s_add_i32 s89, s89, 2
	s_add_u32 s48, s48, 0x10000
	s_addc_u32 s49, s49, 0
	s_add_u32 vcc_hi, vcc_hi, 0x10000
	s_addc_u32 s88, s88, 0
	s_cmp_gt_u32 s89, 29
	s_cbranch_scc0 .LBB0_211
	s_and_b64 vcc, exec, s[22:23]
	s_cbranch_vccz .LBB0_214
	s_barrier

; #define PG8_STAGE(bufoff, gbase, voff) do { _Pragma("unroll") for (int _i = 0; _i < 2; ++_i) \
;         __builtin_amdgcn_global_load_lds((const unsigned*)((const char*)(gbase) + (voff)[_i]), (LAS unsigned*)(lds + (bufoff) + ldsw + _i * 8192), 16, 0, 0); } while (0)
; #define PG8_LDA(dst, b, h) do { _Pragma("unroll") for (int m = 0; m < 4; ++m) _Pragma("unroll") for (int k = 0; k < 2; ++k) dst[m][k] = *(const LAS bf16x8*)(lds + PG8_SA(b, h) + aoff + m * 2048 + k * 1024); } while (0)
; #define PG8_LDB(dst, b, h) do { _Pragma("unroll") for (int n = 0; n < 2; ++n) _Pragma("unroll") for (int k = 0; k < 2; ++k) dst[n][k] = *(const LAS bf16x8*)(lds + PG8_SB(b, h) + boff + n * 2048 + k * 1024); } while (0)
; #define PG8_SCHED __builtin_amdgcn_sched_barrier(0)
; template <class Epi, bool ALIGN_EPI>
; __device__ __forceinline__ void gemm_phase(LAS unsigned char* lds, const Gemm g, const StaticOrder& S, const Epi& E, const int tid) {
;     ...
;         const char* nA = has_next ? (const char*)g.A + (size_t)nxt.pm * tstepA + (size_t)nxt.pn * g.acs : cA; const char* nB = has_next ? (const char*)g.Bt + (size_t)nxt.pn * tstepB : cB;
;         for (int t = 0; t < nt; t += 2) {
;             const bool last = (t == nt - 2);
;             const char* a1 = cA + (size_t)(t + 1) * kstepA;
;             const char* a2 = last ? nA : cA + (size_t)(t + 2) * kstepA; const char* b2 = last ? nB : cB + (size_t)(t + 2) * kstepB;
;             const char* a3 = a2 + kstepA; const char* b3 = b2 + kstepB;
;             PG8_LDB(B0, 0, 0); PG8_LDB(B1, 0, 1); PG8_SCHED; PG8_LDA(At, 0, 0); PG8_STAGE(PG8_SA(1, 1), a1 + hstepA, voffA);
.LBB0_294:
	s_add_u32 s22, s10, 0x4000
	s_addc_u32 s23, s11, 0
	s_cmpk_eq_i32 s86, 0x54
	s_cselect_b32 s42, s48, s22
	s_cselect_b32 s43, s49, s23
	s_cselect_b32 s34, s50, s84
	s_cselect_b32 s35, s51, s85
	s_add_u32 s22, s42, 0x8000
	s_addc_u32 s23, s43, 0
	s_add_i32 s87, 0, 0x10000
	v_add_u32_e32 v0, s87, v154
	s_add_i32 s90, 0, 0x14000
	s_waitcnt lgkmcnt(0)
	ds_read_b128 v[132:135], v0
	ds_read_b128 v[148:151], v0 offset:1024
	ds_read_b128 v[156:159], v0 offset:2048
	ds_read_b128 v[160:163], v0 offset:3072
	v_add_u32_e32 v0, s90, v154
	ds_read_b128 v[164:167], v0
	ds_read_b128 v[168:171], v0 offset:1024
	ds_read_b128 v[172:175], v0 offset:2048
	ds_read_b128 v[176:179], v0 offset:3072
	s_add_i32 m0, s57, 0xc000
	ds_read_b128 v[180:183], v155
	ds_read_b128 v[184:187], v155 offset:1024
	ds_read_b128 v[188:191], v155 offset:2048
	ds_read_b128 v[192:195], v155 offset:3072
	ds_read_b128 v[196:199], v155 offset:4096
	ds_read_b128 v[214:217], v155 offset:5120
	ds_read_b128 v[218:221], v155 offset:6144

; #define PG8_STAGE(bufoff, gbase, voff) do { _Pragma("unroll") for (int _i = 0; _i < 2; ++_i) \
;         __builtin_amdgcn_global_load_lds((const unsigned*)((const char*)(gbase) + (voff)[_i]), (LAS unsigned*)(lds + (bufoff) + ldsw + _i * 8192), 16, 0, 0); } while (0)
; #define PG8_LDA(dst, b, h) do { _Pragma("unroll") for (int m = 0; m < 4; ++m) _Pragma("unroll") for (int k = 0; k < 2; ++k) dst[m][k] = *(const LAS bf16x8*)(lds + PG8_SA(b, h) + aoff + m * 2048 + k * 1024); } while (0)
; #define PG8_LDB(dst, b, h) do { _Pragma("unroll") for (int n = 0; n < 2; ++n) _Pragma("unroll") for (int k = 0; k < 2; ++k) dst[n][k] = *(const LAS bf16x8*)(lds + PG8_SB(b, h) + boff + n * 2048 + k * 1024); } while (0)
; #define PG8_MMA(ai, bj, At, Bt) do { __builtin_amdgcn_s_setprio(1); _Pragma("unroll") for (int m = 0; m < 4; ++m) _Pragma("unroll") for (int n = 0; n < 2; ++n) _Pragma("unroll") for (int k = 0; k < 2; ++k) \
;         acc[ai][bj][m][n] = __builtin_amdgcn_mfma_f32_16x16x32_bf16(Bt[n][k], At[m][k], acc[ai][bj][m][n], 0, 0, 0); __builtin_amdgcn_s_setprio(0); } while (0)
; #define PG8_WAIT_V(n) asm volatile("s_waitcnt vmcnt(" #n ")" ::: "memory")
; #define PG8_WAIT_L(n) asm volatile("s_waitcnt lgkmcnt(" #n ")" ::: "memory")
; #define PG8_BAR __builtin_amdgcn_s_barrier()
; #define PG8_SCHED __builtin_amdgcn_sched_barrier(0)
; template <class Epi, bool ALIGN_EPI>
; __device__ __forceinline__ void gemm_phase(LAS unsigned char* lds, const Gemm g, const StaticOrder& S, const Epi& E, const int tid) {
;     ...
;             PG8_LDB(B0, 0, 0); PG8_LDB(B1, 0, 1); PG8_SCHED; PG8_LDA(At, 0, 0); PG8_STAGE(PG8_SA(1, 1), a1 + hstepA, voffA);
;             PG8_WAIT_V(8); PG8_WAIT_L(0); PG8_BAR; PG8_MMA(0, 0, At, B0); PG8_MMA(0, 1, At, B1); PG8_BAR; PG8_SCHED;
	global_load_lds_dwordx4 v144, s[10:11]
	s_add_i32 m0, s57, 0xe000
	ds_read_b128 v[222:225], v155 offset:7168
	global_load_lds_dwordx4 v146, s[10:11]
	s_waitcnt vmcnt(8)
	s_waitcnt lgkmcnt(0)
	s_barrier


; #define PG8_MMA(ai, bj, At, Bt) do { __builtin_amdgcn_s_setprio(1); _Pragma("unroll") for (int m = 0; m < 4; ++m) _Pragma("unroll") for (int n = 0; n < 2; ++n) _Pragma("unroll") for (int k = 0; k < 2; ++k) \
;         acc[ai][bj][m][n] = __builtin_amdgcn_mfma_f32_16x16x32_bf16(Bt[n][k], At[m][k], acc[ai][bj][m][n], 0, 0, 0); __builtin_amdgcn_s_setprio(0); } while (0)
; #define PG8_WAIT_V(n) asm volatile("s_waitcnt vmcnt(" #n ")" ::: "memory")
; #define PG8_WAIT_L(n) asm volatile("s_waitcnt lgkmcnt(" #n ")" ::: "memory")
; #define PG8_BAR __builtin_amdgcn_s_barrier()
; #define PG8_SCHED __builtin_amdgcn_sched_barrier(0)
; template <class Epi, bool ALIGN_EPI>
; __device__ __forceinline__ void gemm_phase(LAS unsigned char* lds, const Gemm g, const StaticOrder& S, const Epi& E, const int tid) {
;     ...
;             PG8_WAIT_V(8); PG8_WAIT_L(0); PG8_BAR; PG8_MMA(0, 0, At, B0); PG8_MMA(0, 1, At, B1); PG8_BAR; PG8_SCHED;
	v_mfma_f32_16x16x32_bf16 v[8:11], v[132:135], v[180:183], v[8:11]
	v_mfma_f32_16x16x32_bf16 v[8:11], v[148:151], v[184:187], v[8:11]
	v_mfma_f32_16x16x32_bf16 v[56:59], v[160:163], v[184:187], v[56:59]
	v_mfma_f32_16x16x32_bf16 v[56:59], v[156:159], v[180:183], v[56:59]
	v_mfma_f32_16x16x32_bf16 v[48:51], v[156:159], v[188:191], v[48:51]
	v_mfma_f32_16x16x32_bf16 v[48:51], v[160:163], v[192:195], v[48:51]
	v_mfma_f32_16x16x32_bf16 v[52:55], v[148:151], v[192:195], v[52:55]
	v_mfma_f32_16x16x32_bf16 v[52:55], v[132:135], v[188:191], v[52:55]
	v_mfma_f32_16x16x32_bf16 v[44:47], v[132:135], v[196:199], v[44:47]
	v_mfma_f32_16x16x32_bf16 v[44:47], v[148:151], v[214:217], v[44:47]
	v_mfma_f32_16x16x32_bf16 v[40:43], v[160:163], v[214:217], v[40:43]
	v_mfma_f32_16x16x32_bf16 v[40:43], v[156:159], v[196:199], v[40:43]
	v_mfma_f32_16x16x32_bf16 v[32:35], v[156:159], v[218:221], v[32:35]
	v_mfma_f32_16x16x32_bf16 v[32:35], v[160:163], v[222:225], v[32:35]
	v_mfma_f32_16x16x32_bf16 v[36:39], v[148:151], v[222:225], v[36:39]
	v_mfma_f32_16x16x32_bf16 v[36:39], v[132:135], v[218:221], v[36:39]


; #define PG8_MMA(ai, bj, At, Bt) do { __builtin_amdgcn_s_setprio(1); _Pragma("unroll") for (int m = 0; m < 4; ++m) _Pragma("unroll") for (int n = 0; n < 2; ++n) _Pragma("unroll") for (int k = 0; k < 2; ++k) \
;         acc[ai][bj][m][n] = __builtin_amdgcn_mfma_f32_16x16x32_bf16(Bt[n][k], At[m][k], acc[ai][bj][m][n], 0, 0, 0); __builtin_amdgcn_s_setprio(0); } while (0)
; #define PG8_WAIT_V(n) asm volatile("s_waitcnt vmcnt(" #n ")" ::: "memory")
; #define PG8_WAIT_L(n) asm volatile("s_waitcnt lgkmcnt(" #n ")" ::: "memory")
; #define PG8_BAR __builtin_amdgcn_s_barrier()
; #define PG8_SCHED __builtin_amdgcn_sched_barrier(0)
; template <class Epi, bool ALIGN_EPI>
; __device__ __forceinline__ void gemm_phase(LAS unsigned char* lds, const Gemm g, const StaticOrder& S, const Epi& E, const int tid) {
;     ...
;             PG8_WAIT_V(8); PG8_WAIT_L(0); PG8_BAR; PG8_MMA(0, 0, At, B0); PG8_MMA(0, 1, At, B1); PG8_BAR; PG8_SCHED;
	v_mfma_f32_16x16x32_bf16 v[2:5], v[164:167], v[180:183], v[4:7]
	v_mfma_f32_16x16x32_bf16 v[2:5], v[168:171], v[184:187], v[2:5]
	v_mfma_f32_16x16x32_bf16 v[28:31], v[176:179], v[184:187], v[28:31]
	v_mfma_f32_16x16x32_bf16 v[28:31], v[172:175], v[180:183], v[28:31]
	v_mfma_f32_16x16x32_bf16 v[92:95], v[172:175], v[188:191], v[92:95]
	v_mfma_f32_16x16x32_bf16 v[92:95], v[176:179], v[192:195], v[92:95]
	v_mfma_f32_16x16x32_bf16 v[96:99], v[168:171], v[192:195], v[96:99]
	v_mfma_f32_16x16x32_bf16 v[96:99], v[164:167], v[188:191], v[96:99]
	v_mfma_f32_16x16x32_bf16 v[88:91], v[164:167], v[196:199], v[88:91]
	v_mfma_f32_16x16x32_bf16 v[88:91], v[168:171], v[214:217], v[88:91]
	v_mfma_f32_16x16x32_bf16 v[84:87], v[176:179], v[214:217], v[84:87]
	v_mfma_f32_16x16x32_bf16 v[84:87], v[172:175], v[196:199], v[84:87]
	v_mfma_f32_16x16x32_bf16 v[76:79], v[172:175], v[218:221], v[76:79]
	v_mfma_f32_16x16x32_bf16 v[76:79], v[176:179], v[222:225], v[76:79]
	v_mfma_f32_16x16x32_bf16 v[80:83], v[168:171], v[222:225], v[80:83]
	v_mfma_f32_16x16x32_bf16 v[80:83], v[164:167], v[218:221], v[80:83]

; #define PG8_STAGE(bufoff, gbase, voff) do { _Pragma("unroll") for (int _i = 0; _i < 2; ++_i) \
;         __builtin_amdgcn_global_load_lds((const unsigned*)((const char*)(gbase) + (voff)[_i]), (LAS unsigned*)(lds + (bufoff) + ldsw + _i * 8192), 16, 0, 0); } while (0)
; #define PG8_LDA(dst, b, h) do { _Pragma("unroll") for (int m = 0; m < 4; ++m) _Pragma("unroll") for (int k = 0; k < 2; ++k) dst[m][k] = *(const LAS bf16x8*)(lds + PG8_SA(b, h) + aoff + m * 2048 + k * 1024); } while (0)
; #define PG8_MMA(ai, bj, At, Bt) do { __builtin_amdgcn_s_setprio(1); _Pragma("unroll") for (int m = 0; m < 4; ++m) _Pragma("unroll") for (int n = 0; n < 2; ++n) _Pragma("unroll") for (int k = 0; k < 2; ++k) \
;         acc[ai][bj][m][n] = __builtin_amdgcn_mfma_f32_16x16x32_bf16(Bt[n][k], At[m][k], acc[ai][bj][m][n], 0, 0, 0); __builtin_amdgcn_s_setprio(0); } while (0)
; #define PG8_WAIT_V(n) asm volatile("s_waitcnt vmcnt(" #n ")" ::: "memory")
; #define PG8_WAIT_L(n) asm volatile("s_waitcnt lgkmcnt(" #n ")" ::: "memory")
; #define PG8_BAR __builtin_amdgcn_s_barrier()
; #define PG8_SCHED __builtin_amdgcn_sched_barrier(0)
; template <class Epi, bool ALIGN_EPI>
; __device__ __forceinline__ void gemm_phase(LAS unsigned char* lds, const Gemm g, const StaticOrder& S, const Epi& E, const int tid) {
;     ...
;             PG8_WAIT_V(8); PG8_WAIT_L(0); PG8_BAR; PG8_MMA(0, 0, At, B0); PG8_MMA(0, 1, At, B1); PG8_BAR; PG8_SCHED;
;             PG8_LDA(At, 0, 1); PG8_STAGE(PG8_SB(0, 0), b2, voffB); PG8_STAGE(PG8_SB(0, 1), b2 + hstepB, voffB); PG8_STAGE(PG8_SA(0, 0), a2, voffA);
	s_barrier
	s_add_i32 s87, s87, s56
	s_mov_b32 m0, s87
	ds_read_b128 v[180:183], v155 offset:16384
	ds_read_b128 v[184:187], v155 offset:17408
	ds_read_b128 v[188:191], v155 offset:18432
	ds_read_b128 v[192:195], v155 offset:19456


; #define PG8_STAGE(bufoff, gbase, voff) do { _Pragma("unroll") for (int _i = 0; _i < 2; ++_i) \
;         __builtin_amdgcn_global_load_lds((const unsigned*)((const char*)(gbase) + (voff)[_i]), (LAS unsigned*)(lds + (bufoff) + ldsw + _i * 8192), 16, 0, 0); } while (0)
; #define PG8_LDA(dst, b, h) do { _Pragma("unroll") for (int m = 0; m < 4; ++m) _Pragma("unroll") for (int k = 0; k < 2; ++k) dst[m][k] = *(const LAS bf16x8*)(lds + PG8_SA(b, h) + aoff + m * 2048 + k * 1024); } while (0)
; #define PG8_MMA(ai, bj, At, Bt) do { __builtin_amdgcn_s_setprio(1); _Pragma("unroll") for (int m = 0; m < 4; ++m) _Pragma("unroll") for (int n = 0; n < 2; ++n) _Pragma("unroll") for (int k = 0; k < 2; ++k) \
;         acc[ai][bj][m][n] = __builtin_amdgcn_mfma_f32_16x16x32_bf16(Bt[n][k], At[m][k], acc[ai][bj][m][n], 0, 0, 0); __builtin_amdgcn_s_setprio(0); } while (0)
; #define PG8_WAIT_V(n) asm volatile("s_waitcnt vmcnt(" #n ")" ::: "memory")
; #define PG8_WAIT_L(n) asm volatile("s_waitcnt lgkmcnt(" #n ")" ::: "memory")
; #define PG8_BAR __builtin_amdgcn_s_barrier()
; #define PG8_SCHED __builtin_amdgcn_sched_barrier(0)
; template <class Epi, bool ALIGN_EPI>
; __device__ __forceinline__ void gemm_phase(LAS unsigned char* lds, const Gemm g, const StaticOrder& S, const Epi& E, const int tid) {
;     ...
;             PG8_LDA(At, 0, 1); PG8_STAGE(PG8_SB(0, 0), b2, voffB); PG8_STAGE(PG8_SB(0, 1), b2 + hstepB, voffB); PG8_STAGE(PG8_SA(0, 0), a2, voffA);
;             PG8_WAIT_V(8); PG8_WAIT_L(0); PG8_BAR; PG8_MMA(1, 0, At, B0); PG8_MMA(1, 1, At, B1); PG8_BAR; PG8_SCHED;
	global_load_lds_dwordx4 v140, s[34:35]
	s_add_i32 m0, s87, 0x2000
	s_add_u32 s88, s34, 0x4000
	s_addc_u32 s89, s35, 0
	s_add_i32 s87, s90, s56
	global_load_lds_dwordx4 v136, s[34:35]
	s_mov_b32 m0, s87
	ds_read_b128 v[222:225], v155 offset:23552
	global_load_lds_dwordx4 v140, s[88:89]
	s_add_i32 m0, s87, 0x2000
	ds_read_b128 v[218:221], v155 offset:22528
	global_load_lds_dwordx4 v136, s[88:89]
	s_mov_b32 m0, s57
	ds_read_b128 v[214:217], v155 offset:21504
	global_load_lds_dwordx4 v142, s[42:43]
	s_mov_b32 m0, s60
	ds_read_b128 v[196:199], v155 offset:20480
	global_load_lds_dwordx4 v138, s[42:43]
	s_waitcnt vmcnt(8)
	s_waitcnt lgkmcnt(0)
	s_barrier


; #define PG8_MMA(ai, bj, At, Bt) do { __builtin_amdgcn_s_setprio(1); _Pragma("unroll") for (int m = 0; m < 4; ++m) _Pragma("unroll") for (int n = 0; n < 2; ++n) _Pragma("unroll") for (int k = 0; k < 2; ++k) \
;         acc[ai][bj][m][n] = __builtin_amdgcn_mfma_f32_16x16x32_bf16(Bt[n][k], At[m][k], acc[ai][bj][m][n], 0, 0, 0); __builtin_amdgcn_s_setprio(0); } while (0)
; #define PG8_WAIT_V(n) asm volatile("s_waitcnt vmcnt(" #n ")" ::: "memory")
; #define PG8_WAIT_L(n) asm volatile("s_waitcnt lgkmcnt(" #n ")" ::: "memory")
; #define PG8_BAR __builtin_amdgcn_s_barrier()
; #define PG8_SCHED __builtin_amdgcn_sched_barrier(0)
; template <class Epi, bool ALIGN_EPI>
; __device__ __forceinline__ void gemm_phase(LAS unsigned char* lds, const Gemm g, const StaticOrder& S, const Epi& E, const int tid) {
;     ...
;             PG8_WAIT_V(8); PG8_WAIT_L(0); PG8_BAR; PG8_MMA(1, 0, At, B0); PG8_MMA(1, 1, At, B1); PG8_BAR; PG8_SCHED;
	v_mfma_f32_16x16x32_bf16 v[24:27], v[132:135], v[180:183], v[24:27]
	v_mfma_f32_16x16x32_bf16 v[24:27], v[148:151], v[184:187], v[24:27]
	v_mfma_f32_16x16x32_bf16 v[20:23], v[160:163], v[184:187], v[20:23]
	v_mfma_f32_16x16x32_bf16 v[20:23], v[156:159], v[180:183], v[20:23]
	v_mfma_f32_16x16x32_bf16 v[72:75], v[156:159], v[188:191], v[72:75]
	v_mfma_f32_16x16x32_bf16 v[72:75], v[160:163], v[192:195], v[72:75]
	v_mfma_f32_16x16x32_bf16 v[64:67], v[148:151], v[192:195], v[64:67]
	v_mfma_f32_16x16x32_bf16 v[64:67], v[132:135], v[188:191], v[64:67]
	v_mfma_f32_16x16x32_bf16 v[16:19], v[132:135], v[196:199], v[16:19]
	v_mfma_f32_16x16x32_bf16 v[16:19], v[148:151], v[214:217], v[16:19]
	v_mfma_f32_16x16x32_bf16 v[12:15], v[160:163], v[214:217], v[12:15]
	v_mfma_f32_16x16x32_bf16 v[12:15], v[156:159], v[196:199], v[12:15]
	v_mfma_f32_16x16x32_bf16 v[68:71], v[156:159], v[218:221], v[68:71]
	v_mfma_f32_16x16x32_bf16 v[68:71], v[160:163], v[222:225], v[68:71]
	v_mfma_f32_16x16x32_bf16 v[60:63], v[148:151], v[222:225], v[60:63]
	v_mfma_f32_16x16x32_bf16 v[60:63], v[132:135], v[218:221], v[60:63]


; #define PG8_MMA(ai, bj, At, Bt) do { __builtin_amdgcn_s_setprio(1); _Pragma("unroll") for (int m = 0; m < 4; ++m) _Pragma("unroll") for (int n = 0; n < 2; ++n) _Pragma("unroll") for (int k = 0; k < 2; ++k) \
;         acc[ai][bj][m][n] = __builtin_amdgcn_mfma_f32_16x16x32_bf16(Bt[n][k], At[m][k], acc[ai][bj][m][n], 0, 0, 0); __builtin_amdgcn_s_setprio(0); } while (0)
; #define PG8_WAIT_V(n) asm volatile("s_waitcnt vmcnt(" #n ")" ::: "memory")
; #define PG8_WAIT_L(n) asm volatile("s_waitcnt lgkmcnt(" #n ")" ::: "memory")
; #define PG8_BAR __builtin_amdgcn_s_barrier()
; #define PG8_SCHED __builtin_amdgcn_sched_barrier(0)
; template <class Epi, bool ALIGN_EPI>
; __device__ __forceinline__ void gemm_phase(LAS unsigned char* lds, const Gemm g, const StaticOrder& S, const Epi& E, const int tid) {
;     ...
;             PG8_WAIT_V(8); PG8_WAIT_L(0); PG8_BAR; PG8_MMA(1, 0, At, B0); PG8_MMA(1, 1, At, B1); PG8_BAR; PG8_SCHED;
	v_mfma_f32_16x16x32_bf16 v[128:131], v[164:167], v[180:183], v[128:131]
	v_mfma_f32_16x16x32_bf16 v[128:131], v[168:171], v[184:187], v[128:131]
	v_mfma_f32_16x16x32_bf16 v[124:127], v[176:179], v[184:187], v[124:127]
	v_mfma_f32_16x16x32_bf16 v[124:127], v[172:175], v[180:183], v[124:127]
	v_mfma_f32_16x16x32_bf16 v[116:119], v[172:175], v[188:191], v[116:119]
	v_mfma_f32_16x16x32_bf16 v[116:119], v[176:179], v[192:195], v[116:119]
	v_mfma_f32_16x16x32_bf16 v[120:123], v[168:171], v[192:195], v[120:123]
	v_mfma_f32_16x16x32_bf16 v[120:123], v[164:167], v[188:191], v[120:123]
	v_mfma_f32_16x16x32_bf16 v[112:115], v[164:167], v[196:199], v[112:115]
	v_mfma_f32_16x16x32_bf16 v[112:115], v[168:171], v[214:217], v[112:115]
	v_mfma_f32_16x16x32_bf16 v[108:111], v[176:179], v[214:217], v[108:111]
	v_mfma_f32_16x16x32_bf16 v[108:111], v[172:175], v[196:199], v[108:111]
	v_mfma_f32_16x16x32_bf16 v[100:103], v[172:175], v[218:221], v[100:103]
	v_mfma_f32_16x16x32_bf16 v[100:103], v[176:179], v[222:225], v[100:103]
	v_mfma_f32_16x16x32_bf16 v[104:107], v[168:171], v[222:225], v[104:107]
	v_mfma_f32_16x16x32_bf16 v[104:107], v[164:167], v[218:221], v[104:107]

; #define PG8_STAGE(bufoff, gbase, voff) do { _Pragma("unroll") for (int _i = 0; _i < 2; ++_i) \
;         __builtin_amdgcn_global_load_lds((const unsigned*)((const char*)(gbase) + (voff)[_i]), (LAS unsigned*)(lds + (bufoff) + ldsw + _i * 8192), 16, 0, 0); } while (0)
; #define PG8_LDA(dst, b, h) do { _Pragma("unroll") for (int m = 0; m < 4; ++m) _Pragma("unroll") for (int k = 0; k < 2; ++k) dst[m][k] = *(const LAS bf16x8*)(lds + PG8_SA(b, h) + aoff + m * 2048 + k * 1024); } while (0)
; #define PG8_LDB(dst, b, h) do { _Pragma("unroll") for (int n = 0; n < 2; ++n) _Pragma("unroll") for (int k = 0; k < 2; ++k) dst[n][k] = *(const LAS bf16x8*)(lds + PG8_SB(b, h) + boff + n * 2048 + k * 1024); } while (0)
; #define PG8_MMA(ai, bj, At, Bt) do { __builtin_amdgcn_s_setprio(1); _Pragma("unroll") for (int m = 0; m < 4; ++m) _Pragma("unroll") for (int n = 0; n < 2; ++n) _Pragma("unroll") for (int k = 0; k < 2; ++k) \
;         acc[ai][bj][m][n] = __builtin_amdgcn_mfma_f32_16x16x32_bf16(Bt[n][k], At[m][k], acc[ai][bj][m][n], 0, 0, 0); __builtin_amdgcn_s_setprio(0); } while (0)
; #define PG8_WAIT_V(n) asm volatile("s_waitcnt vmcnt(" #n ")" ::: "memory")
; #define PG8_WAIT_L(n) asm volatile("s_waitcnt lgkmcnt(" #n ")" ::: "memory")
; #define PG8_BAR __builtin_amdgcn_s_barrier()
; #define PG8_SCHED __builtin_amdgcn_sched_barrier(0)
; template <class Epi, bool ALIGN_EPI>
; __device__ __forceinline__ void gemm_phase(LAS unsigned char* lds, const Gemm g, const StaticOrder& S, const Epi& E, const int tid) {
;     ...
;             PG8_LDB(B0, 1, 0); PG8_LDB(B1, 1, 1); PG8_SCHED; PG8_LDA(At, 1, 0); PG8_STAGE(PG8_SA(0, 1), a2 + hstepA, voffA);
;             PG8_WAIT_V(8); PG8_WAIT_L(0); PG8_BAR; PG8_MMA(0, 0, At, B0); PG8_MMA(0, 1, At, B1); PG8_BAR; PG8_SCHED;
	s_barrier
	s_add_i32 s87, 0, 0x18000
	v_add_u32_e32 v0, s87, v154
	s_add_i32 s88, 0, 0x1c000
	ds_read_b128 v[132:135], v0
	ds_read_b128 v[148:151], v0 offset:1024
	ds_read_b128 v[156:159], v0 offset:2048
	ds_read_b128 v[160:163], v0 offset:3072
	v_add_u32_e32 v0, s88, v154
	ds_read_b128 v[164:167], v0
	ds_read_b128 v[168:171], v0 offset:1024
	ds_read_b128 v[172:175], v0 offset:2048
	ds_read_b128 v[176:179], v0 offset:3072
	s_add_u32 s42, s42, 0x4000
	s_addc_u32 s43, s43, 0
	s_mov_b32 m0, s61
	ds_read_b128 v[180:183], v155 offset:32768
	ds_read_b128 v[184:187], v155 offset:33792
	ds_read_b128 v[188:191], v155 offset:34816
	ds_read_b128 v[192:195], v155 offset:35840
	ds_read_b128 v[196:199], v155 offset:36864
	ds_read_b128 v[214:217], v155 offset:37888
	ds_read_b128 v[218:221], v155 offset:38912

; #define PG8_STAGE(bufoff, gbase, voff) do { _Pragma("unroll") for (int _i = 0; _i < 2; ++_i) \
;         __builtin_amdgcn_global_load_lds((const unsigned*)((const char*)(gbase) + (voff)[_i]), (LAS unsigned*)(lds + (bufoff) + ldsw + _i * 8192), 16, 0, 0); } while (0)
; #define PG8_LDA(dst, b, h) do { _Pragma("unroll") for (int m = 0; m < 4; ++m) _Pragma("unroll") for (int k = 0; k < 2; ++k) dst[m][k] = *(const LAS bf16x8*)(lds + PG8_SA(b, h) + aoff + m * 2048 + k * 1024); } while (0)
; #define PG8_LDB(dst, b, h) do { _Pragma("unroll") for (int n = 0; n < 2; ++n) _Pragma("unroll") for (int k = 0; k < 2; ++k) dst[n][k] = *(const LAS bf16x8*)(lds + PG8_SB(b, h) + boff + n * 2048 + k * 1024); } while (0)
; #define PG8_MMA(ai, bj, At, Bt) do { __builtin_amdgcn_s_setprio(1); _Pragma("unroll") for (int m = 0; m < 4; ++m) _Pragma("unroll") for (int n = 0; n < 2; ++n) _Pragma("unroll") for (int k = 0; k < 2; ++k) \
;         acc[ai][bj][m][n] = __builtin_amdgcn_mfma_f32_16x16x32_bf16(Bt[n][k], At[m][k], acc[ai][bj][m][n], 0, 0, 0); __builtin_amdgcn_s_setprio(0); } while (0)
; #define PG8_WAIT_V(n) asm volatile("s_waitcnt vmcnt(" #n ")" ::: "memory")
; #define PG8_WAIT_L(n) asm volatile("s_waitcnt lgkmcnt(" #n ")" ::: "memory")
; #define PG8_BAR __builtin_amdgcn_s_barrier()
; #define PG8_SCHED __builtin_amdgcn_sched_barrier(0)
; template <class Epi, bool ALIGN_EPI>
; __device__ __forceinline__ void gemm_phase(LAS unsigned char* lds, const Gemm g, const StaticOrder& S, const Epi& E, const int tid) {
;     ...
;             PG8_LDB(B0, 1, 0); PG8_LDB(B1, 1, 1); PG8_SCHED; PG8_LDA(At, 1, 0); PG8_STAGE(PG8_SA(0, 1), a2 + hstepA, voffA);
;             PG8_WAIT_V(8); PG8_WAIT_L(0); PG8_BAR; PG8_MMA(0, 0, At, B0); PG8_MMA(0, 1, At, B1); PG8_BAR; PG8_SCHED;
	global_load_lds_dwordx4 v142, s[42:43]
	s_mov_b32 m0, s71
	ds_read_b128 v[222:225], v155 offset:39936
	global_load_lds_dwordx4 v138, s[42:43]
	s_waitcnt vmcnt(8)
	s_waitcnt lgkmcnt(0)
	s_barrier


; #define PG8_MMA(ai, bj, At, Bt) do { __builtin_amdgcn_s_setprio(1); _Pragma("unroll") for (int m = 0; m < 4; ++m) _Pragma("unroll") for (int n = 0; n < 2; ++n) _Pragma("unroll") for (int k = 0; k < 2; ++k) \
;         acc[ai][bj][m][n] = __builtin_amdgcn_mfma_f32_16x16x32_bf16(Bt[n][k], At[m][k], acc[ai][bj][m][n], 0, 0, 0); __builtin_amdgcn_s_setprio(0); } while (0)
; #define PG8_WAIT_V(n) asm volatile("s_waitcnt vmcnt(" #n ")" ::: "memory")
; #define PG8_WAIT_L(n) asm volatile("s_waitcnt lgkmcnt(" #n ")" ::: "memory")
; #define PG8_BAR __builtin_amdgcn_s_barrier()
; #define PG8_SCHED __builtin_amdgcn_sched_barrier(0)
; template <class Epi, bool ALIGN_EPI>
; __device__ __forceinline__ void gemm_phase(LAS unsigned char* lds, const Gemm g, const StaticOrder& S, const Epi& E, const int tid) {
;     ...
;             PG8_WAIT_V(8); PG8_WAIT_L(0); PG8_BAR; PG8_MMA(0, 0, At, B0); PG8_MMA(0, 1, At, B1); PG8_BAR; PG8_SCHED;
	v_mfma_f32_16x16x32_bf16 v[6:9], v[132:135], v[180:183], v[8:11]
	v_mfma_f32_16x16x32_bf16 v[8:11], v[148:151], v[184:187], v[6:9]
	v_mfma_f32_16x16x32_bf16 v[56:59], v[160:163], v[184:187], v[56:59]
	v_mfma_f32_16x16x32_bf16 v[56:59], v[156:159], v[180:183], v[56:59]
	v_mfma_f32_16x16x32_bf16 v[48:51], v[156:159], v[188:191], v[48:51]
	v_mfma_f32_16x16x32_bf16 v[48:51], v[160:163], v[192:195], v[48:51]
	v_mfma_f32_16x16x32_bf16 v[52:55], v[148:151], v[192:195], v[52:55]
	v_mfma_f32_16x16x32_bf16 v[52:55], v[132:135], v[188:191], v[52:55]
	v_mfma_f32_16x16x32_bf16 v[44:47], v[132:135], v[196:199], v[44:47]
	v_mfma_f32_16x16x32_bf16 v[44:47], v[148:151], v[214:217], v[44:47]
	v_mfma_f32_16x16x32_bf16 v[40:43], v[160:163], v[214:217], v[40:43]
	v_mfma_f32_16x16x32_bf16 v[40:43], v[156:159], v[196:199], v[40:43]
	v_mfma_f32_16x16x32_bf16 v[32:35], v[156:159], v[218:221], v[32:35]
	v_mfma_f32_16x16x32_bf16 v[32:35], v[160:163], v[222:225], v[32:35]
	v_mfma_f32_16x16x32_bf16 v[36:39], v[148:151], v[222:225], v[36:39]
	v_mfma_f32_16x16x32_bf16 v[36:39], v[132:135], v[218:221], v[36:39]


; #define PG8_MMA(ai, bj, At, Bt) do { __builtin_amdgcn_s_setprio(1); _Pragma("unroll") for (int m = 0; m < 4; ++m) _Pragma("unroll") for (int n = 0; n < 2; ++n) _Pragma("unroll") for (int k = 0; k < 2; ++k) \
;         acc[ai][bj][m][n] = __builtin_amdgcn_mfma_f32_16x16x32_bf16(Bt[n][k], At[m][k], acc[ai][bj][m][n], 0, 0, 0); __builtin_amdgcn_s_setprio(0); } while (0)
; #define PG8_WAIT_V(n) asm volatile("s_waitcnt vmcnt(" #n ")" ::: "memory")
; #define PG8_WAIT_L(n) asm volatile("s_waitcnt lgkmcnt(" #n ")" ::: "memory")
; #define PG8_BAR __builtin_amdgcn_s_barrier()
; #define PG8_SCHED __builtin_amdgcn_sched_barrier(0)
; template <class Epi, bool ALIGN_EPI>
; __device__ __forceinline__ void gemm_phase(LAS unsigned char* lds, const Gemm g, const StaticOrder& S, const Epi& E, const int tid) {
;     ...
;             PG8_WAIT_V(8); PG8_WAIT_L(0); PG8_BAR; PG8_MMA(0, 0, At, B0); PG8_MMA(0, 1, At, B1); PG8_BAR; PG8_SCHED;
	v_mfma_f32_16x16x32_bf16 v[2:5], v[164:167], v[180:183], v[2:5]
	v_mfma_f32_16x16x32_bf16 v[4:7], v[168:171], v[184:187], v[2:5]
	v_mfma_f32_16x16x32_bf16 v[28:31], v[176:179], v[184:187], v[28:31]
	v_mfma_f32_16x16x32_bf16 v[28:31], v[172:175], v[180:183], v[28:31]
	v_mfma_f32_16x16x32_bf16 v[92:95], v[172:175], v[188:191], v[92:95]
	v_mfma_f32_16x16x32_bf16 v[92:95], v[176:179], v[192:195], v[92:95]
	v_mfma_f32_16x16x32_bf16 v[96:99], v[168:171], v[192:195], v[96:99]
	v_mfma_f32_16x16x32_bf16 v[96:99], v[164:167], v[188:191], v[96:99]
	v_mfma_f32_16x16x32_bf16 v[88:91], v[164:167], v[196:199], v[88:91]
	v_mfma_f32_16x16x32_bf16 v[88:91], v[168:171], v[214:217], v[88:91]
	v_mfma_f32_16x16x32_bf16 v[84:87], v[176:179], v[214:217], v[84:87]
	v_mfma_f32_16x16x32_bf16 v[84:87], v[172:175], v[196:199], v[84:87]
	v_mfma_f32_16x16x32_bf16 v[76:79], v[172:175], v[218:221], v[76:79]
	v_mfma_f32_16x16x32_bf16 v[76:79], v[176:179], v[222:225], v[76:79]
	v_mfma_f32_16x16x32_bf16 v[80:83], v[168:171], v[222:225], v[80:83]
	v_mfma_f32_16x16x32_bf16 v[80:83], v[164:167], v[218:221], v[80:83]

; #define PG8_STAGE(bufoff, gbase, voff) do { _Pragma("unroll") for (int _i = 0; _i < 2; ++_i) \
;         __builtin_amdgcn_global_load_lds((const unsigned*)((const char*)(gbase) + (voff)[_i]), (LAS unsigned*)(lds + (bufoff) + ldsw + _i * 8192), 16, 0, 0); } while (0)
; #define PG8_LDA(dst, b, h) do { _Pragma("unroll") for (int m = 0; m < 4; ++m) _Pragma("unroll") for (int k = 0; k < 2; ++k) dst[m][k] = *(const LAS bf16x8*)(lds + PG8_SA(b, h) + aoff + m * 2048 + k * 1024); } while (0)
; template <class Epi, bool ALIGN_EPI>
; __device__ __forceinline__ void gemm_phase(LAS unsigned char* lds, const Gemm g, const StaticOrder& S, const Epi& E, const int tid) {
;     ...
;             PG8_LDA(At, 1, 1); PG8_STAGE(PG8_SB(1, 0), b3, voffB); PG8_STAGE(PG8_SB(1, 1), b3 + hstepB, voffB); PG8_STAGE(PG8_SA(1, 0), a3, voffA);
	s_barrier
	s_add_u32 s42, s34, 0x8000
	s_addc_u32 s43, s35, 0
	s_add_i32 s87, s87, s56
	s_mov_b32 m0, s87
	ds_read_b128 v[180:183], v155 offset:49152
	ds_read_b128 v[184:187], v155 offset:50176
	ds_read_b128 v[188:191], v155 offset:51200
	ds_read_b128 v[192:195], v155 offset:52224


; #define PG8_STAGE(bufoff, gbase, voff) do { _Pragma("unroll") for (int _i = 0; _i < 2; ++_i) \
;         __builtin_amdgcn_global_load_lds((const unsigned*)((const char*)(gbase) + (voff)[_i]), (LAS unsigned*)(lds + (bufoff) + ldsw + _i * 8192), 16, 0, 0); } while (0)
; #define PG8_LDA(dst, b, h) do { _Pragma("unroll") for (int m = 0; m < 4; ++m) _Pragma("unroll") for (int k = 0; k < 2; ++k) dst[m][k] = *(const LAS bf16x8*)(lds + PG8_SA(b, h) + aoff + m * 2048 + k * 1024); } while (0)
; #define PG8_MMA(ai, bj, At, Bt) do { __builtin_amdgcn_s_setprio(1); _Pragma("unroll") for (int m = 0; m < 4; ++m) _Pragma("unroll") for (int n = 0; n < 2; ++n) _Pragma("unroll") for (int k = 0; k < 2; ++k) \
;         acc[ai][bj][m][n] = __builtin_amdgcn_mfma_f32_16x16x32_bf16(Bt[n][k], At[m][k], acc[ai][bj][m][n], 0, 0, 0); __builtin_amdgcn_s_setprio(0); } while (0)
; #define PG8_WAIT_V(n) asm volatile("s_waitcnt vmcnt(" #n ")" ::: "memory")
; #define PG8_WAIT_L(n) asm volatile("s_waitcnt lgkmcnt(" #n ")" ::: "memory")
; #define PG8_BAR __builtin_amdgcn_s_barrier()
; #define PG8_SCHED __builtin_amdgcn_sched_barrier(0)
; template <class Epi, bool ALIGN_EPI>
; __device__ __forceinline__ void gemm_phase(LAS unsigned char* lds, const Gemm g, const StaticOrder& S, const Epi& E, const int tid) {
;     ...
;             PG8_LDA(At, 1, 1); PG8_STAGE(PG8_SB(1, 0), b3, voffB); PG8_STAGE(PG8_SB(1, 1), b3 + hstepB, voffB); PG8_STAGE(PG8_SA(1, 0), a3, voffA);
;             PG8_WAIT_V(8); PG8_WAIT_L(0); PG8_BAR; PG8_MMA(1, 0, At, B0); PG8_MMA(1, 1, At, B1); PG8_BAR; PG8_SCHED;
	global_load_lds_dwordx4 v140, s[42:43]
	s_add_i32 m0, s87, 0x2000
	s_add_u32 s34, s34, 0xc000
	s_addc_u32 s35, s35, 0
	global_load_lds_dwordx4 v136, s[42:43]
	s_add_i32 s42, s88, s56
	s_mov_b32 m0, s42
	ds_read_b128 v[222:225], v155 offset:56320
	global_load_lds_dwordx4 v140, s[34:35]
	s_add_i32 m0, s42, 0x2000
	ds_read_b128 v[218:221], v155 offset:55296
	global_load_lds_dwordx4 v136, s[34:35]
	s_mov_b32 m0, s76
	ds_read_b128 v[214:217], v155 offset:54272
	global_load_lds_dwordx4 v142, s[22:23]
	s_mov_b32 m0, s77
	ds_read_b128 v[196:199], v155 offset:53248
	global_load_lds_dwordx4 v138, s[22:23]
	s_waitcnt vmcnt(8)
	s_waitcnt lgkmcnt(0)
	s_barrier


; #define PG8_MMA(ai, bj, At, Bt) do { __builtin_amdgcn_s_setprio(1); _Pragma("unroll") for (int m = 0; m < 4; ++m) _Pragma("unroll") for (int n = 0; n < 2; ++n) _Pragma("unroll") for (int k = 0; k < 2; ++k) \
;         acc[ai][bj][m][n] = __builtin_amdgcn_mfma_f32_16x16x32_bf16(Bt[n][k], At[m][k], acc[ai][bj][m][n], 0, 0, 0); __builtin_amdgcn_s_setprio(0); } while (0)
; #define PG8_WAIT_V(n) asm volatile("s_waitcnt vmcnt(" #n ")" ::: "memory")
; #define PG8_WAIT_L(n) asm volatile("s_waitcnt lgkmcnt(" #n ")" ::: "memory")
; #define PG8_BAR __builtin_amdgcn_s_barrier()
; #define PG8_SCHED __builtin_amdgcn_sched_barrier(0)
; template <class Epi, bool ALIGN_EPI>
; __device__ __forceinline__ void gemm_phase(LAS unsigned char* lds, const Gemm g, const StaticOrder& S, const Epi& E, const int tid) {
;     ...
;             PG8_WAIT_V(8); PG8_WAIT_L(0); PG8_BAR; PG8_MMA(1, 0, At, B0); PG8_MMA(1, 1, At, B1); PG8_BAR; PG8_SCHED;
	v_mfma_f32_16x16x32_bf16 v[24:27], v[132:135], v[180:183], v[24:27]
	v_mfma_f32_16x16x32_bf16 v[24:27], v[148:151], v[184:187], v[24:27]
	v_mfma_f32_16x16x32_bf16 v[20:23], v[160:163], v[184:187], v[20:23]
	v_mfma_f32_16x16x32_bf16 v[20:23], v[156:159], v[180:183], v[20:23]
	v_mfma_f32_16x16x32_bf16 v[72:75], v[156:159], v[188:191], v[72:75]
	v_mfma_f32_16x16x32_bf16 v[72:75], v[160:163], v[192:195], v[72:75]
	v_mfma_f32_16x16x32_bf16 v[64:67], v[148:151], v[192:195], v[64:67]
	v_mfma_f32_16x16x32_bf16 v[64:67], v[132:135], v[188:191], v[64:67]
	v_mfma_f32_16x16x32_bf16 v[16:19], v[132:135], v[196:199], v[16:19]
	v_mfma_f32_16x16x32_bf16 v[16:19], v[148:151], v[214:217], v[16:19]
	v_mfma_f32_16x16x32_bf16 v[12:15], v[160:163], v[214:217], v[12:15]
	v_mfma_f32_16x16x32_bf16 v[12:15], v[156:159], v[196:199], v[12:15]
	v_mfma_f32_16x16x32_bf16 v[68:71], v[156:159], v[218:221], v[68:71]
	v_mfma_f32_16x16x32_bf16 v[68:71], v[160:163], v[222:225], v[68:71]
	v_mfma_f32_16x16x32_bf16 v[60:63], v[148:151], v[222:225], v[60:63]
	v_mfma_f32_16x16x32_bf16 v[60:63], v[132:135], v[218:221], v[60:63]


; #define PG8_MMA(ai, bj, At, Bt) do { __builtin_amdgcn_s_setprio(1); _Pragma("unroll") for (int m = 0; m < 4; ++m) _Pragma("unroll") for (int n = 0; n < 2; ++n) _Pragma("unroll") for (int k = 0; k < 2; ++k) \
;         acc[ai][bj][m][n] = __builtin_amdgcn_mfma_f32_16x16x32_bf16(Bt[n][k], At[m][k], acc[ai][bj][m][n], 0, 0, 0); __builtin_amdgcn_s_setprio(0); } while (0)
; #define PG8_WAIT_V(n) asm volatile("s_waitcnt vmcnt(" #n ")" ::: "memory")
; #define PG8_WAIT_L(n) asm volatile("s_waitcnt lgkmcnt(" #n ")" ::: "memory")
; #define PG8_BAR __builtin_amdgcn_s_barrier()
; #define PG8_SCHED __builtin_amdgcn_sched_barrier(0)
; template <class Epi, bool ALIGN_EPI>
; __device__ __forceinline__ void gemm_phase(LAS unsigned char* lds, const Gemm g, const StaticOrder& S, const Epi& E, const int tid) {
;     ...
;             PG8_WAIT_V(8); PG8_WAIT_L(0); PG8_BAR; PG8_MMA(1, 0, At, B0); PG8_MMA(1, 1, At, B1); PG8_BAR; PG8_SCHED;
	v_mfma_f32_16x16x32_bf16 v[128:131], v[164:167], v[180:183], v[128:131]
	v_mfma_f32_16x16x32_bf16 v[128:131], v[168:171], v[184:187], v[128:131]
	v_mfma_f32_16x16x32_bf16 v[124:127], v[176:179], v[184:187], v[124:127]
	v_mfma_f32_16x16x32_bf16 v[124:127], v[172:175], v[180:183], v[124:127]
	v_mfma_f32_16x16x32_bf16 v[116:119], v[172:175], v[188:191], v[116:119]
	v_mfma_f32_16x16x32_bf16 v[116:119], v[176:179], v[192:195], v[116:119]
	v_mfma_f32_16x16x32_bf16 v[120:123], v[168:171], v[192:195], v[120:123]
	v_mfma_f32_16x16x32_bf16 v[120:123], v[164:167], v[188:191], v[120:123]
	v_mfma_f32_16x16x32_bf16 v[112:115], v[164:167], v[196:199], v[112:115]
	v_mfma_f32_16x16x32_bf16 v[112:115], v[168:171], v[214:217], v[112:115]
	v_mfma_f32_16x16x32_bf16 v[108:111], v[176:179], v[214:217], v[108:111]
	v_mfma_f32_16x16x32_bf16 v[108:111], v[172:175], v[196:199], v[108:111]
	v_mfma_f32_16x16x32_bf16 v[100:103], v[172:175], v[218:221], v[100:103]
	v_mfma_f32_16x16x32_bf16 v[100:103], v[176:179], v[222:225], v[100:103]
	v_mfma_f32_16x16x32_bf16 v[104:107], v[168:171], v[222:225], v[104:107]
	v_mfma_f32_16x16x32_bf16 v[104:107], v[164:167], v[218:221], v[104:107]

; #define LAS __attribute__((address_space(3)))
; #define PG8_MMA(ai, bj, At, Bt) do { __builtin_amdgcn_s_setprio(1); _Pragma("unroll") for (int m = 0; m < 4; ++m) _Pragma("unroll") for (int n = 0; n < 2; ++n) _Pragma("unroll") for (int k = 0; k < 2; ++k) \
;         acc[ai][bj][m][n] = __builtin_amdgcn_mfma_f32_16x16x32_bf16(Bt[n][k], At[m][k], acc[ai][bj][m][n], 0, 0, 0); __builtin_amdgcn_s_setprio(0); } while (0)
; #define PG8_WAIT_V(n) asm volatile("s_waitcnt vmcnt(" #n ")" ::: "memory")
; #define PG8_WAIT_L(n) asm volatile("s_waitcnt lgkmcnt(" #n ")" ::: "memory")
; #define PG8_BAR __builtin_amdgcn_s_barrier()
; #define PG8_SCHED __builtin_amdgcn_sched_barrier(0)
; __device__ __forceinline__ u32x4 zero_frag() { unsigned z_ = 0u; asm volatile("" : "+v"(z_)); return (u32x4){z_, z_, z_, z_}; }
; __device__ __forceinline__ void epi_lane(int& fr, int& fq) { unsigned ones = ~0u; asm volatile("" : "+s"(ones)); const int ln = (int)__builtin_amdgcn_mbcnt_hi(ones, __builtin_amdgcn_mbcnt_lo(ones, 0u)); fr = ln & 15; fq = ln >> 4; }
; template <class Epi, bool ALIGN_EPI>
; __device__ __forceinline__ void gemm_phase(LAS unsigned char* lds, const Gemm g, const StaticOrder& S, const Epi& E, const int tid) {
;     ...
;             PG8_WAIT_V(8); PG8_WAIT_L(0); PG8_BAR; PG8_MMA(1, 0, At, B0); PG8_MMA(1, 1, At, B1); PG8_BAR; PG8_SCHED;
;         }
;         if constexpr (ALIGN_EPI) { if (wr == 0) PG8_BAR; }
;         E(acc, cur, wr, wc, lds, rs_pm);
;     __device__ __forceinline__ void operator()(f32x4 (&acc)[2][2][4][2], const Unit& u, int wr, int wc, LAS unsigned char* lds, int& rs_pm) const {
;         int fr, fq; epi_lane(fr, fq);
;         const int row0 = u.pm * BM + wr * 64 + fr, col0 = u.pn * BM + wc * 32 + 8 * fq; u32x4 zb = zero_frag();
; #pragma unroll
;         for (int ai = 0; ai < 2; ++ai)
; #pragma unroll
;             for (int m = 0; m < 4; ++m) { float ss = 0.f;
;                 bf16* const xrow = xb + (((size_t)(u.pm * 32 + u.pn * 4 + (wc >> 1)) * BM + (wr * 64 + fr + ai * HALF + m * 16)) * 64 + (wc & 1) * 32 + 8 * fq);
; #pragma unroll
;                 for (int bj = 0; bj < 2; ++bj) {
;                     const u32x4 xw = *(const u32x4*)(xrow + (size_t)bj * (2 * BM * 64));
	s_barrier
	s_add_i32 s86, s86, 2
	s_add_u32 s84, s84, 0x10000
	s_addc_u32 s85, s85, 0
	s_add_u32 s10, s10, 0x10000
	s_addc_u32 s11, s11, 0
	s_cmpk_gt_u32 s86, 0x55
	s_cbranch_scc0 .LBB0_294
	v_and_b32_e32 v222, 15, v238
	v_lshrrev_b32_e32 v156, 4, v238
	s_lshl_b32 s100, s82, 5
	s_lshl_b32 s101, s83, 2
	v_lshlrev_b32_e32 v222, 7, v222
	s_add_i32 s100, s100, s101
	s_or_b32 s100, s100, s78
	v_lshl_or_b32 v222, v156, 4, v222
	s_ashr_i32 s101, s100, 31
	s_lshl_b64 s[100:101], s[100:101], 15
	s_add_u32 s98, s72, s100
	s_addc_u32 s99, s73, s101
	s_add_u32 s98, s98, s30
	s_addc_u32 s99, s99, s31
	s_lshl_b32 s100, s75, 7
	s_add_u32 s98, s98, s100
	s_addc_u32 s99, s99, 0
	s_lshl_b32 s100, s82, 15
	s_lshl_b32 s101, s75, 7
	s_add_i32 s100, s100, s101
	s_lshl_b32 s101, s83, 4
	s_add_i32 s100, s100, s101
	s_lshl_b32 s101, s74, 2
	s_add_i32 s100, s100, s101
	s_add_u32 s22, s44, s100
	s_addc_u32 s23, s45, 0
	global_load_dwordx4 v[176:179], v222, s[98:99]
	s_add_u32 s100, s98, 0x10000
	s_addc_u32 s101, s99, 0
	global_load_dwordx4 v[180:183], v222, s[100:101]
	global_load_dwordx4 v[184:187], v222, s[98:99] offset:2048
	s_add_u32 s100, s98, 0x10000
	s_addc_u32 s101, s99, 0
	global_load_dwordx4 v[188:191], v222, s[100:101] offset:2048
	s_add_u32 s100, s98, 0x1000
	s_addc_u32 s101, s99, 0
	global_load_dwordx4 v[192:195], v222, s[100:101]
	s_add_u32 s100, s98, 0x11000
	s_addc_u32 s101, s99, 0
	global_load_dwordx4 v[196:199], v222, s[100:101]
	s_add_u32 s100, s98, 0x1000
	s_addc_u32 s101, s99, 0
	global_load_dwordx4 v[214:217], v222, s[100:101] offset:2048
	s_add_u32 s100, s98, 0x11000
	s_addc_u32 s101, s99, 0
	global_load_dwordx4 v[218:221], v222, s[100:101] offset:2048
	s_and_b64 vcc, exec, s[46:47]
	s_cbranch_vccz .LBB0_297
	s_barrier

; #define PG8_STAGE(bufoff, gbase, voff) do { _Pragma("unroll") for (int _i = 0; _i < 2; ++_i) \
;         __builtin_amdgcn_global_load_lds((const unsigned*)((const char*)(gbase) + (voff)[_i]), (LAS unsigned*)(lds + (bufoff) + ldsw + _i * 8192), 16, 0, 0); } while (0)
; #define PG8_LDA(dst, b, h) do { _Pragma("unroll") for (int m = 0; m < 4; ++m) _Pragma("unroll") for (int k = 0; k < 2; ++k) dst[m][k] = *(const LAS bf16x8*)(lds + PG8_SA(b, h) + aoff + m * 2048 + k * 1024); } while (0)
; #define PG8_LDB(dst, b, h) do { _Pragma("unroll") for (int n = 0; n < 2; ++n) _Pragma("unroll") for (int k = 0; k < 2; ++k) dst[n][k] = *(const LAS bf16x8*)(lds + PG8_SB(b, h) + boff + n * 2048 + k * 1024); } while (0)
; #define PG8_SCHED __builtin_amdgcn_sched_barrier(0)
; template <class Epi, bool ALIGN_EPI>
; __device__ __forceinline__ void gemm_phase(LAS unsigned char* lds, const Gemm g, const StaticOrder& S, const Epi& E, const int tid) {
;     ...
;         const char* nA = has_next ? (const char*)g.A + (size_t)nxt.pm * tstepA + (size_t)nxt.pn * g.acs : cA; const char* nB = has_next ? (const char*)g.Bt + (size_t)nxt.pn * tstepB : cB;
;         for (int t = 0; t < nt; t += 2) {
;             const bool last = (t == nt - 2);
;             const char* a1 = cA + (size_t)(t + 1) * kstepA;
;             const char* a2 = last ? nA : cA + (size_t)(t + 2) * kstepA; const char* b2 = last ? nB : cB + (size_t)(t + 2) * kstepB;
;             const char* a3 = a2 + kstepA; const char* b3 = b2 + kstepB;
;             PG8_LDB(B0, 0, 0); PG8_LDB(B1, 0, 1); PG8_SCHED; PG8_LDA(At, 0, 0); PG8_STAGE(PG8_SA(1, 1), a1 + hstepA, voffA);
.LBB0_385:
	s_add_u32 s50, s48, 0x4000
	s_addc_u32 s51, s49, 0
	s_cmp_eq_u32 s88, 28
	s_cselect_b32 s54, s84, s50
	s_cselect_b32 s55, s43, s51
	s_cselect_b32 s52, s85, s86
	s_cselect_b32 s53, s41, s87
	s_add_u32 s50, s54, 0x8000
	s_addc_u32 s51, s55, 0
	s_add_i32 s89, 0, 0x10000
	v_add_u32_e32 v0, s89, v167
	s_add_i32 s92, 0, 0x14000
	ds_read_b128 v[132:135], v0
	ds_read_b128 v[136:139], v0 offset:1024
	ds_read_b128 v[152:155], v0 offset:2048
	ds_read_b128 v[156:159], v0 offset:3072
	v_add_u32_e32 v0, s92, v167
	ds_read_b128 v[160:163], v0
	ds_read_b128 v[172:175], v0 offset:1024
	ds_read_b128 v[176:179], v0 offset:2048
	ds_read_b128 v[180:183], v0 offset:3072
	s_add_i32 m0, s71, 0xc000
	ds_read_b128 v[184:187], v171
	ds_read_b128 v[188:191], v171 offset:1024
	ds_read_b128 v[192:195], v171 offset:2048
	ds_read_b128 v[196:199], v171 offset:3072
	ds_read_b128 v[214:217], v171 offset:4096
	ds_read_b128 v[218:221], v171 offset:5120
	ds_read_b128 v[222:225], v171 offset:6144

; #define PG8_STAGE(bufoff, gbase, voff) do { _Pragma("unroll") for (int _i = 0; _i < 2; ++_i) \
;         __builtin_amdgcn_global_load_lds((const unsigned*)((const char*)(gbase) + (voff)[_i]), (LAS unsigned*)(lds + (bufoff) + ldsw + _i * 8192), 16, 0, 0); } while (0)
; #define PG8_LDA(dst, b, h) do { _Pragma("unroll") for (int m = 0; m < 4; ++m) _Pragma("unroll") for (int k = 0; k < 2; ++k) dst[m][k] = *(const LAS bf16x8*)(lds + PG8_SA(b, h) + aoff + m * 2048 + k * 1024); } while (0)
; #define PG8_LDB(dst, b, h) do { _Pragma("unroll") for (int n = 0; n < 2; ++n) _Pragma("unroll") for (int k = 0; k < 2; ++k) dst[n][k] = *(const LAS bf16x8*)(lds + PG8_SB(b, h) + boff + n * 2048 + k * 1024); } while (0)
; #define PG8_MMA(ai, bj, At, Bt) do { __builtin_amdgcn_s_setprio(1); _Pragma("unroll") for (int m = 0; m < 4; ++m) _Pragma("unroll") for (int n = 0; n < 2; ++n) _Pragma("unroll") for (int k = 0; k < 2; ++k) \
;         acc[ai][bj][m][n] = __builtin_amdgcn_mfma_f32_16x16x32_bf16(Bt[n][k], At[m][k], acc[ai][bj][m][n], 0, 0, 0); __builtin_amdgcn_s_setprio(0); } while (0)
; #define PG8_WAIT_V(n) asm volatile("s_waitcnt vmcnt(" #n ")" ::: "memory")
; #define PG8_WAIT_L(n) asm volatile("s_waitcnt lgkmcnt(" #n ")" ::: "memory")
; #define PG8_BAR __builtin_amdgcn_s_barrier()
; #define PG8_SCHED __builtin_amdgcn_sched_barrier(0)
; template <class Epi, bool ALIGN_EPI>
; __device__ __forceinline__ void gemm_phase(LAS unsigned char* lds, const Gemm g, const StaticOrder& S, const Epi& E, const int tid) {
;     ...
;             PG8_LDB(B0, 0, 0); PG8_LDB(B1, 0, 1); PG8_SCHED; PG8_LDA(At, 0, 0); PG8_STAGE(PG8_SA(1, 1), a1 + hstepA, voffA);
;             PG8_WAIT_V(8); PG8_WAIT_L(0); PG8_BAR; PG8_MMA(0, 0, At, B0); PG8_MMA(0, 1, At, B1); PG8_BAR; PG8_SCHED;
	global_load_lds_dwordx4 v148, s[48:49]
	s_add_i32 m0, s71, 0xe000
	ds_read_b128 v[226:229], v171 offset:7168
	global_load_lds_dwordx4 v150, s[48:49]
	s_waitcnt vmcnt(8)
	s_waitcnt lgkmcnt(0)
	s_barrier


; #define PG8_MMA(ai, bj, At, Bt) do { __builtin_amdgcn_s_setprio(1); _Pragma("unroll") for (int m = 0; m < 4; ++m) _Pragma("unroll") for (int n = 0; n < 2; ++n) _Pragma("unroll") for (int k = 0; k < 2; ++k) \
;         acc[ai][bj][m][n] = __builtin_amdgcn_mfma_f32_16x16x32_bf16(Bt[n][k], At[m][k], acc[ai][bj][m][n], 0, 0, 0); __builtin_amdgcn_s_setprio(0); } while (0)
; #define PG8_WAIT_V(n) asm volatile("s_waitcnt vmcnt(" #n ")" ::: "memory")
; #define PG8_WAIT_L(n) asm volatile("s_waitcnt lgkmcnt(" #n ")" ::: "memory")
; #define PG8_BAR __builtin_amdgcn_s_barrier()
; #define PG8_SCHED __builtin_amdgcn_sched_barrier(0)
; template <class Epi, bool ALIGN_EPI>
; __device__ __forceinline__ void gemm_phase(LAS unsigned char* lds, const Gemm g, const StaticOrder& S, const Epi& E, const int tid) {
;     ...
;             PG8_WAIT_V(8); PG8_WAIT_L(0); PG8_BAR; PG8_MMA(0, 0, At, B0); PG8_MMA(0, 1, At, B1); PG8_BAR; PG8_SCHED;
	v_mfma_f32_16x16x32_bf16 v[128:131], v[132:135], v[184:187], v[128:131]
	v_mfma_f32_16x16x32_bf16 v[128:131], v[136:139], v[188:191], v[128:131]
	v_mfma_f32_16x16x32_bf16 v[116:119], v[156:159], v[188:191], v[116:119]
	v_mfma_f32_16x16x32_bf16 v[116:119], v[152:155], v[184:187], v[116:119]
	v_mfma_f32_16x16x32_bf16 v[108:111], v[152:155], v[192:195], v[108:111]
	v_mfma_f32_16x16x32_bf16 v[108:111], v[156:159], v[196:199], v[108:111]
	v_mfma_f32_16x16x32_bf16 v[124:127], v[136:139], v[196:199], v[124:127]
	v_mfma_f32_16x16x32_bf16 v[124:127], v[132:135], v[192:195], v[124:127]
	v_mfma_f32_16x16x32_bf16 v[120:123], v[132:135], v[214:217], v[120:123]
	v_mfma_f32_16x16x32_bf16 v[120:123], v[136:139], v[218:221], v[120:123]
	v_mfma_f32_16x16x32_bf16 v[100:103], v[156:159], v[218:221], v[100:103]
	v_mfma_f32_16x16x32_bf16 v[100:103], v[152:155], v[214:217], v[100:103]
	v_mfma_f32_16x16x32_bf16 v[92:95], v[152:155], v[222:225], v[92:95]
	v_mfma_f32_16x16x32_bf16 v[92:95], v[156:159], v[226:229], v[92:95]
	v_mfma_f32_16x16x32_bf16 v[112:115], v[136:139], v[226:229], v[112:115]
	v_mfma_f32_16x16x32_bf16 v[112:115], v[132:135], v[222:225], v[112:115]


; #define PG8_MMA(ai, bj, At, Bt) do { __builtin_amdgcn_s_setprio(1); _Pragma("unroll") for (int m = 0; m < 4; ++m) _Pragma("unroll") for (int n = 0; n < 2; ++n) _Pragma("unroll") for (int k = 0; k < 2; ++k) \
;         acc[ai][bj][m][n] = __builtin_amdgcn_mfma_f32_16x16x32_bf16(Bt[n][k], At[m][k], acc[ai][bj][m][n], 0, 0, 0); __builtin_amdgcn_s_setprio(0); } while (0)
; #define PG8_WAIT_V(n) asm volatile("s_waitcnt vmcnt(" #n ")" ::: "memory")
; #define PG8_WAIT_L(n) asm volatile("s_waitcnt lgkmcnt(" #n ")" ::: "memory")
; #define PG8_BAR __builtin_amdgcn_s_barrier()
; #define PG8_SCHED __builtin_amdgcn_sched_barrier(0)
; template <class Epi, bool ALIGN_EPI>
; __device__ __forceinline__ void gemm_phase(LAS unsigned char* lds, const Gemm g, const StaticOrder& S, const Epi& E, const int tid) {
;     ...
;             PG8_WAIT_V(8); PG8_WAIT_L(0); PG8_BAR; PG8_MMA(0, 0, At, B0); PG8_MMA(0, 1, At, B1); PG8_BAR; PG8_SCHED;
	v_mfma_f32_16x16x32_bf16 v[104:107], v[160:163], v[184:187], v[104:107]
	v_mfma_f32_16x16x32_bf16 v[104:107], v[172:175], v[188:191], v[104:107]
	v_mfma_f32_16x16x32_bf16 v[80:83], v[180:183], v[188:191], v[80:83]
	v_mfma_f32_16x16x32_bf16 v[80:83], v[176:179], v[184:187], v[80:83]
	v_mfma_f32_16x16x32_bf16 v[68:71], v[176:179], v[192:195], v[68:71]
	v_mfma_f32_16x16x32_bf16 v[68:71], v[180:183], v[196:199], v[68:71]
	v_mfma_f32_16x16x32_bf16 v[96:99], v[172:175], v[196:199], v[96:99]
	v_mfma_f32_16x16x32_bf16 v[96:99], v[160:163], v[192:195], v[96:99]
	v_mfma_f32_16x16x32_bf16 v[88:91], v[160:163], v[214:217], v[88:91]
	v_mfma_f32_16x16x32_bf16 v[88:91], v[172:175], v[218:221], v[88:91]
	v_mfma_f32_16x16x32_bf16 v[60:63], v[180:183], v[218:221], v[60:63]
	v_mfma_f32_16x16x32_bf16 v[60:63], v[176:179], v[214:217], v[60:63]
	v_mfma_f32_16x16x32_bf16 v[48:51], v[176:179], v[222:225], v[48:51]
	v_mfma_f32_16x16x32_bf16 v[48:51], v[180:183], v[226:229], v[48:51]
	v_mfma_f32_16x16x32_bf16 v[76:79], v[172:175], v[226:229], v[76:79]
	v_mfma_f32_16x16x32_bf16 v[76:79], v[160:163], v[222:225], v[76:79]

; #define PG8_STAGE(bufoff, gbase, voff) do { _Pragma("unroll") for (int _i = 0; _i < 2; ++_i) \
;         __builtin_amdgcn_global_load_lds((const unsigned*)((const char*)(gbase) + (voff)[_i]), (LAS unsigned*)(lds + (bufoff) + ldsw + _i * 8192), 16, 0, 0); } while (0)
; #define PG8_LDA(dst, b, h) do { _Pragma("unroll") for (int m = 0; m < 4; ++m) _Pragma("unroll") for (int k = 0; k < 2; ++k) dst[m][k] = *(const LAS bf16x8*)(lds + PG8_SA(b, h) + aoff + m * 2048 + k * 1024); } while (0)
; #define PG8_MMA(ai, bj, At, Bt) do { __builtin_amdgcn_s_setprio(1); _Pragma("unroll") for (int m = 0; m < 4; ++m) _Pragma("unroll") for (int n = 0; n < 2; ++n) _Pragma("unroll") for (int k = 0; k < 2; ++k) \
;         acc[ai][bj][m][n] = __builtin_amdgcn_mfma_f32_16x16x32_bf16(Bt[n][k], At[m][k], acc[ai][bj][m][n], 0, 0, 0); __builtin_amdgcn_s_setprio(0); } while (0)
; #define PG8_WAIT_V(n) asm volatile("s_waitcnt vmcnt(" #n ")" ::: "memory")
; #define PG8_WAIT_L(n) asm volatile("s_waitcnt lgkmcnt(" #n ")" ::: "memory")
; #define PG8_BAR __builtin_amdgcn_s_barrier()
; #define PG8_SCHED __builtin_amdgcn_sched_barrier(0)
; template <class Epi, bool ALIGN_EPI>
; __device__ __forceinline__ void gemm_phase(LAS unsigned char* lds, const Gemm g, const StaticOrder& S, const Epi& E, const int tid) {
;     ...
;             PG8_WAIT_V(8); PG8_WAIT_L(0); PG8_BAR; PG8_MMA(0, 0, At, B0); PG8_MMA(0, 1, At, B1); PG8_BAR; PG8_SCHED;
;             PG8_LDA(At, 0, 1); PG8_STAGE(PG8_SB(0, 0), b2, voffB); PG8_STAGE(PG8_SB(0, 1), b2 + hstepB, voffB); PG8_STAGE(PG8_SA(0, 0), a2, voffA);
	s_barrier
	s_add_i32 s89, s89, s61
	s_mov_b32 m0, s89
	ds_read_b128 v[184:187], v171 offset:16384
	ds_read_b128 v[188:191], v171 offset:17408
	ds_read_b128 v[192:195], v171 offset:18432
	ds_read_b128 v[196:199], v171 offset:19456


; #define PG8_STAGE(bufoff, gbase, voff) do { _Pragma("unroll") for (int _i = 0; _i < 2; ++_i) \
;         __builtin_amdgcn_global_load_lds((const unsigned*)((const char*)(gbase) + (voff)[_i]), (LAS unsigned*)(lds + (bufoff) + ldsw + _i * 8192), 16, 0, 0); } while (0)
; #define PG8_LDA(dst, b, h) do { _Pragma("unroll") for (int m = 0; m < 4; ++m) _Pragma("unroll") for (int k = 0; k < 2; ++k) dst[m][k] = *(const LAS bf16x8*)(lds + PG8_SA(b, h) + aoff + m * 2048 + k * 1024); } while (0)
; #define PG8_MMA(ai, bj, At, Bt) do { __builtin_amdgcn_s_setprio(1); _Pragma("unroll") for (int m = 0; m < 4; ++m) _Pragma("unroll") for (int n = 0; n < 2; ++n) _Pragma("unroll") for (int k = 0; k < 2; ++k) \
;         acc[ai][bj][m][n] = __builtin_amdgcn_mfma_f32_16x16x32_bf16(Bt[n][k], At[m][k], acc[ai][bj][m][n], 0, 0, 0); __builtin_amdgcn_s_setprio(0); } while (0)
; #define PG8_WAIT_V(n) asm volatile("s_waitcnt vmcnt(" #n ")" ::: "memory")
; #define PG8_WAIT_L(n) asm volatile("s_waitcnt lgkmcnt(" #n ")" ::: "memory")
; #define PG8_BAR __builtin_amdgcn_s_barrier()
; #define PG8_SCHED __builtin_amdgcn_sched_barrier(0)
; template <class Epi, bool ALIGN_EPI>
; __device__ __forceinline__ void gemm_phase(LAS unsigned char* lds, const Gemm g, const StaticOrder& S, const Epi& E, const int tid) {
;     ...
;             PG8_LDA(At, 0, 1); PG8_STAGE(PG8_SB(0, 0), b2, voffB); PG8_STAGE(PG8_SB(0, 1), b2 + hstepB, voffB); PG8_STAGE(PG8_SA(0, 0), a2, voffA);
;             PG8_WAIT_V(8); PG8_WAIT_L(0); PG8_BAR; PG8_MMA(1, 0, At, B0); PG8_MMA(1, 1, At, B1); PG8_BAR; PG8_SCHED;
	global_load_lds_dwordx4 v144, s[52:53]
	s_add_i32 m0, s89, 0x2000
	s_add_u32 s90, s52, 0x4000
	s_addc_u32 s91, s53, 0
	s_add_i32 s89, s92, s61
	global_load_lds_dwordx4 v140, s[52:53]
	s_mov_b32 m0, s89
	ds_read_b128 v[226:229], v171 offset:23552
	global_load_lds_dwordx4 v144, s[90:91]
	s_add_i32 m0, s89, 0x2000
	ds_read_b128 v[222:225], v171 offset:22528
	global_load_lds_dwordx4 v140, s[90:91]
	s_mov_b32 m0, s71
	ds_read_b128 v[218:221], v171 offset:21504
	global_load_lds_dwordx4 v146, s[54:55]
	s_mov_b32 m0, s72
	ds_read_b128 v[214:217], v171 offset:20480
	global_load_lds_dwordx4 v142, s[54:55]
	s_waitcnt vmcnt(8)
	s_waitcnt lgkmcnt(0)
	s_barrier


; #define PG8_MMA(ai, bj, At, Bt) do { __builtin_amdgcn_s_setprio(1); _Pragma("unroll") for (int m = 0; m < 4; ++m) _Pragma("unroll") for (int n = 0; n < 2; ++n) _Pragma("unroll") for (int k = 0; k < 2; ++k) \
;         acc[ai][bj][m][n] = __builtin_amdgcn_mfma_f32_16x16x32_bf16(Bt[n][k], At[m][k], acc[ai][bj][m][n], 0, 0, 0); __builtin_amdgcn_s_setprio(0); } while (0)
; #define PG8_WAIT_V(n) asm volatile("s_waitcnt vmcnt(" #n ")" ::: "memory")
; #define PG8_WAIT_L(n) asm volatile("s_waitcnt lgkmcnt(" #n ")" ::: "memory")
; #define PG8_BAR __builtin_amdgcn_s_barrier()
; #define PG8_SCHED __builtin_amdgcn_sched_barrier(0)
; template <class Epi, bool ALIGN_EPI>
; __device__ __forceinline__ void gemm_phase(LAS unsigned char* lds, const Gemm g, const StaticOrder& S, const Epi& E, const int tid) {
;     ...
;             PG8_WAIT_V(8); PG8_WAIT_L(0); PG8_BAR; PG8_MMA(1, 0, At, B0); PG8_MMA(1, 1, At, B1); PG8_BAR; PG8_SCHED;
	v_mfma_f32_16x16x32_bf16 v[84:87], v[132:135], v[184:187], v[84:87]
	v_mfma_f32_16x16x32_bf16 v[84:87], v[136:139], v[188:191], v[84:87]
	v_mfma_f32_16x16x32_bf16 v[56:59], v[156:159], v[188:191], v[56:59]
	v_mfma_f32_16x16x32_bf16 v[56:59], v[152:155], v[184:187], v[56:59]
	v_mfma_f32_16x16x32_bf16 v[44:47], v[152:155], v[192:195], v[44:47]
	v_mfma_f32_16x16x32_bf16 v[44:47], v[156:159], v[196:199], v[44:47]
	v_mfma_f32_16x16x32_bf16 v[72:75], v[136:139], v[196:199], v[72:75]
	v_mfma_f32_16x16x32_bf16 v[72:75], v[132:135], v[192:195], v[72:75]
	v_mfma_f32_16x16x32_bf16 v[64:67], v[132:135], v[214:217], v[64:67]
	v_mfma_f32_16x16x32_bf16 v[64:67], v[136:139], v[218:221], v[64:67]
	v_mfma_f32_16x16x32_bf16 v[36:39], v[156:159], v[218:221], v[36:39]
	v_mfma_f32_16x16x32_bf16 v[36:39], v[152:155], v[214:217], v[36:39]
	v_mfma_f32_16x16x32_bf16 v[28:31], v[152:155], v[222:225], v[28:31]
	v_mfma_f32_16x16x32_bf16 v[28:31], v[156:159], v[226:229], v[28:31]
	v_mfma_f32_16x16x32_bf16 v[52:55], v[136:139], v[226:229], v[52:55]
	v_mfma_f32_16x16x32_bf16 v[52:55], v[132:135], v[222:225], v[52:55]


; #define PG8_MMA(ai, bj, At, Bt) do { __builtin_amdgcn_s_setprio(1); _Pragma("unroll") for (int m = 0; m < 4; ++m) _Pragma("unroll") for (int n = 0; n < 2; ++n) _Pragma("unroll") for (int k = 0; k < 2; ++k) \
;         acc[ai][bj][m][n] = __builtin_amdgcn_mfma_f32_16x16x32_bf16(Bt[n][k], At[m][k], acc[ai][bj][m][n], 0, 0, 0); __builtin_amdgcn_s_setprio(0); } while (0)
; #define PG8_WAIT_V(n) asm volatile("s_waitcnt vmcnt(" #n ")" ::: "memory")
; #define PG8_WAIT_L(n) asm volatile("s_waitcnt lgkmcnt(" #n ")" ::: "memory")
; #define PG8_BAR __builtin_amdgcn_s_barrier()
; #define PG8_SCHED __builtin_amdgcn_sched_barrier(0)
; template <class Epi, bool ALIGN_EPI>
; __device__ __forceinline__ void gemm_phase(LAS unsigned char* lds, const Gemm g, const StaticOrder& S, const Epi& E, const int tid) {
;     ...
;             PG8_WAIT_V(8); PG8_WAIT_L(0); PG8_BAR; PG8_MMA(1, 0, At, B0); PG8_MMA(1, 1, At, B1); PG8_BAR; PG8_SCHED;
	v_mfma_f32_16x16x32_bf16 v[40:43], v[160:163], v[184:187], v[40:43]
	v_mfma_f32_16x16x32_bf16 v[40:43], v[172:175], v[188:191], v[40:43]
	v_mfma_f32_16x16x32_bf16 v[20:23], v[180:183], v[188:191], v[20:23]
	v_mfma_f32_16x16x32_bf16 v[20:23], v[176:179], v[184:187], v[20:23]
	v_mfma_f32_16x16x32_bf16 v[12:15], v[176:179], v[192:195], v[12:15]
	v_mfma_f32_16x16x32_bf16 v[12:15], v[180:183], v[196:199], v[12:15]
	v_mfma_f32_16x16x32_bf16 v[32:35], v[172:175], v[196:199], v[32:35]
	v_mfma_f32_16x16x32_bf16 v[32:35], v[160:163], v[192:195], v[32:35]
	v_mfma_f32_16x16x32_bf16 v[24:27], v[160:163], v[214:217], v[24:27]
	v_mfma_f32_16x16x32_bf16 v[24:27], v[172:175], v[218:221], v[24:27]
	v_mfma_f32_16x16x32_bf16 v[8:11], v[180:183], v[218:221], v[8:11]
	v_mfma_f32_16x16x32_bf16 v[8:11], v[176:179], v[214:217], v[8:11]
	v_mfma_f32_16x16x32_bf16 v[2:5], v[176:179], v[222:225], v[4:7]
	v_mfma_f32_16x16x32_bf16 v[2:5], v[180:183], v[226:229], v[2:5]
	v_mfma_f32_16x16x32_bf16 v[16:19], v[172:175], v[226:229], v[16:19]
	v_mfma_f32_16x16x32_bf16 v[16:19], v[160:163], v[222:225], v[16:19]

; #define PG8_STAGE(bufoff, gbase, voff) do { _Pragma("unroll") for (int _i = 0; _i < 2; ++_i) \
;         __builtin_amdgcn_global_load_lds((const unsigned*)((const char*)(gbase) + (voff)[_i]), (LAS unsigned*)(lds + (bufoff) + ldsw + _i * 8192), 16, 0, 0); } while (0)
; #define PG8_LDA(dst, b, h) do { _Pragma("unroll") for (int m = 0; m < 4; ++m) _Pragma("unroll") for (int k = 0; k < 2; ++k) dst[m][k] = *(const LAS bf16x8*)(lds + PG8_SA(b, h) + aoff + m * 2048 + k * 1024); } while (0)
; #define PG8_LDB(dst, b, h) do { _Pragma("unroll") for (int n = 0; n < 2; ++n) _Pragma("unroll") for (int k = 0; k < 2; ++k) dst[n][k] = *(const LAS bf16x8*)(lds + PG8_SB(b, h) + boff + n * 2048 + k * 1024); } while (0)
; #define PG8_SCHED __builtin_amdgcn_sched_barrier(0)
; template <class Epi, bool ALIGN_EPI>
; __device__ __forceinline__ void gemm_phase(LAS unsigned char* lds, const Gemm g, const StaticOrder& S, const Epi& E, const int tid) {
;     ...
;             PG8_LDB(B0, 1, 0); PG8_LDB(B1, 1, 1); PG8_SCHED; PG8_LDA(At, 1, 0); PG8_STAGE(PG8_SA(0, 1), a2 + hstepA, voffA);
	s_barrier
	s_add_i32 s89, 0, 0x18000
	v_add_u32_e32 v0, s89, v167
	s_add_i32 s90, 0, 0x1c000
	ds_read_b128 v[132:135], v0
	ds_read_b128 v[136:139], v0 offset:1024
	ds_read_b128 v[152:155], v0 offset:2048
	ds_read_b128 v[156:159], v0 offset:3072
	v_add_u32_e32 v0, s90, v167
	ds_read_b128 v[160:163], v0
	ds_read_b128 v[172:175], v0 offset:1024
	ds_read_b128 v[176:179], v0 offset:2048
	ds_read_b128 v[180:183], v0 offset:3072
	s_add_u32 s54, s54, 0x4000
	s_addc_u32 s55, s55, 0
	s_mov_b32 m0, s73
	ds_read_b128 v[184:187], v171 offset:32768
	ds_read_b128 v[188:191], v171 offset:33792
	ds_read_b128 v[192:195], v171 offset:34816
	ds_read_b128 v[196:199], v171 offset:35840
	ds_read_b128 v[214:217], v171 offset:36864
	ds_read_b128 v[218:221], v171 offset:37888
	ds_read_b128 v[222:225], v171 offset:38912

; #define PG8_STAGE(bufoff, gbase, voff) do { _Pragma("unroll") for (int _i = 0; _i < 2; ++_i) \
;         __builtin_amdgcn_global_load_lds((const unsigned*)((const char*)(gbase) + (voff)[_i]), (LAS unsigned*)(lds + (bufoff) + ldsw + _i * 8192), 16, 0, 0); } while (0)
; #define PG8_LDA(dst, b, h) do { _Pragma("unroll") for (int m = 0; m < 4; ++m) _Pragma("unroll") for (int k = 0; k < 2; ++k) dst[m][k] = *(const LAS bf16x8*)(lds + PG8_SA(b, h) + aoff + m * 2048 + k * 1024); } while (0)
; #define PG8_LDB(dst, b, h) do { _Pragma("unroll") for (int n = 0; n < 2; ++n) _Pragma("unroll") for (int k = 0; k < 2; ++k) dst[n][k] = *(const LAS bf16x8*)(lds + PG8_SB(b, h) + boff + n * 2048 + k * 1024); } while (0)
; #define PG8_MMA(ai, bj, At, Bt) do { __builtin_amdgcn_s_setprio(1); _Pragma("unroll") for (int m = 0; m < 4; ++m) _Pragma("unroll") for (int n = 0; n < 2; ++n) _Pragma("unroll") for (int k = 0; k < 2; ++k) \
;         acc[ai][bj][m][n] = __builtin_amdgcn_mfma_f32_16x16x32_bf16(Bt[n][k], At[m][k], acc[ai][bj][m][n], 0, 0, 0); __builtin_amdgcn_s_setprio(0); } while (0)
; #define PG8_WAIT_V(n) asm volatile("s_waitcnt vmcnt(" #n ")" ::: "memory")
; #define PG8_WAIT_L(n) asm volatile("s_waitcnt lgkmcnt(" #n ")" ::: "memory")
; #define PG8_BAR __builtin_amdgcn_s_barrier()
; #define PG8_SCHED __builtin_amdgcn_sched_barrier(0)
; template <class Epi, bool ALIGN_EPI>
; __device__ __forceinline__ void gemm_phase(LAS unsigned char* lds, const Gemm g, const StaticOrder& S, const Epi& E, const int tid) {
;     ...
;             PG8_LDB(B0, 1, 0); PG8_LDB(B1, 1, 1); PG8_SCHED; PG8_LDA(At, 1, 0); PG8_STAGE(PG8_SA(0, 1), a2 + hstepA, voffA);
;             PG8_WAIT_V(8); PG8_WAIT_L(0); PG8_BAR; PG8_MMA(0, 0, At, B0); PG8_MMA(0, 1, At, B1); PG8_BAR; PG8_SCHED;
	global_load_lds_dwordx4 v146, s[54:55]
	s_mov_b32 m0, s74
	ds_read_b128 v[226:229], v171 offset:39936
	global_load_lds_dwordx4 v142, s[54:55]
	s_waitcnt vmcnt(8)
	s_waitcnt lgkmcnt(0)
	s_barrier


; #define PG8_MMA(ai, bj, At, Bt) do { __builtin_amdgcn_s_setprio(1); _Pragma("unroll") for (int m = 0; m < 4; ++m) _Pragma("unroll") for (int n = 0; n < 2; ++n) _Pragma("unroll") for (int k = 0; k < 2; ++k) \
;         acc[ai][bj][m][n] = __builtin_amdgcn_mfma_f32_16x16x32_bf16(Bt[n][k], At[m][k], acc[ai][bj][m][n], 0, 0, 0); __builtin_amdgcn_s_setprio(0); } while (0)
; #define PG8_WAIT_V(n) asm volatile("s_waitcnt vmcnt(" #n ")" ::: "memory")
; #define PG8_WAIT_L(n) asm volatile("s_waitcnt lgkmcnt(" #n ")" ::: "memory")
; #define PG8_BAR __builtin_amdgcn_s_barrier()
; #define PG8_SCHED __builtin_amdgcn_sched_barrier(0)
; template <class Epi, bool ALIGN_EPI>
; __device__ __forceinline__ void gemm_phase(LAS unsigned char* lds, const Gemm g, const StaticOrder& S, const Epi& E, const int tid) {
;     ...
;             PG8_WAIT_V(8); PG8_WAIT_L(0); PG8_BAR; PG8_MMA(0, 0, At, B0); PG8_MMA(0, 1, At, B1); PG8_BAR; PG8_SCHED;
	v_mfma_f32_16x16x32_bf16 v[128:131], v[132:135], v[184:187], v[128:131]
	v_mfma_f32_16x16x32_bf16 v[128:131], v[136:139], v[188:191], v[128:131]
	v_mfma_f32_16x16x32_bf16 v[116:119], v[156:159], v[188:191], v[116:119]
	v_mfma_f32_16x16x32_bf16 v[116:119], v[152:155], v[184:187], v[116:119]
	v_mfma_f32_16x16x32_bf16 v[108:111], v[152:155], v[192:195], v[108:111]
	v_mfma_f32_16x16x32_bf16 v[108:111], v[156:159], v[196:199], v[108:111]
	v_mfma_f32_16x16x32_bf16 v[124:127], v[136:139], v[196:199], v[124:127]
	v_mfma_f32_16x16x32_bf16 v[124:127], v[132:135], v[192:195], v[124:127]
	v_mfma_f32_16x16x32_bf16 v[120:123], v[132:135], v[214:217], v[120:123]
	v_mfma_f32_16x16x32_bf16 v[120:123], v[136:139], v[218:221], v[120:123]
	v_mfma_f32_16x16x32_bf16 v[100:103], v[156:159], v[218:221], v[100:103]
	v_mfma_f32_16x16x32_bf16 v[100:103], v[152:155], v[214:217], v[100:103]
	v_mfma_f32_16x16x32_bf16 v[92:95], v[152:155], v[222:225], v[92:95]
	v_mfma_f32_16x16x32_bf16 v[92:95], v[156:159], v[226:229], v[92:95]
	v_mfma_f32_16x16x32_bf16 v[112:115], v[136:139], v[226:229], v[112:115]
	v_mfma_f32_16x16x32_bf16 v[112:115], v[132:135], v[222:225], v[112:115]


; #define PG8_MMA(ai, bj, At, Bt) do { __builtin_amdgcn_s_setprio(1); _Pragma("unroll") for (int m = 0; m < 4; ++m) _Pragma("unroll") for (int n = 0; n < 2; ++n) _Pragma("unroll") for (int k = 0; k < 2; ++k) \
;         acc[ai][bj][m][n] = __builtin_amdgcn_mfma_f32_16x16x32_bf16(Bt[n][k], At[m][k], acc[ai][bj][m][n], 0, 0, 0); __builtin_amdgcn_s_setprio(0); } while (0)
; #define PG8_WAIT_V(n) asm volatile("s_waitcnt vmcnt(" #n ")" ::: "memory")
; #define PG8_WAIT_L(n) asm volatile("s_waitcnt lgkmcnt(" #n ")" ::: "memory")
; #define PG8_BAR __builtin_amdgcn_s_barrier()
; #define PG8_SCHED __builtin_amdgcn_sched_barrier(0)
; template <class Epi, bool ALIGN_EPI>
; __device__ __forceinline__ void gemm_phase(LAS unsigned char* lds, const Gemm g, const StaticOrder& S, const Epi& E, const int tid) {
;     ...
;             PG8_WAIT_V(8); PG8_WAIT_L(0); PG8_BAR; PG8_MMA(0, 0, At, B0); PG8_MMA(0, 1, At, B1); PG8_BAR; PG8_SCHED;
	v_mfma_f32_16x16x32_bf16 v[104:107], v[160:163], v[184:187], v[104:107]
	v_mfma_f32_16x16x32_bf16 v[104:107], v[172:175], v[188:191], v[104:107]
	v_mfma_f32_16x16x32_bf16 v[80:83], v[180:183], v[188:191], v[80:83]
	v_mfma_f32_16x16x32_bf16 v[80:83], v[176:179], v[184:187], v[80:83]
	v_mfma_f32_16x16x32_bf16 v[68:71], v[176:179], v[192:195], v[68:71]
	v_mfma_f32_16x16x32_bf16 v[68:71], v[180:183], v[196:199], v[68:71]
	v_mfma_f32_16x16x32_bf16 v[96:99], v[172:175], v[196:199], v[96:99]
	v_mfma_f32_16x16x32_bf16 v[96:99], v[160:163], v[192:195], v[96:99]
	v_mfma_f32_16x16x32_bf16 v[88:91], v[160:163], v[214:217], v[88:91]
	v_mfma_f32_16x16x32_bf16 v[88:91], v[172:175], v[218:221], v[88:91]
	v_mfma_f32_16x16x32_bf16 v[60:63], v[180:183], v[218:221], v[60:63]
	v_mfma_f32_16x16x32_bf16 v[60:63], v[176:179], v[214:217], v[60:63]
	v_mfma_f32_16x16x32_bf16 v[48:51], v[176:179], v[222:225], v[48:51]
	v_mfma_f32_16x16x32_bf16 v[48:51], v[180:183], v[226:229], v[48:51]
	v_mfma_f32_16x16x32_bf16 v[76:79], v[172:175], v[226:229], v[76:79]
	v_mfma_f32_16x16x32_bf16 v[76:79], v[160:163], v[222:225], v[76:79]

; #define PG8_STAGE(bufoff, gbase, voff) do { _Pragma("unroll") for (int _i = 0; _i < 2; ++_i) \
;         __builtin_amdgcn_global_load_lds((const unsigned*)((const char*)(gbase) + (voff)[_i]), (LAS unsigned*)(lds + (bufoff) + ldsw + _i * 8192), 16, 0, 0); } while (0)
; #define PG8_LDA(dst, b, h) do { _Pragma("unroll") for (int m = 0; m < 4; ++m) _Pragma("unroll") for (int k = 0; k < 2; ++k) dst[m][k] = *(const LAS bf16x8*)(lds + PG8_SA(b, h) + aoff + m * 2048 + k * 1024); } while (0)
; template <class Epi, bool ALIGN_EPI>
; __device__ __forceinline__ void gemm_phase(LAS unsigned char* lds, const Gemm g, const StaticOrder& S, const Epi& E, const int tid) {
;     ...
;             PG8_LDA(At, 1, 1); PG8_STAGE(PG8_SB(1, 0), b3, voffB); PG8_STAGE(PG8_SB(1, 1), b3 + hstepB, voffB); PG8_STAGE(PG8_SA(1, 0), a3, voffA);
	s_barrier
	s_add_u32 s54, s52, 0x8000
	s_addc_u32 s55, s53, 0
	s_add_i32 s89, s89, s61
	s_mov_b32 m0, s89
	ds_read_b128 v[184:187], v171 offset:49152
	ds_read_b128 v[188:191], v171 offset:50176
	ds_read_b128 v[192:195], v171 offset:51200
	ds_read_b128 v[196:199], v171 offset:52224


; #define PG8_STAGE(bufoff, gbase, voff) do { _Pragma("unroll") for (int _i = 0; _i < 2; ++_i) \
;         __builtin_amdgcn_global_load_lds((const unsigned*)((const char*)(gbase) + (voff)[_i]), (LAS unsigned*)(lds + (bufoff) + ldsw + _i * 8192), 16, 0, 0); } while (0)
; #define PG8_LDA(dst, b, h) do { _Pragma("unroll") for (int m = 0; m < 4; ++m) _Pragma("unroll") for (int k = 0; k < 2; ++k) dst[m][k] = *(const LAS bf16x8*)(lds + PG8_SA(b, h) + aoff + m * 2048 + k * 1024); } while (0)
; #define PG8_MMA(ai, bj, At, Bt) do { __builtin_amdgcn_s_setprio(1); _Pragma("unroll") for (int m = 0; m < 4; ++m) _Pragma("unroll") for (int n = 0; n < 2; ++n) _Pragma("unroll") for (int k = 0; k < 2; ++k) \
;         acc[ai][bj][m][n] = __builtin_amdgcn_mfma_f32_16x16x32_bf16(Bt[n][k], At[m][k], acc[ai][bj][m][n], 0, 0, 0); __builtin_amdgcn_s_setprio(0); } while (0)
; #define PG8_WAIT_V(n) asm volatile("s_waitcnt vmcnt(" #n ")" ::: "memory")
; #define PG8_WAIT_L(n) asm volatile("s_waitcnt lgkmcnt(" #n ")" ::: "memory")
; #define PG8_BAR __builtin_amdgcn_s_barrier()
; #define PG8_SCHED __builtin_amdgcn_sched_barrier(0)
; template <class Epi, bool ALIGN_EPI>
; __device__ __forceinline__ void gemm_phase(LAS unsigned char* lds, const Gemm g, const StaticOrder& S, const Epi& E, const int tid) {
;     ...
;             PG8_LDA(At, 1, 1); PG8_STAGE(PG8_SB(1, 0), b3, voffB); PG8_STAGE(PG8_SB(1, 1), b3 + hstepB, voffB); PG8_STAGE(PG8_SA(1, 0), a3, voffA);
;             PG8_WAIT_V(8); PG8_WAIT_L(0); PG8_BAR; PG8_MMA(1, 0, At, B0); PG8_MMA(1, 1, At, B1); PG8_BAR; PG8_SCHED;
	global_load_lds_dwordx4 v144, s[54:55]
	s_add_i32 m0, s89, 0x2000
	s_add_u32 s52, s52, 0xc000
	s_addc_u32 s53, s53, 0
	global_load_lds_dwordx4 v140, s[54:55]
	s_add_i32 s54, s90, s61
	s_mov_b32 m0, s54
	ds_read_b128 v[226:229], v171 offset:56320
	global_load_lds_dwordx4 v144, s[52:53]
	s_add_i32 m0, s54, 0x2000
	ds_read_b128 v[222:225], v171 offset:55296
	global_load_lds_dwordx4 v140, s[52:53]
	s_mov_b32 m0, s77
	ds_read_b128 v[218:221], v171 offset:54272
	global_load_lds_dwordx4 v146, s[50:51]
	s_mov_b32 m0, s78
	ds_read_b128 v[214:217], v171 offset:53248
	global_load_lds_dwordx4 v142, s[50:51]
	s_waitcnt vmcnt(8)
	s_waitcnt lgkmcnt(0)
	s_barrier


; #define PG8_MMA(ai, bj, At, Bt) do { __builtin_amdgcn_s_setprio(1); _Pragma("unroll") for (int m = 0; m < 4; ++m) _Pragma("unroll") for (int n = 0; n < 2; ++n) _Pragma("unroll") for (int k = 0; k < 2; ++k) \
;         acc[ai][bj][m][n] = __builtin_amdgcn_mfma_f32_16x16x32_bf16(Bt[n][k], At[m][k], acc[ai][bj][m][n], 0, 0, 0); __builtin_amdgcn_s_setprio(0); } while (0)
; #define PG8_WAIT_V(n) asm volatile("s_waitcnt vmcnt(" #n ")" ::: "memory")
; #define PG8_WAIT_L(n) asm volatile("s_waitcnt lgkmcnt(" #n ")" ::: "memory")
; #define PG8_BAR __builtin_amdgcn_s_barrier()
; #define PG8_SCHED __builtin_amdgcn_sched_barrier(0)
; template <class Epi, bool ALIGN_EPI>
; __device__ __forceinline__ void gemm_phase(LAS unsigned char* lds, const Gemm g, const StaticOrder& S, const Epi& E, const int tid) {
;     ...
;             PG8_WAIT_V(8); PG8_WAIT_L(0); PG8_BAR; PG8_MMA(1, 0, At, B0); PG8_MMA(1, 1, At, B1); PG8_BAR; PG8_SCHED;
	v_mfma_f32_16x16x32_bf16 v[84:87], v[132:135], v[184:187], v[84:87]
	v_mfma_f32_16x16x32_bf16 v[84:87], v[136:139], v[188:191], v[84:87]
	v_mfma_f32_16x16x32_bf16 v[56:59], v[156:159], v[188:191], v[56:59]
	v_mfma_f32_16x16x32_bf16 v[56:59], v[152:155], v[184:187], v[56:59]
	v_mfma_f32_16x16x32_bf16 v[44:47], v[152:155], v[192:195], v[44:47]
	v_mfma_f32_16x16x32_bf16 v[44:47], v[156:159], v[196:199], v[44:47]
	v_mfma_f32_16x16x32_bf16 v[72:75], v[136:139], v[196:199], v[72:75]
	v_mfma_f32_16x16x32_bf16 v[72:75], v[132:135], v[192:195], v[72:75]
	v_mfma_f32_16x16x32_bf16 v[64:67], v[132:135], v[214:217], v[64:67]
	v_mfma_f32_16x16x32_bf16 v[64:67], v[136:139], v[218:221], v[64:67]
	v_mfma_f32_16x16x32_bf16 v[36:39], v[156:159], v[218:221], v[36:39]
	v_mfma_f32_16x16x32_bf16 v[36:39], v[152:155], v[214:217], v[36:39]
	v_mfma_f32_16x16x32_bf16 v[28:31], v[152:155], v[222:225], v[28:31]
	v_mfma_f32_16x16x32_bf16 v[28:31], v[156:159], v[226:229], v[28:31]
	v_mfma_f32_16x16x32_bf16 v[52:55], v[136:139], v[226:229], v[52:55]
	v_mfma_f32_16x16x32_bf16 v[52:55], v[132:135], v[222:225], v[52:55]


; #define PG8_MMA(ai, bj, At, Bt) do { __builtin_amdgcn_s_setprio(1); _Pragma("unroll") for (int m = 0; m < 4; ++m) _Pragma("unroll") for (int n = 0; n < 2; ++n) _Pragma("unroll") for (int k = 0; k < 2; ++k) \
;         acc[ai][bj][m][n] = __builtin_amdgcn_mfma_f32_16x16x32_bf16(Bt[n][k], At[m][k], acc[ai][bj][m][n], 0, 0, 0); __builtin_amdgcn_s_setprio(0); } while (0)
; #define PG8_WAIT_V(n) asm volatile("s_waitcnt vmcnt(" #n ")" ::: "memory")
; #define PG8_WAIT_L(n) asm volatile("s_waitcnt lgkmcnt(" #n ")" ::: "memory")
; #define PG8_BAR __builtin_amdgcn_s_barrier()
; #define PG8_SCHED __builtin_amdgcn_sched_barrier(0)
; template <class Epi, bool ALIGN_EPI>
; __device__ __forceinline__ void gemm_phase(LAS unsigned char* lds, const Gemm g, const StaticOrder& S, const Epi& E, const int tid) {
;     ...
;             PG8_WAIT_V(8); PG8_WAIT_L(0); PG8_BAR; PG8_MMA(1, 0, At, B0); PG8_MMA(1, 1, At, B1); PG8_BAR; PG8_SCHED;
	v_mfma_f32_16x16x32_bf16 v[40:43], v[160:163], v[184:187], v[40:43]
	v_mfma_f32_16x16x32_bf16 v[40:43], v[172:175], v[188:191], v[40:43]
	v_mfma_f32_16x16x32_bf16 v[20:23], v[180:183], v[188:191], v[20:23]
	v_mfma_f32_16x16x32_bf16 v[20:23], v[176:179], v[184:187], v[20:23]
	v_mfma_f32_16x16x32_bf16 v[12:15], v[176:179], v[192:195], v[12:15]
	v_mfma_f32_16x16x32_bf16 v[12:15], v[180:183], v[196:199], v[12:15]
	v_mfma_f32_16x16x32_bf16 v[32:35], v[172:175], v[196:199], v[32:35]
	v_mfma_f32_16x16x32_bf16 v[32:35], v[160:163], v[192:195], v[32:35]
	v_mfma_f32_16x16x32_bf16 v[24:27], v[160:163], v[214:217], v[24:27]
	v_mfma_f32_16x16x32_bf16 v[24:27], v[172:175], v[218:221], v[24:27]
	v_mfma_f32_16x16x32_bf16 v[6:9], v[176:179], v[214:217], v[8:11]
	v_mfma_f32_16x16x32_bf16 v[8:11], v[180:183], v[218:221], v[6:9]
	v_mfma_f32_16x16x32_bf16 v[16:19], v[160:163], v[222:225], v[16:19]
	v_mfma_f32_16x16x32_bf16 v[16:19], v[172:175], v[226:229], v[16:19]
	v_mfma_f32_16x16x32_bf16 v[2:5], v[176:179], v[222:225], v[2:5]
	v_mfma_f32_16x16x32_bf16 v[4:7], v[180:183], v[226:229], v[2:5]

; #define PG8_MMA(ai, bj, At, Bt) do { __builtin_amdgcn_s_setprio(1); _Pragma("unroll") for (int m = 0; m < 4; ++m) _Pragma("unroll") for (int n = 0; n < 2; ++n) _Pragma("unroll") for (int k = 0; k < 2; ++k) \
;         acc[ai][bj][m][n] = __builtin_amdgcn_mfma_f32_16x16x32_bf16(Bt[n][k], At[m][k], acc[ai][bj][m][n], 0, 0, 0); __builtin_amdgcn_s_setprio(0); } while (0)
; #define PG8_WAIT_V(n) asm volatile("s_waitcnt vmcnt(" #n ")" ::: "memory")
; #define PG8_WAIT_L(n) asm volatile("s_waitcnt lgkmcnt(" #n ")" ::: "memory")
; #define PG8_BAR __builtin_amdgcn_s_barrier()
; #define PG8_SCHED __builtin_amdgcn_sched_barrier(0)
; template <class Epi, bool ALIGN_EPI>
; __device__ __forceinline__ void gemm_phase(LAS unsigned char* lds, const Gemm g, const StaticOrder& S, const Epi& E, const int tid) {
;     ...
;             PG8_WAIT_V(8); PG8_WAIT_L(0); PG8_BAR; PG8_MMA(1, 0, At, B0); PG8_MMA(1, 1, At, B1); PG8_BAR; PG8_SCHED;
;         }
;         if constexpr (ALIGN_EPI) { if (wr == 0) PG8_BAR; }
	s_barrier
	s_add_i32 s88, s88, 2
	s_add_u32 s48, s48, 0x10000
	s_addc_u32 s49, s49, 0
	s_add_u32 s86, s86, 0x10000
	s_addc_u32 s87, s87, 0
	s_cmp_gt_u32 s88, 29
	s_cbranch_scc0 .LBB0_385
	s_and_b64 vcc, exec, s[34:35]
	s_cbranch_vccz .LBB0_388
	s_barrier

; #define PG8_STAGE(bufoff, gbase, voff) do { _Pragma("unroll") for (int _i = 0; _i < 2; ++_i) \
;         __builtin_amdgcn_global_load_lds((const unsigned*)((const char*)(gbase) + (voff)[_i]), (LAS unsigned*)(lds + (bufoff) + ldsw + _i * 8192), 16, 0, 0); } while (0)
; #define PG8_LDA(dst, b, h) do { _Pragma("unroll") for (int m = 0; m < 4; ++m) _Pragma("unroll") for (int k = 0; k < 2; ++k) dst[m][k] = *(const LAS bf16x8*)(lds + PG8_SA(b, h) + aoff + m * 2048 + k * 1024); } while (0)
; #define PG8_LDB(dst, b, h) do { _Pragma("unroll") for (int n = 0; n < 2; ++n) _Pragma("unroll") for (int k = 0; k < 2; ++k) dst[n][k] = *(const LAS bf16x8*)(lds + PG8_SB(b, h) + boff + n * 2048 + k * 1024); } while (0)
; #define PG8_SCHED __builtin_amdgcn_sched_barrier(0)
; template <class Epi, bool ALIGN_EPI>
; __device__ __forceinline__ void gemm_phase(LAS unsigned char* lds, const Gemm g, const StaticOrder& S, const Epi& E, const int tid) {
;     ...
;         const char* nA = has_next ? (const char*)g.A + (size_t)nxt.pm * tstepA + (size_t)nxt.pn * g.acs : cA; const char* nB = has_next ? (const char*)g.Bt + (size_t)nxt.pn * tstepB : cB;
;         for (int t = 0; t < nt; t += 2) {
;             const bool last = (t == nt - 2);
;             const char* a1 = cA + (size_t)(t + 1) * kstepA;
;             const char* a2 = last ? nA : cA + (size_t)(t + 2) * kstepA; const char* b2 = last ? nB : cB + (size_t)(t + 2) * kstepB;
;             const char* a3 = a2 + kstepA; const char* b3 = b2 + kstepB;
;             PG8_LDB(B0, 0, 0); PG8_LDB(B1, 0, 1); PG8_SCHED; PG8_LDA(At, 0, 0); PG8_STAGE(PG8_SA(1, 1), a1 + hstepA, voffA);
.LBB0_847:
	s_add_u32 s22, s10, 0xfff80080
	s_addc_u32 s23, s11, -1
	s_add_i32 s87, 0, 0x10000
	s_cmp_eq_u32 s86, 28
	s_cselect_b32 s35, s49, s23
	s_cselect_b32 s34, s82, s22
	v_add_u32_e32 v0, s87, v154
	s_cselect_b32 s23, s47, s85
	s_cselect_b32 s22, s83, s84
	s_add_i32 s90, 0, 0x14000
	s_waitcnt lgkmcnt(0)
	ds_read_b128 v[132:135], v0
	ds_read_b128 v[148:151], v0 offset:1024
	ds_read_b128 v[156:159], v0 offset:2048
	ds_read_b128 v[160:163], v0 offset:3072
	v_add_u32_e32 v0, s90, v154
	ds_read_b128 v[164:167], v0
	ds_read_b128 v[168:171], v0 offset:1024
	ds_read_b128 v[172:175], v0 offset:2048
	ds_read_b128 v[176:179], v0 offset:3072
	s_add_i32 m0, s70, 0xc000
	ds_read_b128 v[180:183], v155
	ds_read_b128 v[184:187], v155 offset:1024
	ds_read_b128 v[188:191], v155 offset:2048
	ds_read_b128 v[192:195], v155 offset:3072
	ds_read_b128 v[196:199], v155 offset:4096
	ds_read_b128 v[214:217], v155 offset:5120
	ds_read_b128 v[218:221], v155 offset:6144

; #define PG8_STAGE(bufoff, gbase, voff) do { _Pragma("unroll") for (int _i = 0; _i < 2; ++_i) \
;         __builtin_amdgcn_global_load_lds((const unsigned*)((const char*)(gbase) + (voff)[_i]), (LAS unsigned*)(lds + (bufoff) + ldsw + _i * 8192), 16, 0, 0); } while (0)
; #define PG8_LDA(dst, b, h) do { _Pragma("unroll") for (int m = 0; m < 4; ++m) _Pragma("unroll") for (int k = 0; k < 2; ++k) dst[m][k] = *(const LAS bf16x8*)(lds + PG8_SA(b, h) + aoff + m * 2048 + k * 1024); } while (0)
; #define PG8_LDB(dst, b, h) do { _Pragma("unroll") for (int n = 0; n < 2; ++n) _Pragma("unroll") for (int k = 0; k < 2; ++k) dst[n][k] = *(const LAS bf16x8*)(lds + PG8_SB(b, h) + boff + n * 2048 + k * 1024); } while (0)
; #define PG8_MMA(ai, bj, At, Bt) do { __builtin_amdgcn_s_setprio(1); _Pragma("unroll") for (int m = 0; m < 4; ++m) _Pragma("unroll") for (int n = 0; n < 2; ++n) _Pragma("unroll") for (int k = 0; k < 2; ++k) \
;         acc[ai][bj][m][n] = __builtin_amdgcn_mfma_f32_16x16x32_bf16(Bt[n][k], At[m][k], acc[ai][bj][m][n], 0, 0, 0); __builtin_amdgcn_s_setprio(0); } while (0)
; #define PG8_WAIT_V(n) asm volatile("s_waitcnt vmcnt(" #n ")" ::: "memory")
; #define PG8_WAIT_L(n) asm volatile("s_waitcnt lgkmcnt(" #n ")" ::: "memory")
; #define PG8_BAR __builtin_amdgcn_s_barrier()
; #define PG8_SCHED __builtin_amdgcn_sched_barrier(0)
; template <class Epi, bool ALIGN_EPI>
; __device__ __forceinline__ void gemm_phase(LAS unsigned char* lds, const Gemm g, const StaticOrder& S, const Epi& E, const int tid) {
;     ...
;             PG8_LDB(B0, 0, 0); PG8_LDB(B1, 0, 1); PG8_SCHED; PG8_LDA(At, 0, 0); PG8_STAGE(PG8_SA(1, 1), a1 + hstepA, voffA);
;             PG8_WAIT_V(8); PG8_WAIT_L(0); PG8_BAR; PG8_MMA(0, 0, At, B0); PG8_MMA(0, 1, At, B1); PG8_BAR; PG8_SCHED;
	global_load_lds_dwordx4 v144, s[10:11]
	s_add_i32 m0, s70, 0xe000
	ds_read_b128 v[222:225], v155 offset:7168
	global_load_lds_dwordx4 v146, s[10:11]
	s_waitcnt vmcnt(8)
	s_waitcnt lgkmcnt(0)
	s_barrier


; #define PG8_MMA(ai, bj, At, Bt) do { __builtin_amdgcn_s_setprio(1); _Pragma("unroll") for (int m = 0; m < 4; ++m) _Pragma("unroll") for (int n = 0; n < 2; ++n) _Pragma("unroll") for (int k = 0; k < 2; ++k) \
;         acc[ai][bj][m][n] = __builtin_amdgcn_mfma_f32_16x16x32_bf16(Bt[n][k], At[m][k], acc[ai][bj][m][n], 0, 0, 0); __builtin_amdgcn_s_setprio(0); } while (0)
; #define PG8_WAIT_V(n) asm volatile("s_waitcnt vmcnt(" #n ")" ::: "memory")
; #define PG8_WAIT_L(n) asm volatile("s_waitcnt lgkmcnt(" #n ")" ::: "memory")
; #define PG8_BAR __builtin_amdgcn_s_barrier()
; #define PG8_SCHED __builtin_amdgcn_sched_barrier(0)
; template <class Epi, bool ALIGN_EPI>
; __device__ __forceinline__ void gemm_phase(LAS unsigned char* lds, const Gemm g, const StaticOrder& S, const Epi& E, const int tid) {
;     ...
;             PG8_WAIT_V(8); PG8_WAIT_L(0); PG8_BAR; PG8_MMA(0, 0, At, B0); PG8_MMA(0, 1, At, B1); PG8_BAR; PG8_SCHED;
	v_mfma_f32_16x16x32_bf16 v[8:11], v[132:135], v[180:183], v[8:11]
	v_mfma_f32_16x16x32_bf16 v[8:11], v[148:151], v[184:187], v[8:11]
	v_mfma_f32_16x16x32_bf16 v[56:59], v[160:163], v[184:187], v[56:59]
	v_mfma_f32_16x16x32_bf16 v[56:59], v[156:159], v[180:183], v[56:59]
	v_mfma_f32_16x16x32_bf16 v[48:51], v[156:159], v[188:191], v[48:51]
	v_mfma_f32_16x16x32_bf16 v[48:51], v[160:163], v[192:195], v[48:51]
	v_mfma_f32_16x16x32_bf16 v[52:55], v[148:151], v[192:195], v[52:55]
	v_mfma_f32_16x16x32_bf16 v[52:55], v[132:135], v[188:191], v[52:55]
	v_mfma_f32_16x16x32_bf16 v[44:47], v[132:135], v[196:199], v[44:47]
	v_mfma_f32_16x16x32_bf16 v[44:47], v[148:151], v[214:217], v[44:47]
	v_mfma_f32_16x16x32_bf16 v[40:43], v[160:163], v[214:217], v[40:43]
	v_mfma_f32_16x16x32_bf16 v[40:43], v[156:159], v[196:199], v[40:43]
	v_mfma_f32_16x16x32_bf16 v[32:35], v[156:159], v[218:221], v[32:35]
	v_mfma_f32_16x16x32_bf16 v[32:35], v[160:163], v[222:225], v[32:35]
	v_mfma_f32_16x16x32_bf16 v[36:39], v[148:151], v[222:225], v[36:39]
	v_mfma_f32_16x16x32_bf16 v[36:39], v[132:135], v[218:221], v[36:39]


; #define PG8_MMA(ai, bj, At, Bt) do { __builtin_amdgcn_s_setprio(1); _Pragma("unroll") for (int m = 0; m < 4; ++m) _Pragma("unroll") for (int n = 0; n < 2; ++n) _Pragma("unroll") for (int k = 0; k < 2; ++k) \
;         acc[ai][bj][m][n] = __builtin_amdgcn_mfma_f32_16x16x32_bf16(Bt[n][k], At[m][k], acc[ai][bj][m][n], 0, 0, 0); __builtin_amdgcn_s_setprio(0); } while (0)
; #define PG8_WAIT_V(n) asm volatile("s_waitcnt vmcnt(" #n ")" ::: "memory")
; #define PG8_WAIT_L(n) asm volatile("s_waitcnt lgkmcnt(" #n ")" ::: "memory")
; #define PG8_BAR __builtin_amdgcn_s_barrier()
; #define PG8_SCHED __builtin_amdgcn_sched_barrier(0)
; template <class Epi, bool ALIGN_EPI>
; __device__ __forceinline__ void gemm_phase(LAS unsigned char* lds, const Gemm g, const StaticOrder& S, const Epi& E, const int tid) {
;     ...
;             PG8_WAIT_V(8); PG8_WAIT_L(0); PG8_BAR; PG8_MMA(0, 0, At, B0); PG8_MMA(0, 1, At, B1); PG8_BAR; PG8_SCHED;
	v_mfma_f32_16x16x32_bf16 v[2:5], v[164:167], v[180:183], v[4:7]
	v_mfma_f32_16x16x32_bf16 v[2:5], v[168:171], v[184:187], v[2:5]
	v_mfma_f32_16x16x32_bf16 v[28:31], v[176:179], v[184:187], v[28:31]
	v_mfma_f32_16x16x32_bf16 v[28:31], v[172:175], v[180:183], v[28:31]
	v_mfma_f32_16x16x32_bf16 v[92:95], v[172:175], v[188:191], v[92:95]
	v_mfma_f32_16x16x32_bf16 v[92:95], v[176:179], v[192:195], v[92:95]
	v_mfma_f32_16x16x32_bf16 v[96:99], v[168:171], v[192:195], v[96:99]
	v_mfma_f32_16x16x32_bf16 v[96:99], v[164:167], v[188:191], v[96:99]
	v_mfma_f32_16x16x32_bf16 v[88:91], v[164:167], v[196:199], v[88:91]
	v_mfma_f32_16x16x32_bf16 v[88:91], v[168:171], v[214:217], v[88:91]
	v_mfma_f32_16x16x32_bf16 v[84:87], v[176:179], v[214:217], v[84:87]
	v_mfma_f32_16x16x32_bf16 v[84:87], v[172:175], v[196:199], v[84:87]
	v_mfma_f32_16x16x32_bf16 v[76:79], v[172:175], v[218:221], v[76:79]
	v_mfma_f32_16x16x32_bf16 v[76:79], v[176:179], v[222:225], v[76:79]
	v_mfma_f32_16x16x32_bf16 v[80:83], v[168:171], v[222:225], v[80:83]
	v_mfma_f32_16x16x32_bf16 v[80:83], v[164:167], v[218:221], v[80:83]

; #define PG8_STAGE(bufoff, gbase, voff) do { _Pragma("unroll") for (int _i = 0; _i < 2; ++_i) \
;         __builtin_amdgcn_global_load_lds((const unsigned*)((const char*)(gbase) + (voff)[_i]), (LAS unsigned*)(lds + (bufoff) + ldsw + _i * 8192), 16, 0, 0); } while (0)
; #define PG8_LDA(dst, b, h) do { _Pragma("unroll") for (int m = 0; m < 4; ++m) _Pragma("unroll") for (int k = 0; k < 2; ++k) dst[m][k] = *(const LAS bf16x8*)(lds + PG8_SA(b, h) + aoff + m * 2048 + k * 1024); } while (0)
; #define PG8_MMA(ai, bj, At, Bt) do { __builtin_amdgcn_s_setprio(1); _Pragma("unroll") for (int m = 0; m < 4; ++m) _Pragma("unroll") for (int n = 0; n < 2; ++n) _Pragma("unroll") for (int k = 0; k < 2; ++k) \
;         acc[ai][bj][m][n] = __builtin_amdgcn_mfma_f32_16x16x32_bf16(Bt[n][k], At[m][k], acc[ai][bj][m][n], 0, 0, 0); __builtin_amdgcn_s_setprio(0); } while (0)
; #define PG8_WAIT_V(n) asm volatile("s_waitcnt vmcnt(" #n ")" ::: "memory")
; #define PG8_WAIT_L(n) asm volatile("s_waitcnt lgkmcnt(" #n ")" ::: "memory")
; #define PG8_BAR __builtin_amdgcn_s_barrier()
; #define PG8_SCHED __builtin_amdgcn_sched_barrier(0)
; template <class Epi, bool ALIGN_EPI>
; __device__ __forceinline__ void gemm_phase(LAS unsigned char* lds, const Gemm g, const StaticOrder& S, const Epi& E, const int tid) {
;     ...
;             PG8_WAIT_V(8); PG8_WAIT_L(0); PG8_BAR; PG8_MMA(0, 0, At, B0); PG8_MMA(0, 1, At, B1); PG8_BAR; PG8_SCHED;
;             PG8_LDA(At, 0, 1); PG8_STAGE(PG8_SB(0, 0), b2, voffB); PG8_STAGE(PG8_SB(0, 1), b2 + hstepB, voffB); PG8_STAGE(PG8_SA(0, 0), a2, voffA);
	s_barrier
	s_add_i32 s87, s87, s61
	s_mov_b32 m0, s87
	ds_read_b128 v[180:183], v155 offset:16384
	ds_read_b128 v[184:187], v155 offset:17408
	ds_read_b128 v[188:191], v155 offset:18432
	ds_read_b128 v[192:195], v155 offset:19456
	ds_read_b128 v[196:199], v155 offset:20480
	ds_read_b128 v[214:217], v155 offset:21504


; #define PG8_STAGE(bufoff, gbase, voff) do { _Pragma("unroll") for (int _i = 0; _i < 2; ++_i) \
;         __builtin_amdgcn_global_load_lds((const unsigned*)((const char*)(gbase) + (voff)[_i]), (LAS unsigned*)(lds + (bufoff) + ldsw + _i * 8192), 16, 0, 0); } while (0)
; #define PG8_LDA(dst, b, h) do { _Pragma("unroll") for (int m = 0; m < 4; ++m) _Pragma("unroll") for (int k = 0; k < 2; ++k) dst[m][k] = *(const LAS bf16x8*)(lds + PG8_SA(b, h) + aoff + m * 2048 + k * 1024); } while (0)
; #define PG8_MMA(ai, bj, At, Bt) do { __builtin_amdgcn_s_setprio(1); _Pragma("unroll") for (int m = 0; m < 4; ++m) _Pragma("unroll") for (int n = 0; n < 2; ++n) _Pragma("unroll") for (int k = 0; k < 2; ++k) \
;         acc[ai][bj][m][n] = __builtin_amdgcn_mfma_f32_16x16x32_bf16(Bt[n][k], At[m][k], acc[ai][bj][m][n], 0, 0, 0); __builtin_amdgcn_s_setprio(0); } while (0)
; #define PG8_WAIT_V(n) asm volatile("s_waitcnt vmcnt(" #n ")" ::: "memory")
; #define PG8_WAIT_L(n) asm volatile("s_waitcnt lgkmcnt(" #n ")" ::: "memory")
; #define PG8_BAR __builtin_amdgcn_s_barrier()
; #define PG8_SCHED __builtin_amdgcn_sched_barrier(0)
; template <class Epi, bool ALIGN_EPI>
; __device__ __forceinline__ void gemm_phase(LAS unsigned char* lds, const Gemm g, const StaticOrder& S, const Epi& E, const int tid) {
;     ...
;             PG8_LDA(At, 0, 1); PG8_STAGE(PG8_SB(0, 0), b2, voffB); PG8_STAGE(PG8_SB(0, 1), b2 + hstepB, voffB); PG8_STAGE(PG8_SA(0, 0), a2, voffA);
;             PG8_WAIT_V(8); PG8_WAIT_L(0); PG8_BAR; PG8_MMA(1, 0, At, B0); PG8_MMA(1, 1, At, B1); PG8_BAR; PG8_SCHED;
	global_load_lds_dwordx4 v140, s[22:23]
	s_add_i32 m0, s87, 0x2000
	s_add_u32 s88, s22, 0x4000
	s_addc_u32 s89, s23, 0
	s_add_i32 s87, s90, s61
	global_load_lds_dwordx4 v136, s[22:23]
	s_mov_b32 m0, s87
	v_lshl_add_u64 v[152:153], s[34:35], 0, v[142:143]
	global_load_lds_dwordx4 v140, s[88:89]
	s_add_i32 m0, s87, 0x2000
	v_lshl_add_u64 v[200:201], s[34:35], 0, v[138:139]
	global_load_lds_dwordx4 v136, s[88:89]
	s_mov_b32 m0, s70
	ds_read_b128 v[222:225], v155 offset:23552
	global_load_lds_dwordx4 v[152:153], off
	s_mov_b32 m0, s71
	ds_read_b128 v[218:221], v155 offset:22528
	global_load_lds_dwordx4 v[200:201], off
	s_waitcnt vmcnt(8)
	s_waitcnt lgkmcnt(0)
	s_barrier


; #define PG8_MMA(ai, bj, At, Bt) do { __builtin_amdgcn_s_setprio(1); _Pragma("unroll") for (int m = 0; m < 4; ++m) _Pragma("unroll") for (int n = 0; n < 2; ++n) _Pragma("unroll") for (int k = 0; k < 2; ++k) \
;         acc[ai][bj][m][n] = __builtin_amdgcn_mfma_f32_16x16x32_bf16(Bt[n][k], At[m][k], acc[ai][bj][m][n], 0, 0, 0); __builtin_amdgcn_s_setprio(0); } while (0)
; #define PG8_WAIT_V(n) asm volatile("s_waitcnt vmcnt(" #n ")" ::: "memory")
; #define PG8_WAIT_L(n) asm volatile("s_waitcnt lgkmcnt(" #n ")" ::: "memory")
; #define PG8_BAR __builtin_amdgcn_s_barrier()
; #define PG8_SCHED __builtin_amdgcn_sched_barrier(0)
; template <class Epi, bool ALIGN_EPI>
; __device__ __forceinline__ void gemm_phase(LAS unsigned char* lds, const Gemm g, const StaticOrder& S, const Epi& E, const int tid) {
;     ...
;             PG8_WAIT_V(8); PG8_WAIT_L(0); PG8_BAR; PG8_MMA(1, 0, At, B0); PG8_MMA(1, 1, At, B1); PG8_BAR; PG8_SCHED;
	v_mfma_f32_16x16x32_bf16 v[24:27], v[132:135], v[180:183], v[24:27]
	v_mfma_f32_16x16x32_bf16 v[24:27], v[148:151], v[184:187], v[24:27]
	v_mfma_f32_16x16x32_bf16 v[20:23], v[160:163], v[184:187], v[20:23]
	v_mfma_f32_16x16x32_bf16 v[20:23], v[156:159], v[180:183], v[20:23]
	v_mfma_f32_16x16x32_bf16 v[72:75], v[156:159], v[188:191], v[72:75]
	v_mfma_f32_16x16x32_bf16 v[72:75], v[160:163], v[192:195], v[72:75]
	v_mfma_f32_16x16x32_bf16 v[64:67], v[148:151], v[192:195], v[64:67]
	v_mfma_f32_16x16x32_bf16 v[64:67], v[132:135], v[188:191], v[64:67]
	v_mfma_f32_16x16x32_bf16 v[16:19], v[132:135], v[196:199], v[16:19]
	v_mfma_f32_16x16x32_bf16 v[16:19], v[148:151], v[214:217], v[16:19]
	v_mfma_f32_16x16x32_bf16 v[12:15], v[160:163], v[214:217], v[12:15]
	v_mfma_f32_16x16x32_bf16 v[12:15], v[156:159], v[196:199], v[12:15]
	v_mfma_f32_16x16x32_bf16 v[68:71], v[156:159], v[218:221], v[68:71]
	v_mfma_f32_16x16x32_bf16 v[68:71], v[160:163], v[222:225], v[68:71]
	v_mfma_f32_16x16x32_bf16 v[60:63], v[148:151], v[222:225], v[60:63]
	v_mfma_f32_16x16x32_bf16 v[60:63], v[132:135], v[218:221], v[60:63]


; #define PG8_MMA(ai, bj, At, Bt) do { __builtin_amdgcn_s_setprio(1); _Pragma("unroll") for (int m = 0; m < 4; ++m) _Pragma("unroll") for (int n = 0; n < 2; ++n) _Pragma("unroll") for (int k = 0; k < 2; ++k) \
;         acc[ai][bj][m][n] = __builtin_amdgcn_mfma_f32_16x16x32_bf16(Bt[n][k], At[m][k], acc[ai][bj][m][n], 0, 0, 0); __builtin_amdgcn_s_setprio(0); } while (0)
; #define PG8_WAIT_V(n) asm volatile("s_waitcnt vmcnt(" #n ")" ::: "memory")
; #define PG8_WAIT_L(n) asm volatile("s_waitcnt lgkmcnt(" #n ")" ::: "memory")
; #define PG8_BAR __builtin_amdgcn_s_barrier()
; #define PG8_SCHED __builtin_amdgcn_sched_barrier(0)
; template <class Epi, bool ALIGN_EPI>
; __device__ __forceinline__ void gemm_phase(LAS unsigned char* lds, const Gemm g, const StaticOrder& S, const Epi& E, const int tid) {
;     ...
;             PG8_WAIT_V(8); PG8_WAIT_L(0); PG8_BAR; PG8_MMA(1, 0, At, B0); PG8_MMA(1, 1, At, B1); PG8_BAR; PG8_SCHED;
	v_mfma_f32_16x16x32_bf16 v[128:131], v[164:167], v[180:183], v[128:131]
	v_mfma_f32_16x16x32_bf16 v[128:131], v[168:171], v[184:187], v[128:131]
	v_mfma_f32_16x16x32_bf16 v[124:127], v[176:179], v[184:187], v[124:127]
	v_mfma_f32_16x16x32_bf16 v[124:127], v[172:175], v[180:183], v[124:127]
	v_mfma_f32_16x16x32_bf16 v[116:119], v[172:175], v[188:191], v[116:119]
	v_mfma_f32_16x16x32_bf16 v[116:119], v[176:179], v[192:195], v[116:119]
	v_mfma_f32_16x16x32_bf16 v[120:123], v[168:171], v[192:195], v[120:123]
	v_mfma_f32_16x16x32_bf16 v[120:123], v[164:167], v[188:191], v[120:123]
	v_mfma_f32_16x16x32_bf16 v[112:115], v[164:167], v[196:199], v[112:115]
	v_mfma_f32_16x16x32_bf16 v[112:115], v[168:171], v[214:217], v[112:115]
	v_mfma_f32_16x16x32_bf16 v[108:111], v[176:179], v[214:217], v[108:111]
	v_mfma_f32_16x16x32_bf16 v[108:111], v[172:175], v[196:199], v[108:111]
	v_mfma_f32_16x16x32_bf16 v[100:103], v[172:175], v[218:221], v[100:103]
	v_mfma_f32_16x16x32_bf16 v[100:103], v[176:179], v[222:225], v[100:103]
	v_mfma_f32_16x16x32_bf16 v[104:107], v[168:171], v[222:225], v[104:107]
	v_mfma_f32_16x16x32_bf16 v[104:107], v[164:167], v[218:221], v[104:107]

; #define PG8_STAGE(bufoff, gbase, voff) do { _Pragma("unroll") for (int _i = 0; _i < 2; ++_i) \
;         __builtin_amdgcn_global_load_lds((const unsigned*)((const char*)(gbase) + (voff)[_i]), (LAS unsigned*)(lds + (bufoff) + ldsw + _i * 8192), 16, 0, 0); } while (0)
; #define PG8_LDA(dst, b, h) do { _Pragma("unroll") for (int m = 0; m < 4; ++m) _Pragma("unroll") for (int k = 0; k < 2; ++k) dst[m][k] = *(const LAS bf16x8*)(lds + PG8_SA(b, h) + aoff + m * 2048 + k * 1024); } while (0)
; #define PG8_LDB(dst, b, h) do { _Pragma("unroll") for (int n = 0; n < 2; ++n) _Pragma("unroll") for (int k = 0; k < 2; ++k) dst[n][k] = *(const LAS bf16x8*)(lds + PG8_SB(b, h) + boff + n * 2048 + k * 1024); } while (0)
; #define PG8_SCHED __builtin_amdgcn_sched_barrier(0)
; template <class Epi, bool ALIGN_EPI>
; __device__ __forceinline__ void gemm_phase(LAS unsigned char* lds, const Gemm g, const StaticOrder& S, const Epi& E, const int tid) {
;     ...
;             PG8_LDB(B0, 1, 0); PG8_LDB(B1, 1, 1); PG8_SCHED; PG8_LDA(At, 1, 0); PG8_STAGE(PG8_SA(0, 1), a2 + hstepA, voffA);
	s_barrier
	s_add_i32 s87, 0, 0x18000
	v_add_u32_e32 v0, s87, v154
	s_add_i32 s88, 0, 0x1c000
	ds_read_b128 v[132:135], v0
	ds_read_b128 v[148:151], v0 offset:1024
	ds_read_b128 v[156:159], v0 offset:2048
	ds_read_b128 v[160:163], v0 offset:3072
	v_add_u32_e32 v0, s88, v154
	ds_read_b128 v[164:167], v0
	ds_read_b128 v[168:171], v0 offset:1024
	ds_read_b128 v[172:175], v0 offset:2048
	ds_read_b128 v[176:179], v0 offset:3072
	s_add_u32 s34, s34, 0x80000
	s_addc_u32 s35, s35, 0
	s_mov_b32 m0, s72
	ds_read_b128 v[180:183], v155 offset:32768
	ds_read_b128 v[184:187], v155 offset:33792
	ds_read_b128 v[188:191], v155 offset:34816
	ds_read_b128 v[192:195], v155 offset:35840
	ds_read_b128 v[196:199], v155 offset:36864
	ds_read_b128 v[214:217], v155 offset:37888
	ds_read_b128 v[218:221], v155 offset:38912

; #define PG8_STAGE(bufoff, gbase, voff) do { _Pragma("unroll") for (int _i = 0; _i < 2; ++_i) \
;         __builtin_amdgcn_global_load_lds((const unsigned*)((const char*)(gbase) + (voff)[_i]), (LAS unsigned*)(lds + (bufoff) + ldsw + _i * 8192), 16, 0, 0); } while (0)
; #define PG8_LDA(dst, b, h) do { _Pragma("unroll") for (int m = 0; m < 4; ++m) _Pragma("unroll") for (int k = 0; k < 2; ++k) dst[m][k] = *(const LAS bf16x8*)(lds + PG8_SA(b, h) + aoff + m * 2048 + k * 1024); } while (0)
; #define PG8_LDB(dst, b, h) do { _Pragma("unroll") for (int n = 0; n < 2; ++n) _Pragma("unroll") for (int k = 0; k < 2; ++k) dst[n][k] = *(const LAS bf16x8*)(lds + PG8_SB(b, h) + boff + n * 2048 + k * 1024); } while (0)
; #define PG8_MMA(ai, bj, At, Bt) do { __builtin_amdgcn_s_setprio(1); _Pragma("unroll") for (int m = 0; m < 4; ++m) _Pragma("unroll") for (int n = 0; n < 2; ++n) _Pragma("unroll") for (int k = 0; k < 2; ++k) \
;         acc[ai][bj][m][n] = __builtin_amdgcn_mfma_f32_16x16x32_bf16(Bt[n][k], At[m][k], acc[ai][bj][m][n], 0, 0, 0); __builtin_amdgcn_s_setprio(0); } while (0)
; #define PG8_WAIT_V(n) asm volatile("s_waitcnt vmcnt(" #n ")" ::: "memory")
; #define PG8_WAIT_L(n) asm volatile("s_waitcnt lgkmcnt(" #n ")" ::: "memory")
; #define PG8_BAR __builtin_amdgcn_s_barrier()
; #define PG8_SCHED __builtin_amdgcn_sched_barrier(0)
; template <class Epi, bool ALIGN_EPI>
; __device__ __forceinline__ void gemm_phase(LAS unsigned char* lds, const Gemm g, const StaticOrder& S, const Epi& E, const int tid) {
;     ...
;             PG8_LDB(B0, 1, 0); PG8_LDB(B1, 1, 1); PG8_SCHED; PG8_LDA(At, 1, 0); PG8_STAGE(PG8_SA(0, 1), a2 + hstepA, voffA);
;             PG8_WAIT_V(8); PG8_WAIT_L(0); PG8_BAR; PG8_MMA(0, 0, At, B0); PG8_MMA(0, 1, At, B1); PG8_BAR; PG8_SCHED;
	global_load_lds_dwordx4 v142, s[34:35]
	s_mov_b32 m0, s73
	ds_read_b128 v[222:225], v155 offset:39936
	global_load_lds_dwordx4 v138, s[34:35]
	s_waitcnt vmcnt(8)
	s_waitcnt lgkmcnt(0)
	s_barrier


; #define PG8_MMA(ai, bj, At, Bt) do { __builtin_amdgcn_s_setprio(1); _Pragma("unroll") for (int m = 0; m < 4; ++m) _Pragma("unroll") for (int n = 0; n < 2; ++n) _Pragma("unroll") for (int k = 0; k < 2; ++k) \
;         acc[ai][bj][m][n] = __builtin_amdgcn_mfma_f32_16x16x32_bf16(Bt[n][k], At[m][k], acc[ai][bj][m][n], 0, 0, 0); __builtin_amdgcn_s_setprio(0); } while (0)
; #define PG8_WAIT_V(n) asm volatile("s_waitcnt vmcnt(" #n ")" ::: "memory")
; #define PG8_WAIT_L(n) asm volatile("s_waitcnt lgkmcnt(" #n ")" ::: "memory")
; #define PG8_BAR __builtin_amdgcn_s_barrier()
; #define PG8_SCHED __builtin_amdgcn_sched_barrier(0)
; template <class Epi, bool ALIGN_EPI>
; __device__ __forceinline__ void gemm_phase(LAS unsigned char* lds, const Gemm g, const StaticOrder& S, const Epi& E, const int tid) {
;     ...
;             PG8_WAIT_V(8); PG8_WAIT_L(0); PG8_BAR; PG8_MMA(0, 0, At, B0); PG8_MMA(0, 1, At, B1); PG8_BAR; PG8_SCHED;
	v_mfma_f32_16x16x32_bf16 v[6:9], v[132:135], v[180:183], v[8:11]
	v_mfma_f32_16x16x32_bf16 v[8:11], v[148:151], v[184:187], v[6:9]
	v_mfma_f32_16x16x32_bf16 v[56:59], v[160:163], v[184:187], v[56:59]
	v_mfma_f32_16x16x32_bf16 v[56:59], v[156:159], v[180:183], v[56:59]
	v_mfma_f32_16x16x32_bf16 v[48:51], v[156:159], v[188:191], v[48:51]
	v_mfma_f32_16x16x32_bf16 v[48:51], v[160:163], v[192:195], v[48:51]
	v_mfma_f32_16x16x32_bf16 v[52:55], v[148:151], v[192:195], v[52:55]
	v_mfma_f32_16x16x32_bf16 v[52:55], v[132:135], v[188:191], v[52:55]
	v_mfma_f32_16x16x32_bf16 v[44:47], v[132:135], v[196:199], v[44:47]
	v_mfma_f32_16x16x32_bf16 v[44:47], v[148:151], v[214:217], v[44:47]
	v_mfma_f32_16x16x32_bf16 v[40:43], v[160:163], v[214:217], v[40:43]
	v_mfma_f32_16x16x32_bf16 v[40:43], v[156:159], v[196:199], v[40:43]
	v_mfma_f32_16x16x32_bf16 v[32:35], v[156:159], v[218:221], v[32:35]
	v_mfma_f32_16x16x32_bf16 v[32:35], v[160:163], v[222:225], v[32:35]
	v_mfma_f32_16x16x32_bf16 v[36:39], v[148:151], v[222:225], v[36:39]
	v_mfma_f32_16x16x32_bf16 v[36:39], v[132:135], v[218:221], v[36:39]


; #define PG8_MMA(ai, bj, At, Bt) do { __builtin_amdgcn_s_setprio(1); _Pragma("unroll") for (int m = 0; m < 4; ++m) _Pragma("unroll") for (int n = 0; n < 2; ++n) _Pragma("unroll") for (int k = 0; k < 2; ++k) \
;         acc[ai][bj][m][n] = __builtin_amdgcn_mfma_f32_16x16x32_bf16(Bt[n][k], At[m][k], acc[ai][bj][m][n], 0, 0, 0); __builtin_amdgcn_s_setprio(0); } while (0)
; #define PG8_WAIT_V(n) asm volatile("s_waitcnt vmcnt(" #n ")" ::: "memory")
; #define PG8_WAIT_L(n) asm volatile("s_waitcnt lgkmcnt(" #n ")" ::: "memory")
; #define PG8_BAR __builtin_amdgcn_s_barrier()
; #define PG8_SCHED __builtin_amdgcn_sched_barrier(0)
; template <class Epi, bool ALIGN_EPI>
; __device__ __forceinline__ void gemm_phase(LAS unsigned char* lds, const Gemm g, const StaticOrder& S, const Epi& E, const int tid) {
;     ...
;             PG8_WAIT_V(8); PG8_WAIT_L(0); PG8_BAR; PG8_MMA(0, 0, At, B0); PG8_MMA(0, 1, At, B1); PG8_BAR; PG8_SCHED;
	v_mfma_f32_16x16x32_bf16 v[2:5], v[164:167], v[180:183], v[2:5]
	v_mfma_f32_16x16x32_bf16 v[4:7], v[168:171], v[184:187], v[2:5]
	v_mfma_f32_16x16x32_bf16 v[28:31], v[176:179], v[184:187], v[28:31]
	v_mfma_f32_16x16x32_bf16 v[28:31], v[172:175], v[180:183], v[28:31]
	v_mfma_f32_16x16x32_bf16 v[92:95], v[172:175], v[188:191], v[92:95]
	v_mfma_f32_16x16x32_bf16 v[92:95], v[176:179], v[192:195], v[92:95]
	v_mfma_f32_16x16x32_bf16 v[96:99], v[168:171], v[192:195], v[96:99]
	v_mfma_f32_16x16x32_bf16 v[96:99], v[164:167], v[188:191], v[96:99]
	v_mfma_f32_16x16x32_bf16 v[88:91], v[164:167], v[196:199], v[88:91]
	v_mfma_f32_16x16x32_bf16 v[88:91], v[168:171], v[214:217], v[88:91]
	v_mfma_f32_16x16x32_bf16 v[84:87], v[176:179], v[214:217], v[84:87]
	v_mfma_f32_16x16x32_bf16 v[84:87], v[172:175], v[196:199], v[84:87]
	v_mfma_f32_16x16x32_bf16 v[76:79], v[172:175], v[218:221], v[76:79]
	v_mfma_f32_16x16x32_bf16 v[76:79], v[176:179], v[222:225], v[76:79]
	v_mfma_f32_16x16x32_bf16 v[80:83], v[168:171], v[222:225], v[80:83]
	v_mfma_f32_16x16x32_bf16 v[80:83], v[164:167], v[218:221], v[80:83]

; #define PG8_STAGE(bufoff, gbase, voff) do { _Pragma("unroll") for (int _i = 0; _i < 2; ++_i) \
;         __builtin_amdgcn_global_load_lds((const unsigned*)((const char*)(gbase) + (voff)[_i]), (LAS unsigned*)(lds + (bufoff) + ldsw + _i * 8192), 16, 0, 0); } while (0)
; #define PG8_LDA(dst, b, h) do { _Pragma("unroll") for (int m = 0; m < 4; ++m) _Pragma("unroll") for (int k = 0; k < 2; ++k) dst[m][k] = *(const LAS bf16x8*)(lds + PG8_SA(b, h) + aoff + m * 2048 + k * 1024); } while (0)
; template <class Epi, bool ALIGN_EPI>
; __device__ __forceinline__ void gemm_phase(LAS unsigned char* lds, const Gemm g, const StaticOrder& S, const Epi& E, const int tid) {
;     ...
;             PG8_LDA(At, 1, 1); PG8_STAGE(PG8_SB(1, 0), b3, voffB); PG8_STAGE(PG8_SB(1, 1), b3 + hstepB, voffB); PG8_STAGE(PG8_SA(1, 0), a3, voffA);
	s_barrier
	s_add_u32 s34, s22, 0x8000
	s_addc_u32 s35, s23, 0
	s_add_i32 s87, s87, s61
	s_mov_b32 m0, s87
	ds_read_b128 v[180:183], v155 offset:49152
	ds_read_b128 v[184:187], v155 offset:50176
	ds_read_b128 v[188:191], v155 offset:51200
	ds_read_b128 v[192:195], v155 offset:52224


; #define PG8_STAGE(bufoff, gbase, voff) do { _Pragma("unroll") for (int _i = 0; _i < 2; ++_i) \
;         __builtin_amdgcn_global_load_lds((const unsigned*)((const char*)(gbase) + (voff)[_i]), (LAS unsigned*)(lds + (bufoff) + ldsw + _i * 8192), 16, 0, 0); } while (0)
; #define PG8_LDA(dst, b, h) do { _Pragma("unroll") for (int m = 0; m < 4; ++m) _Pragma("unroll") for (int k = 0; k < 2; ++k) dst[m][k] = *(const LAS bf16x8*)(lds + PG8_SA(b, h) + aoff + m * 2048 + k * 1024); } while (0)
; #define PG8_MMA(ai, bj, At, Bt) do { __builtin_amdgcn_s_setprio(1); _Pragma("unroll") for (int m = 0; m < 4; ++m) _Pragma("unroll") for (int n = 0; n < 2; ++n) _Pragma("unroll") for (int k = 0; k < 2; ++k) \
;         acc[ai][bj][m][n] = __builtin_amdgcn_mfma_f32_16x16x32_bf16(Bt[n][k], At[m][k], acc[ai][bj][m][n], 0, 0, 0); __builtin_amdgcn_s_setprio(0); } while (0)
; #define PG8_WAIT_V(n) asm volatile("s_waitcnt vmcnt(" #n ")" ::: "memory")
; #define PG8_WAIT_L(n) asm volatile("s_waitcnt lgkmcnt(" #n ")" ::: "memory")
; #define PG8_BAR __builtin_amdgcn_s_barrier()
; #define PG8_SCHED __builtin_amdgcn_sched_barrier(0)
; template <class Epi, bool ALIGN_EPI>
; __device__ __forceinline__ void gemm_phase(LAS unsigned char* lds, const Gemm g, const StaticOrder& S, const Epi& E, const int tid) {
;     ...
;             PG8_LDA(At, 1, 1); PG8_STAGE(PG8_SB(1, 0), b3, voffB); PG8_STAGE(PG8_SB(1, 1), b3 + hstepB, voffB); PG8_STAGE(PG8_SA(1, 0), a3, voffA);
;             PG8_WAIT_V(8); PG8_WAIT_L(0); PG8_BAR; PG8_MMA(1, 0, At, B0); PG8_MMA(1, 1, At, B1); PG8_BAR; PG8_SCHED;
	global_load_lds_dwordx4 v140, s[34:35]
	s_add_i32 m0, s87, 0x2000
	s_add_u32 s22, s22, 0xc000
	s_addc_u32 s23, s23, 0
	global_load_lds_dwordx4 v136, s[34:35]
	s_add_i32 s34, s88, s61
	s_mov_b32 m0, s34
	ds_read_b128 v[222:225], v155 offset:56320
	global_load_lds_dwordx4 v140, s[22:23]
	s_add_i32 m0, s34, 0x2000
	ds_read_b128 v[218:221], v155 offset:55296
	global_load_lds_dwordx4 v136, s[22:23]
	v_lshl_add_u64 v[2:3], v[152:153], 0, s[6:7]
	s_mov_b32 m0, s78
	ds_read_b128 v[214:217], v155 offset:54272
	global_load_lds_dwordx4 v[2:3], off
	v_lshl_add_u64 v[2:3], v[200:201], 0, s[6:7]
	s_mov_b32 m0, s79
	ds_read_b128 v[196:199], v155 offset:53248
	global_load_lds_dwordx4 v[2:3], off
	s_waitcnt vmcnt(8)
	s_waitcnt lgkmcnt(0)
	s_barrier


; #define PG8_MMA(ai, bj, At, Bt) do { __builtin_amdgcn_s_setprio(1); _Pragma("unroll") for (int m = 0; m < 4; ++m) _Pragma("unroll") for (int n = 0; n < 2; ++n) _Pragma("unroll") for (int k = 0; k < 2; ++k) \
;         acc[ai][bj][m][n] = __builtin_amdgcn_mfma_f32_16x16x32_bf16(Bt[n][k], At[m][k], acc[ai][bj][m][n], 0, 0, 0); __builtin_amdgcn_s_setprio(0); } while (0)
; #define PG8_WAIT_V(n) asm volatile("s_waitcnt vmcnt(" #n ")" ::: "memory")
; #define PG8_WAIT_L(n) asm volatile("s_waitcnt lgkmcnt(" #n ")" ::: "memory")
; #define PG8_BAR __builtin_amdgcn_s_barrier()
; #define PG8_SCHED __builtin_amdgcn_sched_barrier(0)
; template <class Epi, bool ALIGN_EPI>
; __device__ __forceinline__ void gemm_phase(LAS unsigned char* lds, const Gemm g, const StaticOrder& S, const Epi& E, const int tid) {
;     ...
;             PG8_WAIT_V(8); PG8_WAIT_L(0); PG8_BAR; PG8_MMA(1, 0, At, B0); PG8_MMA(1, 1, At, B1); PG8_BAR; PG8_SCHED;
	v_mfma_f32_16x16x32_bf16 v[24:27], v[132:135], v[180:183], v[24:27]
	v_mfma_f32_16x16x32_bf16 v[24:27], v[148:151], v[184:187], v[24:27]
	v_mfma_f32_16x16x32_bf16 v[20:23], v[160:163], v[184:187], v[20:23]
	v_mfma_f32_16x16x32_bf16 v[20:23], v[156:159], v[180:183], v[20:23]
	v_mfma_f32_16x16x32_bf16 v[72:75], v[156:159], v[188:191], v[72:75]
	v_mfma_f32_16x16x32_bf16 v[72:75], v[160:163], v[192:195], v[72:75]
	v_mfma_f32_16x16x32_bf16 v[64:67], v[148:151], v[192:195], v[64:67]
	v_mfma_f32_16x16x32_bf16 v[64:67], v[132:135], v[188:191], v[64:67]
	v_mfma_f32_16x16x32_bf16 v[16:19], v[132:135], v[196:199], v[16:19]
	v_mfma_f32_16x16x32_bf16 v[16:19], v[148:151], v[214:217], v[16:19]
	v_mfma_f32_16x16x32_bf16 v[12:15], v[160:163], v[214:217], v[12:15]
	v_mfma_f32_16x16x32_bf16 v[12:15], v[156:159], v[196:199], v[12:15]
	v_mfma_f32_16x16x32_bf16 v[68:71], v[156:159], v[218:221], v[68:71]
	v_mfma_f32_16x16x32_bf16 v[68:71], v[160:163], v[222:225], v[68:71]
	v_mfma_f32_16x16x32_bf16 v[60:63], v[148:151], v[222:225], v[60:63]
	v_mfma_f32_16x16x32_bf16 v[60:63], v[132:135], v[218:221], v[60:63]


; #define PG8_MMA(ai, bj, At, Bt) do { __builtin_amdgcn_s_setprio(1); _Pragma("unroll") for (int m = 0; m < 4; ++m) _Pragma("unroll") for (int n = 0; n < 2; ++n) _Pragma("unroll") for (int k = 0; k < 2; ++k) \
;         acc[ai][bj][m][n] = __builtin_amdgcn_mfma_f32_16x16x32_bf16(Bt[n][k], At[m][k], acc[ai][bj][m][n], 0, 0, 0); __builtin_amdgcn_s_setprio(0); } while (0)
; #define PG8_WAIT_V(n) asm volatile("s_waitcnt vmcnt(" #n ")" ::: "memory")
; #define PG8_WAIT_L(n) asm volatile("s_waitcnt lgkmcnt(" #n ")" ::: "memory")
; #define PG8_BAR __builtin_amdgcn_s_barrier()
; #define PG8_SCHED __builtin_amdgcn_sched_barrier(0)
; template <class Epi, bool ALIGN_EPI>
; __device__ __forceinline__ void gemm_phase(LAS unsigned char* lds, const Gemm g, const StaticOrder& S, const Epi& E, const int tid) {
;     ...
;             PG8_WAIT_V(8); PG8_WAIT_L(0); PG8_BAR; PG8_MMA(1, 0, At, B0); PG8_MMA(1, 1, At, B1); PG8_BAR; PG8_SCHED;
	v_mfma_f32_16x16x32_bf16 v[128:131], v[164:167], v[180:183], v[128:131]
	v_mfma_f32_16x16x32_bf16 v[128:131], v[168:171], v[184:187], v[128:131]
	v_mfma_f32_16x16x32_bf16 v[124:127], v[176:179], v[184:187], v[124:127]
	v_mfma_f32_16x16x32_bf16 v[124:127], v[172:175], v[180:183], v[124:127]
	v_mfma_f32_16x16x32_bf16 v[116:119], v[172:175], v[188:191], v[116:119]
	v_mfma_f32_16x16x32_bf16 v[116:119], v[176:179], v[192:195], v[116:119]
	v_mfma_f32_16x16x32_bf16 v[120:123], v[168:171], v[192:195], v[120:123]
	v_mfma_f32_16x16x32_bf16 v[120:123], v[164:167], v[188:191], v[120:123]
	v_mfma_f32_16x16x32_bf16 v[112:115], v[164:167], v[196:199], v[112:115]
	v_mfma_f32_16x16x32_bf16 v[112:115], v[168:171], v[214:217], v[112:115]
	v_mfma_f32_16x16x32_bf16 v[108:111], v[176:179], v[214:217], v[108:111]
	v_mfma_f32_16x16x32_bf16 v[108:111], v[172:175], v[196:199], v[108:111]
	v_mfma_f32_16x16x32_bf16 v[100:103], v[172:175], v[218:221], v[100:103]
	v_mfma_f32_16x16x32_bf16 v[100:103], v[176:179], v[222:225], v[100:103]
	v_mfma_f32_16x16x32_bf16 v[104:107], v[168:171], v[222:225], v[104:107]
	v_mfma_f32_16x16x32_bf16 v[104:107], v[164:167], v[218:221], v[104:107]

; #define LAS __attribute__((address_space(3)))
; #define PG8_MMA(ai, bj, At, Bt) do { __builtin_amdgcn_s_setprio(1); _Pragma("unroll") for (int m = 0; m < 4; ++m) _Pragma("unroll") for (int n = 0; n < 2; ++n) _Pragma("unroll") for (int k = 0; k < 2; ++k) \
;         acc[ai][bj][m][n] = __builtin_amdgcn_mfma_f32_16x16x32_bf16(Bt[n][k], At[m][k], acc[ai][bj][m][n], 0, 0, 0); __builtin_amdgcn_s_setprio(0); } while (0)
; #define PG8_WAIT_V(n) asm volatile("s_waitcnt vmcnt(" #n ")" ::: "memory")
; #define PG8_WAIT_L(n) asm volatile("s_waitcnt lgkmcnt(" #n ")" ::: "memory")
; #define PG8_BAR __builtin_amdgcn_s_barrier()
; #define PG8_SCHED __builtin_amdgcn_sched_barrier(0)
; __device__ __forceinline__ u32x4 zero_frag() { unsigned z_ = 0u; asm volatile("" : "+v"(z_)); return (u32x4){z_, z_, z_, z_}; }
; __device__ __forceinline__ void epi_lane(int& fr, int& fq) { unsigned ones = ~0u; asm volatile("" : "+s"(ones)); const int ln = (int)__builtin_amdgcn_mbcnt_hi(ones, __builtin_amdgcn_mbcnt_lo(ones, 0u)); fr = ln & 15; fq = ln >> 4; }
; template <class Epi, bool ALIGN_EPI>
; __device__ __forceinline__ void gemm_phase(LAS unsigned char* lds, const Gemm g, const StaticOrder& S, const Epi& E, const int tid) {
;     ...
;             PG8_WAIT_V(8); PG8_WAIT_L(0); PG8_BAR; PG8_MMA(1, 0, At, B0); PG8_MMA(1, 1, At, B1); PG8_BAR; PG8_SCHED;
;         }
;         if constexpr (ALIGN_EPI) { if (wr == 0) PG8_BAR; }
;         E(acc, cur, wr, wc, lds, rs_pm);
;     __device__ __forceinline__ void operator()(f32x4 (&acc)[2][2][4][2], const Unit& u, int wr, int wc, LAS unsigned char* lds, int& rs_pm) const {
;         int fr, fq; epi_lane(fr, fq);
;         const int row0 = u.pm * BM + wr * 64 + fr, col0 = u.pn * BM + wc * 32 + 8 * fq; u32x4 zb = zero_frag();
; #pragma unroll
;         for (int ai = 0; ai < 2; ++ai)
; #pragma unroll
;             for (int m = 0; m < 4; ++m) { float ss = 0.f;
;                 bf16* const xrow = xb + (((size_t)(u.pm * 32 + u.pn * 4 + (wc >> 1)) * BM + (wr * 64 + fr + ai * HALF + m * 16)) * 64 + (wc & 1) * 32 + 8 * fq);
; #pragma unroll
;                 for (int bj = 0; bj < 2; ++bj) {
;                     const u32x4 xw = *(const u32x4*)(xrow + (size_t)bj * (2 * BM * 64));
	s_barrier
	s_add_i32 s86, s86, 2
	s_add_u32 s10, s10, 0x100
	s_addc_u32 s11, s11, 0
	s_add_u32 s84, s84, 0x10000
	s_addc_u32 s85, s85, 0
	s_cmp_gt_u32 s86, 29
	s_cbranch_scc0 .LBB0_847
	v_and_b32_e32 v222, 15, v238
	v_lshrrev_b32_e32 v156, 4, v238
	s_lshl_b32 s100, s40, 5
	s_lshl_b32 s101, s41, 2
	v_lshlrev_b32_e32 v222, 7, v222
	s_add_i32 s100, s100, s101
	s_or_b32 s100, s100, s80
	v_lshl_or_b32 v222, v156, 4, v222
	s_ashr_i32 s101, s100, 31
	s_lshl_b64 s[100:101], s[100:101], 15
	s_add_u32 s98, s74, s100
	s_addc_u32 s99, s75, s101
	s_add_u32 s98, s98, s30
	s_addc_u32 s99, s99, s31
	s_lshl_b32 s100, s77, 7
	s_add_u32 s98, s98, s100
	s_addc_u32 s99, s99, 0
	s_lshl_b32 s100, s40, 15
	s_lshl_b32 s101, s77, 7
	s_add_i32 s100, s100, s101
	s_lshl_b32 s101, s41, 4
	s_add_i32 s100, s100, s101
	s_lshl_b32 s101, s76, 2
	s_add_i32 s100, s100, s101
	s_add_u32 s22, s42, s100
	s_addc_u32 s23, s43, 0
	global_load_dwordx4 v[176:179], v222, s[98:99]
	s_add_u32 s100, s98, 0x10000
	s_addc_u32 s101, s99, 0
	global_load_dwordx4 v[180:183], v222, s[100:101]
	global_load_dwordx4 v[184:187], v222, s[98:99] offset:2048
	s_add_u32 s100, s98, 0x10000
	s_addc_u32 s101, s99, 0
	global_load_dwordx4 v[188:191], v222, s[100:101] offset:2048
	s_add_u32 s100, s98, 0x1000
	s_addc_u32 s101, s99, 0
	global_load_dwordx4 v[192:195], v222, s[100:101]
	s_add_u32 s100, s98, 0x11000
	s_addc_u32 s101, s99, 0
	global_load_dwordx4 v[196:199], v222, s[100:101]
	s_add_u32 s100, s98, 0x1000
	s_addc_u32 s101, s99, 0
	global_load_dwordx4 v[214:217], v222, s[100:101] offset:2048
	s_add_u32 s100, s98, 0x11000
	s_addc_u32 s101, s99, 0
	global_load_dwordx4 v[218:221], v222, s[100:101] offset:2048
	s_and_b64 vcc, exec, s[44:45]
	s_cbranch_vccz .LBB0_850
	s_barrier
